# P6 W/U products: the 8 B-fragment loads for column blocks 3 and 4 issued ~3000 instructions earlier into free registers instead of serialized load-wait-mfma
# speedup vs baseline: 1.0021x; 1.0021x over previous
.LBB0_685:
	s_or_b64 exec, exec, s[62:63]
	s_waitcnt lgkmcnt(0)
	v_sub_f32_e32 v43, v131, v43
	v_mul_f32_e32 v43, 0x3fb8aa3b, v43
	v_sub_f32_e32 v42, v131, v42
	v_exp_f32_e32 v43, v43
	v_mul_f32_e32 v42, 0x3fb8aa3b, v42
	v_sub_f32_e32 v41, v131, v41
	v_exp_f32_e32 v42, v42
	v_mul_f32_e32 v41, 0x3fb8aa3b, v41
	v_sub_f32_e32 v40, v131, v40
	v_exp_f32_e32 v41, v41
	v_mul_f32_e32 v40, 0x3fb8aa3b, v40
	v_mul_f32_e32 v44, 0x3db504f3, v49
	v_exp_f32_e32 v40, v40
	v_mul_f32_e32 v43, v44, v43
	v_mul_f32_e32 v44, 0x3db504f3, v48
	v_mul_f32_e32 v42, v44, v42
	v_mul_f32_e32 v44, 0x3db504f3, v47
	v_mul_f32_e32 v41, v44, v41
	v_mul_f32_e32 v44, 0x3db504f3, v46
	v_sub_f32_e32 v45, v162, v131
	v_mul_f32_e32 v40, v44, v40
	v_sub_f32_e32 v44, v162, v130
	v_mul_f32_e32 v45, 0x3fb8aa3b, v45
	v_mul_f32_e32 v44, 0x3fb8aa3b, v44
	v_exp_f32_e32 v45, v45
	v_exp_f32_e32 v44, v44
	v_mul_f32_e32 v17, v17, v163
	v_mul_f32_e32 v33, v33, v163
	v_mul_f32_e32 v17, v17, v45
	v_mul_f32_e32 v211, v33, v44
	v_cndmask_b32_e64 v62, 0, v17, s[60:61]
	v_sub_f32_e32 v17, v160, v130
	v_sub_f32_e32 v33, v160, v131
	v_mul_f32_e32 v17, 0x3fb8aa3b, v17
	v_mul_f32_e32 v33, 0x3fb8aa3b, v33
	v_exp_f32_e32 v17, v17
	v_exp_f32_e32 v33, v33
	v_mul_f32_e32 v32, v32, v161
	v_mul_f32_e32 v16, v16, v161
	v_mul_f32_e32 v212, v32, v17
	v_mul_f32_e32 v16, v16, v33
	v_sub_f32_e32 v17, v158, v131
	v_cndmask_b32_e64 v66, 0, v16, s[58:59]
	v_sub_f32_e32 v16, v158, v130
	v_mul_f32_e32 v17, 0x3fb8aa3b, v17
	v_mul_f32_e32 v16, 0x3fb8aa3b, v16
	v_exp_f32_e32 v17, v17
	v_exp_f32_e32 v16, v16
	v_mul_f32_e32 v15, v15, v159
	v_mul_f32_e32 v31, v31, v159
	v_mul_f32_e32 v15, v15, v17
	v_mul_f32_e32 v213, v31, v16
	v_cndmask_b32_e64 v70, 0, v15, s[56:57]
	v_sub_f32_e32 v15, v156, v130
	v_sub_f32_e32 v16, v156, v131
	v_mul_f32_e32 v15, 0x3fb8aa3b, v15
	v_mul_f32_e32 v16, 0x3fb8aa3b, v16
	v_exp_f32_e32 v15, v15
	v_exp_f32_e32 v16, v16
	v_mul_f32_e32 v17, v30, v157
	v_mul_f32_e32 v14, v14, v157
	v_mul_f32_e32 v214, v17, v15
	v_mul_f32_e32 v14, v14, v16
	v_sub_f32_e32 v15, v154, v130
	v_sub_f32_e32 v16, v154, v131
	v_mul_f32_e32 v15, 0x3fb8aa3b, v15
	v_mul_f32_e32 v16, 0x3fb8aa3b, v16
	v_exp_f32_e32 v15, v15
	v_exp_f32_e32 v16, v16
	v_mul_f32_e32 v17, v29, v155
	v_mul_f32_e32 v13, v13, v155
	v_mul_f32_e32 v215, v17, v15
	v_mul_f32_e32 v13, v13, v16
	v_sub_f32_e32 v15, v152, v131
	v_cndmask_b32_e64 v74, 0, v13, s[52:53]
	v_sub_f32_e32 v13, v152, v130
	v_mul_f32_e32 v15, 0x3fb8aa3b, v15
	v_mul_f32_e32 v13, 0x3fb8aa3b, v13
	v_exp_f32_e32 v15, v15
	v_exp_f32_e32 v13, v13
	v_mul_f32_e32 v12, v12, v153
	v_mul_f32_e32 v16, v28, v153
	v_mul_f32_e32 v12, v12, v15
	v_mul_f32_e32 v216, v16, v13
	v_cndmask_b32_e64 v28, 0, v12, s[50:51]
	v_sub_f32_e32 v12, v150, v130
	v_sub_f32_e32 v13, v150, v131
	v_mul_f32_e32 v12, 0x3fb8aa3b, v12
	v_mul_f32_e32 v13, 0x3fb8aa3b, v13
	v_exp_f32_e32 v12, v12
	v_exp_f32_e32 v13, v13
	v_mul_f32_e32 v15, v27, v151
	v_mul_f32_e32 v11, v11, v151
	v_mul_f32_e32 v217, v15, v12
	v_mul_f32_e32 v11, v11, v13
	v_sub_f32_e32 v12, v148, v131
	v_cndmask_b32_e64 v78, 0, v11, s[48:49]
	v_sub_f32_e32 v11, v148, v130
	v_mul_f32_e32 v12, 0x3fb8aa3b, v12
	v_mul_f32_e32 v11, 0x3fb8aa3b, v11
	v_exp_f32_e32 v12, v12
	v_exp_f32_e32 v11, v11
	v_mul_f32_e32 v10, v10, v149
	v_mul_f32_e32 v13, v26, v149
	v_mul_f32_e32 v10, v10, v12
	v_mul_f32_e32 v218, v13, v11
	v_cndmask_b32_e64 v82, 0, v10, s[46:47]
	v_sub_f32_e32 v10, v146, v130
	v_sub_f32_e32 v11, v146, v131
	v_mul_f32_e32 v10, 0x3fb8aa3b, v10
	v_mul_f32_e32 v11, 0x3fb8aa3b, v11
	v_exp_f32_e32 v10, v10
	v_exp_f32_e32 v11, v11
	v_mul_f32_e32 v12, v25, v147
	v_mul_f32_e32 v9, v9, v147
	v_mul_f32_e32 v219, v12, v10
	v_mul_f32_e32 v9, v9, v11
	v_sub_f32_e32 v10, v144, v131
	v_cndmask_b32_e64 v84, 0, v9, s[44:45]
	v_sub_f32_e32 v9, v144, v130
	v_mul_f32_e32 v10, 0x3fb8aa3b, v10
	v_mul_f32_e32 v9, 0x3fb8aa3b, v9
	v_exp_f32_e32 v10, v10
	v_exp_f32_e32 v9, v9
	v_mul_f32_e32 v8, v8, v145
	v_mul_f32_e32 v11, v24, v145
	v_mul_f32_e32 v8, v8, v10
	v_mul_f32_e32 v220, v11, v9
	v_cndmask_b32_e64 v24, 0, v8, s[42:43]
	v_sub_f32_e32 v8, v142, v130
	v_sub_f32_e32 v9, v142, v131
	v_mul_f32_e32 v8, 0x3fb8aa3b, v8
	v_mul_f32_e32 v9, 0x3fb8aa3b, v9
	v_exp_f32_e32 v8, v8
	v_exp_f32_e32 v9, v9
	v_mul_f32_e32 v10, v23, v143
	v_mul_f32_e32 v7, v7, v143
	v_mul_f32_e32 v221, v10, v8
	v_mul_f32_e32 v7, v7, v9
	v_sub_f32_e32 v8, v140, v131
	v_cndmask_b32_e64 v142, 0, v7, s[40:41]
	v_sub_f32_e32 v7, v140, v130
	v_mul_f32_e32 v8, 0x3fb8aa3b, v8
	v_mul_f32_e32 v7, 0x3fb8aa3b, v7
	v_exp_f32_e32 v8, v8
	v_exp_f32_e32 v7, v7
	v_mul_f32_e32 v6, v6, v141
	v_mul_f32_e32 v9, v22, v141
	v_mul_f32_e32 v6, v6, v8
	v_sub_f32_e32 v8, v138, v131
	v_mul_f32_e32 v222, v9, v7
	v_sub_f32_e32 v7, v138, v130
	v_mul_f32_e32 v8, 0x3fb8aa3b, v8
	v_mul_f32_e32 v7, 0x3fb8aa3b, v7
	v_exp_f32_e32 v8, v8
	v_exp_f32_e32 v7, v7
	v_mul_f32_e32 v5, v5, v139
	v_mul_f32_e32 v9, v21, v139
	v_mul_f32_e32 v5, v5, v8
	v_mul_f32_e32 v223, v9, v7
	v_cndmask_b32_e64 v140, 0, v5, s[8:9]
	v_sub_f32_e32 v5, v136, v130
	v_sub_f32_e32 v7, v136, v131
	v_mul_f32_e32 v5, 0x3fb8aa3b, v5
	v_mul_f32_e32 v7, 0x3fb8aa3b, v7
	v_exp_f32_e32 v5, v5
	v_exp_f32_e32 v7, v7
	v_mul_f32_e32 v8, v20, v137
	v_mul_f32_e32 v4, v4, v137
	v_mul_f32_e32 v224, v8, v5
	v_mul_f32_e32 v4, v4, v7
	v_sub_f32_e32 v5, v134, v131
	v_cndmask_b32_e64 v144, 0, v4, s[6:7]
	v_sub_f32_e32 v4, v134, v130
	v_mul_f32_e32 v5, 0x3fb8aa3b, v5
	v_mul_f32_e32 v4, 0x3fb8aa3b, v4
	v_exp_f32_e32 v5, v5
	v_exp_f32_e32 v4, v4
	v_mul_f32_e32 v3, v3, v135
	v_mul_f32_e32 v7, v19, v135
	v_mul_f32_e32 v3, v3, v5
	v_mul_f32_e32 v225, v7, v4
	v_cndmask_b32_e64 v146, v3, 0, s[4:5]
	v_sub_f32_e32 v3, v132, v130
	v_sub_f32_e32 v4, v132, v131
	v_mul_f32_e32 v3, 0x3fb8aa3b, v3
	v_mul_f32_e32 v4, 0x3fb8aa3b, v4
	v_exp_f32_e32 v3, v3
	v_exp_f32_e32 v4, v4
	v_mul_f32_e32 v5, v18, v133
	v_mul_f32_e32 v2, v2, v133
	v_mul_f32_e32 v226, v5, v3
	v_mul_f32_e32 v2, v2, v4
	v_cvt_pk_bf16_f32 v4, v40, v41
	v_cvt_pk_bf16_f32 v5, v42, v43
	global_store_dwordx2 v[34:35], v[4:5], off offset:48
	v_cvt_pk_bf16_f32 v4, v36, v38
	v_cvt_pk_bf16_f32 v5, v37, v39
	global_store_dwordx2 v[34:35], v[4:5], off offset:112
	v_cndmask_b32_e64 v14, 0, v14, s[54:55]
	v_cndmask_b32_e64 v6, 0, v6, s[38:39]
	v_cndmask_b32_e64 v2, 0, v2, s[0:1]
	v_lshlrev_b64 v[86:87], 1, v[128:129]
	s_add_u32 s0, s94, s28
	v_lshl_add_u64 v[4:5], v[122:123], 0, v[86:87]
	s_addc_u32 s1, s95, s29
	v_lshl_add_u64 v[98:99], s[0:1], 0, v[4:5]
	s_mov_b32 s4, 0x9000000
	v_add_co_u32_e32 v4, vcc, s4, v98
	s_mov_b32 s4, 0x9001000
	s_nop 0
	v_addc_co_u32_e32 v5, vcc, 0, v99, vcc
	v_add_co_u32_e32 v8, vcc, s4, v98
	v_lshlrev_b32_e32 v90, 4, v126
	s_nop 0
	v_addc_co_u32_e32 v9, vcc, 0, v99, vcc
	v_cmp_eq_u32_e32 vcc, 63, v126
	global_load_dwordx4 v[58:61], v[4:5], off offset:32
	global_load_dwordx4 v[54:57], v[4:5], off offset:64
	global_load_dwordx4 v[18:21], v[8:9], off offset:-4096
	global_load_dwordx4 v[50:53], v[4:5], off offset:96
	global_load_dwordx4 v[46:49], v[8:9], off
	global_load_dwordx4 v[42:45], v[8:9], off offset:32
	global_load_dwordx4 v[38:41], v[8:9], off offset:64
	global_load_dwordx4 v[34:37], v[8:9], off offset:96
	v_cndmask_b32_e64 v89, 0, 1.0, vcc
	v_cmp_eq_u32_e32 vcc, 62, v126
	v_add_u32_e32 v92, 0x1000, v90
	v_ashrrev_i32_e32 v93, 31, v92
	v_cndmask_b32_e64 v3, 0, 1.0, vcc
	v_cmp_eq_u32_e32 vcc, 61, v126
	v_lshl_add_u64 v[120:121], v[92:93], 1, s[0:1]
	v_add_u32_e32 v92, 0x1400, v90
	v_cndmask_b32_e64 v4, 0, 1.0, vcc
	v_cmp_eq_u32_e32 vcc, 60, v126
	v_ashrrev_i32_e32 v93, 31, v92
	v_lshl_add_u64 v[112:113], v[92:93], 1, s[0:1]
	v_cndmask_b32_e64 v8, 0, 1.0, vcc
	v_cmp_eq_u32_e32 vcc, 59, v126
	v_add_u32_e32 v92, 0x800, v90
	v_ashrrev_i32_e32 v91, 31, v90
	v_cndmask_b32_e64 v5, 0, 1.0, vcc
	v_cmp_eq_u32_e32 vcc, 58, v126
	v_ashrrev_i32_e32 v93, 31, v92
	v_add_u32_e32 v100, 0x1800, v90
	v_cndmask_b32_e64 v9, 0, 1.0, vcc
	v_cmp_eq_u32_e32 vcc, 57, v126
	v_lshl_add_u64 v[108:109], v[92:93], 1, s[0:1]
	v_add_u32_e32 v92, 0xc00, v90
	v_cndmask_b32_e64 v95, 0, 1.0, vcc
	v_cmp_eq_u32_e32 vcc, 56, v126
	s_nop 7
	s_mov_b32 s54, 62
	s_nop 0
	v_readlane_b32 s4, v62, s54
	s_nop 1
	v_fma_f32 v3, -s4, v89, v3
	s_mov_b32 s55, 61
	v_cndmask_b32_e64 v181, 0, 1.0, vcc
	v_cmp_eq_u32_e32 vcc, 55, v126
	v_add_f32_e32 v88, 0, v3
	s_nop 0
	v_readlane_b32 s4, v66, s55
	s_nop 1
	v_fma_f32 v4, -s4, v88, v4
	v_ashrrev_i32_e32 v101, 31, v100
	v_cndmask_b32_e64 v11, 0, 1.0, vcc
	v_cmp_eq_u32_e32 vcc, 54, v126
	s_nop 0
	v_readlane_b32 s4, v62, s55
	s_nop 1
	v_fma_f32 v4, -s4, v89, v4
	v_lshl_add_u64 v[106:107], v[100:101], 1, s[0:1]
	v_ashrrev_i32_e32 v93, 31, v92
	v_cndmask_b32_e64 v97, 0, 1.0, vcc
	v_cmp_eq_u32_e32 vcc, 53, v126
	s_mov_b32 s56, 60
	v_lshl_add_u64 v[102:103], v[92:93], 1, s[0:1]
	v_cndmask_b32_e64 v13, 0, 1.0, vcc
	v_cmp_eq_u32_e32 vcc, 52, v126
	v_mov_b32_e32 v93, v123
	v_mov_b32_e32 v92, v123
	v_cndmask_b32_e64 v105, 0, 1.0, vcc
	v_cmp_eq_u32_e32 vcc, 51, v126
	s_mov_b32 s57, 59
	s_mov_b32 s53, 26
	v_cndmask_b32_e64 v17, 0, 1.0, vcc
	v_cmp_eq_u32_e32 vcc, 50, v126
	s_mov_b32 s58, 58
	v_mov_b32_e32 v94, v123
	v_cndmask_b32_e64 v111, 0, 1.0, vcc
	v_cmp_eq_u32_e32 vcc, 49, v126
	s_mov_b32 s52, 25
	s_mov_b32 s59, 57
	v_cndmask_b32_e64 v23, 0, 1.0, vcc
	v_cmp_eq_u32_e32 vcc, 48, v126
	v_mul_f32_e32 v10, 0x3fb8aa3b, v166
	v_mov_b32_e32 v180, v123
	v_cndmask_b32_e64 v115, 0, 1.0, vcc
	v_cmp_eq_u32_e32 vcc, 47, v126
	v_exp_f32_e32 v10, v10
	s_mov_b32 s51, 24
	v_cndmask_b32_e64 v27, 0, 1.0, vcc
	v_cmp_eq_u32_e32 vcc, 46, v126
	s_mov_b32 s60, 56
	v_mul_f32_e32 v210, v193, v10
	v_cndmask_b32_e64 v117, 0, 1.0, vcc
	v_cmp_eq_u32_e32 vcc, 45, v126
	v_mov_b32_e32 v10, v123
	s_mov_b32 s70, 23
	v_cndmask_b32_e64 v31, 0, 1.0, vcc
	v_cmp_eq_u32_e32 vcc, 44, v126
	s_mov_b32 s61, 55
	v_mov_b32_e32 v96, v123
	v_cndmask_b32_e64 v119, 0, 1.0, vcc
	v_cmp_eq_u32_e32 vcc, 43, v126
	s_mov_b32 s62, 54
	s_mov_b32 s71, 22
	v_cndmask_b32_e64 v33, 0, 1.0, vcc
	v_cmp_eq_u32_e32 vcc, 42, v126
	v_mov_b32_e32 v12, v123
	s_mov_b32 s63, 53
	v_cndmask_b32_e64 v129, 0, 1.0, vcc
	v_cmp_eq_u32_e32 vcc, 41, v126
	s_mov_b32 s72, 21
	v_mov_b32_e32 v104, v123
	v_cndmask_b32_e64 v65, 0, 1.0, vcc
	v_cmp_eq_u32_e32 vcc, 40, v126
	s_mov_b32 s73, 20
	v_mov_b32_e32 v16, v123
	v_cndmask_b32_e64 v131, 0, 1.0, vcc
	v_cmp_eq_u32_e32 vcc, 39, v126
	s_mov_b32 s64, 51
	s_mov_b32 s50, 19
	v_cndmask_b32_e64 v69, 0, 1.0, vcc
	v_cmp_eq_u32_e32 vcc, 38, v126
	v_mov_b32_e32 v110, v123
	s_mov_b32 s49, 18
	v_cndmask_b32_e64 v133, 0, 1.0, vcc
	v_cmp_eq_u32_e32 vcc, 37, v126
	s_mov_b32 s65, 50
	v_mov_b32_e32 v22, v123
	v_cndmask_b32_e64 v73, 0, 1.0, vcc
	v_cmp_eq_u32_e32 vcc, 36, v126
	s_mov_b32 s48, 17
	v_mov_b32_e32 v114, v123
	v_cndmask_b32_e64 v135, 0, 1.0, vcc
	v_cmp_eq_u32_e32 vcc, 35, v126
	s_mov_b32 s47, 16
	v_mov_b32_e32 v26, v123
	v_cndmask_b32_e64 v77, 0, 1.0, vcc
	v_cmp_eq_u32_e32 vcc, 34, v126
	s_mov_b32 s45, 15
	s_mov_b32 s66, 47
	v_cndmask_b32_e64 v137, 0, 1.0, vcc
	v_cmp_eq_u32_e32 vcc, 33, v126
	v_mov_b32_e32 v116, v123
	s_mov_b32 s39, 14
	v_cndmask_b32_e64 v81, 0, 1.0, vcc
	v_cmp_eq_u32_e32 vcc, 32, v126
	v_mov_b32_e32 v30, v123
	s_mov_b32 s38, 13
	v_cndmask_b32_e64 v139, 0, 1.0, vcc
	v_cmp_eq_u32_e32 vcc, 31, v126
	v_mov_b32_e32 v118, v123
	s_mov_b32 s43, 12
	v_cndmask_b32_e64 v153, 0, 1.0, vcc
	v_cmp_eq_u32_e32 vcc, 30, v126
	v_mov_b32_e32 v32, v123
	s_mov_b32 s67, 43
	v_cndmask_b32_e64 v141, 0, 1.0, vcc
	v_cmp_eq_u32_e32 vcc, 29, v126
	s_mov_b32 s42, 11
	v_mov_b32_e32 v128, v123
	v_cndmask_b32_e64 v159, 0, 1.0, vcc
	v_cmp_eq_u32_e32 vcc, 28, v126
	s_mov_b32 s46, 10
	s_lshl_b32 s4, s20, 4
	v_cndmask_b32_e64 v143, 0, 1.0, vcc
	v_cmp_eq_u32_e32 vcc, 27, v126
	v_mov_b32_e32 v64, v123
	s_or_b32 s4, s37, s4
	v_cndmask_b32_e64 v167, 0, 1.0, vcc
	v_cmp_eq_u32_e32 vcc, 26, v126
	s_mov_b32 s37, 9
	v_mov_b32_e32 v130, v123
	v_cndmask_b32_e64 v145, 0, 1.0, vcc
	v_cmp_eq_u32_e32 vcc, 25, v126
	s_mov_b32 s40, 8
	v_mov_b32_e32 v68, v123
	v_cndmask_b32_e64 v171, 0, 1.0, vcc
	v_cmp_eq_u32_e32 vcc, 24, v126
	s_mov_b32 s44, 7
	s_mov_b32 s68, 39
	v_cndmask_b32_e64 v147, 0, 1.0, vcc
	v_cmp_eq_u32_e32 vcc, 23, v126
	v_mov_b32_e32 v132, v123
	v_mov_b32_e32 v72, v123
	v_cndmask_b32_e64 v175, 0, 1.0, vcc
	v_cmp_eq_u32_e32 vcc, 22, v126
	v_mov_b32_e32 v134, v123
	v_mov_b32_e32 v76, v123
	v_cndmask_b32_e64 v149, 0, 1.0, vcc
	v_cmp_eq_u32_e32 vcc, 21, v126
	s_mov_b32 s69, 35
	s_mov_b32 s12, 3
	v_cndmask_b32_e64 v179, 0, 1.0, vcc
	v_cmp_eq_u32_e32 vcc, 20, v126
	v_mov_b32_e32 v136, v123
	v_mov_b32_e32 v80, v123
	v_cndmask_b32_e64 v151, 0, 1.0, vcc
	v_cmp_eq_u32_e32 vcc, 19, v126
	v_mov_b32_e32 v138, v123
	v_mov_b32_e32 v152, v123
	v_cndmask_b32_e64 v177, 0, 1.0, vcc
	v_cmp_eq_u32_e32 vcc, 18, v126
	s_mov_b32 s41, 31
	s_mov_b32 s20, 63
	v_cndmask_b32_e64 v157, 0, 1.0, vcc
	v_cmp_eq_u32_e32 vcc, 17, v126
	v_mov_b32_e32 v158, v123
	v_mov_b32_e32 v166, v123
	v_cndmask_b32_e64 v173, 0, 1.0, vcc
	v_cmp_eq_u32_e32 vcc, 16, v126
	v_mov_b32_e32 v170, v123
	v_mov_b32_e32 v174, v123
	v_cndmask_b32_e64 v165, 0, 1.0, vcc
	v_cmp_eq_u32_e32 vcc, 15, v126
	v_mov_b32_e32 v148, v123
	v_mov_b32_e32 v178, v123
	v_cndmask_b32_e64 v169, 0, 1.0, vcc
	v_cmp_eq_u32_e32 vcc, 14, v126
	v_mov_b32_e32 v150, v123
	v_mov_b32_e32 v176, v123
	v_cndmask_b32_e64 v163, 0, 1.0, vcc
	v_cmp_eq_u32_e32 vcc, 13, v126
	v_mov_b32_e32 v156, v123
	v_mov_b32_e32 v172, v123
	v_cndmask_b32_e64 v161, 0, 1.0, vcc
	v_cmp_eq_u32_e32 vcc, 12, v126
	v_mov_b32_e32 v164, v123
	v_mov_b32_e32 v168, v123
	v_cndmask_b32_e64 v155, 0, 1.0, vcc
	v_cmp_eq_u32_e32 vcc, 11, v126
	v_mov_b32_e32 v162, v123
	v_mov_b32_e32 v160, v123
	v_cndmask_b32_e64 v85, 0, 1.0, vcc
	v_cmp_eq_u32_e32 vcc, 10, v126
	v_mov_b32_e32 v154, v123
	s_ashr_i32 s5, s4, 31
	v_cndmask_b32_e64 v83, 0, 1.0, vcc
	v_cmp_eq_u32_e32 vcc, 9, v126
	s_nop 1
	v_cndmask_b32_e64 v79, 0, 1.0, vcc
	v_cmp_eq_u32_e32 vcc, 8, v126
	s_nop 1
	v_cndmask_b32_e64 v75, 0, 1.0, vcc
	v_cmp_eq_u32_e32 vcc, 7, v126
	s_nop 1
	v_cndmask_b32_e64 v71, 0, 1.0, vcc
	v_cmp_eq_u32_e32 vcc, 6, v126
	s_nop 1
	v_cndmask_b32_e64 v67, 0, 1.0, vcc
	v_cmp_eq_u32_e32 vcc, 5, v126
	s_nop 1
	v_cndmask_b32_e64 v63, 0, 1.0, vcc
	v_cmp_eq_u32_e32 vcc, 4, v126
	s_nop 1
	v_cndmask_b32_e64 v29, 0, 1.0, vcc
	v_cmp_eq_u32_e32 vcc, 3, v126
	s_nop 1
	v_cndmask_b32_e64 v25, 0, 1.0, vcc
	v_cmp_eq_u32_e32 vcc, 2, v126
	s_nop 1
	v_cndmask_b32_e64 v15, 0, 1.0, vcc
	v_cmp_eq_u32_e32 vcc, 1, v126
	s_nop 1
	v_cndmask_b32_e64 v7, 0, 1.0, vcc
	v_cmp_eq_u32_e32 vcc, 0, v126
	v_lshl_add_u64 v[126:127], v[90:91], 1, s[0:1]
	v_add_u32_e32 v90, 0x1c00, v90
	v_ashrrev_i32_e32 v91, 31, v90
	v_lshl_add_u64 v[100:101], v[90:91], 1, s[0:1]
	v_add_f32_e32 v91, 0, v4
	s_nop 0
	v_readlane_b32 s6, v70, s56
	s_nop 1
	v_fma_f32 v8, -s6, v91, v8
	v_mov_b32_e32 v4, v123
	s_nop 0
	v_readlane_b32 s6, v66, s56
	s_nop 1
	v_fma_f32 v8, -s6, v88, v8
	v_cndmask_b32_e64 v3, 0, 1.0, vcc
	s_nop 0
	v_readlane_b32 s6, v62, s56
	s_nop 1
	v_fma_f32 v8, -s6, v89, v8
	s_nop 0
	v_add_f32_e32 v90, 0, v8
	s_nop 0
	v_readlane_b32 s6, v14, s57
	v_readlane_b32 s7, v70, s57
	v_readlane_b32 s8, v66, s57
	v_readlane_b32 s9, v62, s57
	v_fma_f32 v5, -s6, v90, v5
	v_fma_f32 v93, -s7, v91, v93
	v_fma_f32 v92, -s8, v88, v92
	v_fma_f32 v4, -s9, v89, v4
	v_mov_b32_e32 v8, v123
	v_pk_add_f32 v[4:5], v[92:93], v[4:5]
	v_mov_b32_e32 v93, v123
	v_mov_b32_e32 v92, v123
	v_pk_add_f32 v[4:5], v[4:5], v[4:5] op_sel:[0,1] op_sel_hi:[1,0]
	s_nop 0
	s_nop 0
	v_readlane_b32 s6, v62, s53
	v_readlane_b32 s7, v14, s58
	v_readlane_b32 s8, v70, s58
	v_readlane_b32 s9, v66, s58
	v_fma_f32 v9, -s6, v4, v9
	v_fma_f32 v93, -s7, v90, v93
	v_fma_f32 v92, -s8, v91, v92
	v_fma_f32 v8, -s9, v88, v8
	s_nop 0
	s_nop 0
	v_readlane_b32 s6, v62, s58
	s_nop 1
	v_fma_f32 v9, -s6, v89, v9
	s_nop 0
	v_pk_add_f32 v[8:9], v[92:93], v[8:9]
	s_nop 0
	v_pk_add_f32 v[92:93], v[8:9], v[8:9] op_sel:[0,1] op_sel_hi:[1,0]
	v_mov_b32_e32 v9, v123
	v_mov_b32_e32 v8, v123
	s_nop 0
	v_readlane_b32 s6, v66, s52
	v_readlane_b32 s7, v62, s52
	v_readlane_b32 s8, v14, s59
	v_readlane_b32 s9, v70, s59
	v_fma_f32 v95, -s6, v92, v95
	v_fma_f32 v9, -s7, v4, v9
	v_fma_f32 v8, -s8, v90, v8
	v_fma_f32 v94, -s9, v91, v94
	v_mov_b32_e32 v93, v4
	s_nop 0
	v_readlane_b32 s6, v66, s59
	s_nop 1
	v_fma_f32 v95, -s6, v88, v95
	s_nop 0
	s_nop 0
	v_readlane_b32 s6, v62, s59
	s_nop 1
	v_fma_f32 v95, -s6, v89, v95
	s_nop 0
	v_pk_add_f32 v[8:9], v[8:9], v[94:95]
	v_mov_b32_e32 v95, v123
	v_mov_b32_e32 v94, v123
	v_pk_add_f32 v[8:9], v[8:9], v[8:9] op_sel:[0,1] op_sel_hi:[1,0]
	s_nop 0
	s_nop 0
	v_readlane_b32 s6, v70, s51
	v_readlane_b32 s7, v66, s51
	v_readlane_b32 s8, v62, s51
	v_readlane_b32 s9, v14, s60
	v_fma_f32 v181, -s6, v8, v181
	v_fma_f32 v95, -s7, v92, v95
	v_fma_f32 v94, -s8, v4, v94
	v_fma_f32 v180, -s9, v90, v180
	s_nop 0
	s_nop 0
	v_readlane_b32 s6, v70, s60
	s_nop 1
	v_fma_f32 v181, -s6, v91, v181
	s_nop 0
	s_nop 0
	v_readlane_b32 s6, v66, s60
	s_nop 1
	v_fma_f32 v181, -s6, v88, v181
	s_nop 0
	s_nop 0
	v_readlane_b32 s6, v62, s60
	s_nop 1
	v_fma_f32 v181, -s6, v89, v181
	s_nop 0
	v_pk_add_f32 v[94:95], v[94:95], v[180:181]
	v_mov_b32_e32 v181, v123
	v_mov_b32_e32 v180, v123
	v_pk_add_f32 v[94:95], v[94:95], v[94:95] op_sel:[0,1] op_sel_hi:[1,0]
	s_nop 0
	s_nop 0
	v_readlane_b32 s6, v14, s70
	v_readlane_b32 s7, v70, s70
	v_readlane_b32 s8, v66, s70
	v_readlane_b32 s9, v62, s70
	v_fma_f32 v11, -s6, v94, v11
	v_fma_f32 v181, -s7, v8, v181
	v_fma_f32 v180, -s8, v92, v180
	v_fma_f32 v10, -s9, v4, v10
	v_mov_b32_e32 v95, v8
	s_nop 0
	v_readlane_b32 s6, v14, s61
	v_readlane_b32 s7, v70, s61
	v_readlane_b32 s8, v66, s61
	v_readlane_b32 s9, v62, s61
	v_fma_f32 v11, -s6, v90, v11
	v_fma_f32 v181, -s7, v91, v181
	v_fma_f32 v180, -s8, v88, v180
	v_fma_f32 v10, -s9, v89, v10
	s_nop 0
	v_pk_add_f32 v[10:11], v[180:181], v[10:11]
	v_mov_b32_e32 v181, v123
	v_mov_b32_e32 v180, v123
	v_pk_add_f32 v[10:11], v[10:11], v[10:11] op_sel:[0,1] op_sel_hi:[1,0]
	s_nop 0
	s_nop 0
	v_readlane_b32 s6, v74, s62
	v_readlane_b32 s7, v14, s71
	v_readlane_b32 s8, v70, s71
	v_readlane_b32 s9, v66, s71
	v_fma_f32 v97, -s6, v10, v97
	v_fma_f32 v181, -s7, v94, v181
	v_fma_f32 v180, -s8, v8, v180
	v_fma_f32 v96, -s9, v92, v96
	s_nop 0
	s_nop 0
	v_readlane_b32 s6, v62, s71
	v_readlane_b32 s7, v14, s62
	v_readlane_b32 s8, v70, s62
	v_readlane_b32 s9, v66, s62
	v_fma_f32 v97, -s6, v4, v97
	v_fma_f32 v181, -s7, v90, v181
	v_fma_f32 v180, -s8, v91, v180
	v_fma_f32 v96, -s9, v88, v96
	s_nop 0
	s_nop 0
	v_readlane_b32 s6, v62, s62
	s_nop 1
	v_fma_f32 v97, -s6, v89, v97
	s_nop 0
	v_pk_add_f32 v[96:97], v[180:181], v[96:97]
	v_mov_b32_e32 v181, v123
	v_mov_b32_e32 v180, v123
	v_pk_add_f32 v[96:97], v[96:97], v[96:97] op_sel:[0,1] op_sel_hi:[1,0]
	s_nop 0
	s_nop 0
	v_readlane_b32 s6, v28, s63
	v_readlane_b32 s7, v74, s63
	v_readlane_b32 s8, v14, s72
	v_readlane_b32 s9, v70, s72
	v_fma_f32 v13, -s6, v96, v13
	v_fma_f32 v181, -s7, v10, v181
	v_fma_f32 v180, -s8, v94, v180
	v_fma_f32 v12, -s9, v8, v12
	v_mov_b32_e32 v97, v10
	s_nop 0
	v_readlane_b32 s6, v66, s72
	v_readlane_b32 s7, v62, s72
	v_readlane_b32 s8, v14, s63
	v_readlane_b32 s9, v70, s63
	v_fma_f32 v13, -s6, v92, v13
	v_fma_f32 v181, -s7, v4, v181
	v_fma_f32 v180, -s8, v90, v180
	v_fma_f32 v12, -s9, v91, v12
	s_nop 0
	s_nop 0
	v_readlane_b32 s6, v66, s63
	s_nop 1
	v_fma_f32 v13, -s6, v88, v13
	s_nop 0
	s_nop 0
	v_readlane_b32 s6, v62, s63
	s_nop 1
	v_fma_f32 v13, -s6, v89, v13
	s_nop 0
	v_pk_add_f32 v[12:13], v[180:181], v[12:13]
	v_mov_b32_e32 v181, v123
	v_mov_b32_e32 v180, v123
	v_pk_add_f32 v[12:13], v[12:13], v[12:13] op_sel:[0,1] op_sel_hi:[1,0]
	s_nop 0
	s_nop 0
	v_readlane_b32 s6, v78, s22
	v_readlane_b32 s7, v28, s22
	v_readlane_b32 s8, v74, s22
	v_readlane_b32 s9, v14, s73
	v_fma_f32 v105, -s6, v12, v105
	v_fma_f32 v181, -s7, v96, v181
	v_fma_f32 v180, -s8, v10, v180
	v_fma_f32 v104, -s9, v94, v104
	s_nop 0
	s_nop 0
	v_readlane_b32 s6, v70, s73
	v_readlane_b32 s7, v66, s73
	v_readlane_b32 s8, v62, s73
	v_readlane_b32 s9, v14, s22
	v_fma_f32 v105, -s6, v8, v105
	v_fma_f32 v181, -s7, v92, v181
	v_fma_f32 v180, -s8, v4, v180
	v_fma_f32 v104, -s9, v90, v104
	s_nop 0
	s_nop 0
	v_readlane_b32 s6, v70, s22
	s_nop 1
	v_fma_f32 v105, -s6, v91, v105
	s_nop 0
	s_nop 0
	v_readlane_b32 s6, v66, s22
	s_nop 1
	v_fma_f32 v105, -s6, v88, v105
	s_nop 0
	s_nop 0
	v_readlane_b32 s6, v62, s22
	s_nop 1
	v_fma_f32 v105, -s6, v89, v105
	s_nop 0
	v_pk_add_f32 v[104:105], v[180:181], v[104:105]
	v_mov_b32_e32 v181, v123
	v_mov_b32_e32 v180, v123
	v_pk_add_f32 v[104:105], v[104:105], v[104:105] op_sel:[0,1] op_sel_hi:[1,0]
	s_nop 0
	s_nop 0
	v_readlane_b32 s6, v82, s64
	v_readlane_b32 s7, v78, s64
	v_readlane_b32 s8, v28, s64
	v_readlane_b32 s9, v74, s64
	v_fma_f32 v17, -s6, v104, v17
	v_fma_f32 v181, -s7, v12, v181
	v_fma_f32 v180, -s8, v96, v180
	v_fma_f32 v16, -s9, v10, v16
	v_mov_b32_e32 v105, v12
	s_nop 0
	v_readlane_b32 s6, v14, s50
	v_readlane_b32 s7, v70, s50
	v_readlane_b32 s8, v66, s50
	v_readlane_b32 s9, v62, s50
	v_fma_f32 v17, -s6, v94, v17
	v_fma_f32 v181, -s7, v8, v181
	v_fma_f32 v180, -s8, v92, v180
	v_fma_f32 v16, -s9, v4, v16
	s_nop 0
	s_nop 0
	v_readlane_b32 s6, v14, s64
	v_readlane_b32 s7, v70, s64
	v_readlane_b32 s8, v66, s64
	v_readlane_b32 s9, v62, s64
	v_fma_f32 v17, -s6, v90, v17
	v_fma_f32 v181, -s7, v91, v181
	v_fma_f32 v180, -s8, v88, v180
	v_fma_f32 v16, -s9, v89, v16
	s_nop 0
	v_pk_add_f32 v[16:17], v[180:181], v[16:17]
	v_mov_b32_e32 v181, v123
	v_mov_b32_e32 v180, v123
	v_pk_add_f32 v[16:17], v[16:17], v[16:17] op_sel:[0,1] op_sel_hi:[1,0]
	s_nop 0
	s_nop 0
	v_readlane_b32 s6, v74, s49
	v_readlane_b32 s7, v82, s65
	v_readlane_b32 s8, v78, s65
	v_readlane_b32 s9, v28, s65
	v_fma_f32 v111, -s6, v16, v111
	v_fma_f32 v181, -s7, v104, v181
	v_fma_f32 v180, -s8, v12, v180
	v_fma_f32 v110, -s9, v96, v110
	s_nop 0
	s_nop 0
	v_readlane_b32 s6, v74, s65
	v_readlane_b32 s7, v14, s49
	v_readlane_b32 s8, v70, s49
	v_readlane_b32 s9, v66, s49
	v_fma_f32 v111, -s6, v10, v111
	v_fma_f32 v181, -s7, v94, v181
	v_fma_f32 v180, -s8, v8, v180
	v_fma_f32 v110, -s9, v92, v110
	s_nop 0
	s_nop 0
	v_readlane_b32 s6, v62, s49
	v_readlane_b32 s7, v14, s65
	v_readlane_b32 s8, v70, s65
	v_readlane_b32 s9, v66, s65
	v_fma_f32 v111, -s6, v4, v111
	v_fma_f32 v181, -s7, v90, v181
	v_fma_f32 v180, -s8, v91, v180
	v_fma_f32 v110, -s9, v88, v110
	s_nop 0
	s_nop 0
	v_readlane_b32 s6, v62, s65
	s_nop 1
	v_fma_f32 v111, -s6, v89, v111
	s_nop 0
	v_pk_add_f32 v[110:111], v[180:181], v[110:111]
	v_mov_b32_e32 v181, v123
	v_mov_b32_e32 v180, v123
	v_pk_add_f32 v[110:111], v[110:111], v[110:111] op_sel:[0,1] op_sel_hi:[1,0]
	s_nop 0
	s_nop 0
	v_readlane_b32 s6, v28, s48
	v_readlane_b32 s7, v74, s48
	v_readlane_b32 s8, v82, s21
	v_readlane_b32 s9, v78, s21
	v_fma_f32 v23, -s6, v110, v23
	v_fma_f32 v181, -s7, v16, v181
	v_fma_f32 v180, -s8, v104, v180
	v_fma_f32 v22, -s9, v12, v22
	v_mov_b32_e32 v111, v16
	s_nop 0
	v_readlane_b32 s6, v28, s21
	v_readlane_b32 s7, v74, s21
	v_readlane_b32 s8, v14, s48
	v_readlane_b32 s9, v70, s48
	v_fma_f32 v23, -s6, v96, v23
	v_fma_f32 v181, -s7, v10, v181
	v_fma_f32 v180, -s8, v94, v180
	v_fma_f32 v22, -s9, v8, v22
	s_nop 0
	s_nop 0
	v_readlane_b32 s6, v66, s48
	v_readlane_b32 s7, v62, s48
	v_readlane_b32 s8, v14, s21
	v_readlane_b32 s9, v70, s21
	v_fma_f32 v23, -s6, v92, v23
	v_fma_f32 v181, -s7, v4, v181
	v_fma_f32 v180, -s8, v90, v180
	v_fma_f32 v22, -s9, v91, v22
	s_nop 0
	s_nop 0
	v_readlane_b32 s6, v66, s21
	s_nop 1
	v_fma_f32 v23, -s6, v88, v23
	s_nop 0
	s_nop 0
	v_readlane_b32 s6, v62, s21
	s_nop 1
	v_fma_f32 v23, -s6, v89, v23
	s_nop 0
	v_pk_add_f32 v[22:23], v[180:181], v[22:23]
	v_mov_b32_e32 v181, v123
	v_mov_b32_e32 v180, v123
	v_pk_add_f32 v[22:23], v[22:23], v[22:23] op_sel:[0,1] op_sel_hi:[1,0]
	s_nop 0
	s_nop 0
	v_readlane_b32 s6, v78, s47
	v_readlane_b32 s7, v28, s47
	v_readlane_b32 s8, v74, s47
	v_readlane_b32 s9, v82, s34
	v_fma_f32 v115, -s6, v22, v115
	v_fma_f32 v181, -s7, v110, v181
	v_fma_f32 v180, -s8, v16, v180
	v_fma_f32 v114, -s9, v104, v114
	s_nop 0
	s_nop 0
	v_readlane_b32 s6, v78, s34
	v_readlane_b32 s7, v28, s34
	v_readlane_b32 s8, v74, s34
	v_readlane_b32 s9, v14, s47
	v_fma_f32 v115, -s6, v12, v115
	v_fma_f32 v181, -s7, v96, v181
	v_fma_f32 v180, -s8, v10, v180
	v_fma_f32 v114, -s9, v94, v114
	s_nop 0
	s_nop 0
	v_readlane_b32 s6, v70, s47
	v_readlane_b32 s7, v66, s47
	v_readlane_b32 s8, v62, s47
	v_readlane_b32 s9, v14, s34
	v_fma_f32 v115, -s6, v8, v115
	v_fma_f32 v181, -s7, v92, v181
	v_fma_f32 v180, -s8, v4, v180
	v_fma_f32 v114, -s9, v90, v114
	s_nop 0
	s_nop 0
	v_readlane_b32 s6, v70, s34
	s_nop 1
	v_fma_f32 v115, -s6, v91, v115
	s_nop 0
	s_nop 0
	v_readlane_b32 s6, v66, s34
	s_nop 1
	v_fma_f32 v115, -s6, v88, v115
	s_nop 0
	s_nop 0
	v_readlane_b32 s6, v62, s34
	s_nop 1
	v_fma_f32 v115, -s6, v89, v115
	s_nop 0
	v_pk_add_f32 v[114:115], v[180:181], v[114:115]
	v_mov_b32_e32 v181, v123
	v_mov_b32_e32 v180, v123
	v_pk_add_f32 v[114:115], v[114:115], v[114:115] op_sel:[0,1] op_sel_hi:[1,0]
	s_nop 0
	s_nop 0
	v_readlane_b32 s6, v82, s45
	v_readlane_b32 s7, v78, s45
	v_readlane_b32 s8, v28, s45
	v_readlane_b32 s9, v74, s45
	v_fma_f32 v27, -s6, v114, v27
	v_fma_f32 v181, -s7, v22, v181
	v_fma_f32 v180, -s8, v110, v180
	v_fma_f32 v26, -s9, v16, v26
	v_mov_b32_e32 v115, v22
	s_nop 0
	v_readlane_b32 s6, v82, s66
	v_readlane_b32 s7, v78, s66
	v_readlane_b32 s8, v28, s66
	v_readlane_b32 s9, v74, s66
	v_fma_f32 v27, -s6, v104, v27
	v_fma_f32 v181, -s7, v12, v181
	v_fma_f32 v180, -s8, v96, v180
	v_fma_f32 v26, -s9, v10, v26
	s_nop 0
	s_nop 0
	v_readlane_b32 s6, v14, s45
	v_readlane_b32 s7, v70, s45
	v_readlane_b32 s8, v66, s45
	v_readlane_b32 s9, v62, s45
	v_fma_f32 v27, -s6, v94, v27
	v_fma_f32 v181, -s7, v8, v181
	v_fma_f32 v180, -s8, v92, v180
	v_fma_f32 v26, -s9, v4, v26
	s_nop 0
	s_nop 0
	v_readlane_b32 s6, v14, s66
	v_readlane_b32 s7, v70, s66
	v_readlane_b32 s8, v66, s66
	v_readlane_b32 s9, v62, s66
	v_fma_f32 v27, -s6, v90, v27
	v_fma_f32 v181, -s7, v91, v181
	v_fma_f32 v180, -s8, v88, v180
	v_fma_f32 v26, -s9, v89, v26
	s_nop 0
	v_pk_add_f32 v[26:27], v[180:181], v[26:27]
	v_mov_b32_e32 v181, v123
	v_mov_b32_e32 v180, v123
	v_pk_add_f32 v[26:27], v[26:27], v[26:27] op_sel:[0,1] op_sel_hi:[1,0]
	s_nop 0
	s_nop 0
	v_readlane_b32 s6, v84, s14
	v_readlane_b32 s7, v82, s39
	v_readlane_b32 s8, v78, s39
	v_readlane_b32 s9, v28, s39
	v_fma_f32 v117, -s6, v26, v117
	v_fma_f32 v181, -s7, v114, v181
	v_fma_f32 v180, -s8, v22, v180
	v_fma_f32 v116, -s9, v110, v116
	s_nop 0
	s_nop 0
	v_readlane_b32 s6, v74, s39
	v_readlane_b32 s7, v82, s14
	v_readlane_b32 s8, v78, s14
	v_readlane_b32 s9, v28, s14
	v_fma_f32 v117, -s6, v16, v117
	v_fma_f32 v181, -s7, v104, v181
	v_fma_f32 v180, -s8, v12, v180
	v_fma_f32 v116, -s9, v96, v116
	s_nop 0
	s_nop 0
	v_readlane_b32 s6, v74, s14
	v_readlane_b32 s7, v14, s39
	v_readlane_b32 s8, v70, s39
	v_readlane_b32 s9, v66, s39
	v_fma_f32 v117, -s6, v10, v117
	v_fma_f32 v181, -s7, v94, v181
	v_fma_f32 v180, -s8, v8, v180
	v_fma_f32 v116, -s9, v92, v116
	s_nop 0
	s_nop 0
	v_readlane_b32 s6, v62, s39
	v_readlane_b32 s7, v14, s14
	v_readlane_b32 s8, v70, s14
	v_readlane_b32 s9, v66, s14
	v_fma_f32 v117, -s6, v4, v117
	v_fma_f32 v181, -s7, v90, v181
	v_fma_f32 v180, -s8, v91, v180
	v_fma_f32 v116, -s9, v88, v116
	s_nop 0
	s_nop 0
	v_readlane_b32 s6, v62, s14
	s_nop 1
	v_fma_f32 v117, -s6, v89, v117
	s_nop 0
	v_pk_add_f32 v[116:117], v[180:181], v[116:117]
	v_mov_b32_e32 v181, v123
	v_mov_b32_e32 v180, v123
	v_pk_add_f32 v[116:117], v[116:117], v[116:117] op_sel:[0,1] op_sel_hi:[1,0]
	s_nop 0
	s_nop 0
	v_readlane_b32 s6, v24, s11
	v_readlane_b32 s7, v84, s11
	v_readlane_b32 s8, v82, s38
	v_readlane_b32 s9, v78, s38
	v_fma_f32 v31, -s6, v116, v31
	v_fma_f32 v181, -s7, v26, v181
	v_fma_f32 v180, -s8, v114, v180
	v_fma_f32 v30, -s9, v22, v30
	v_mov_b32_e32 v117, v26
	s_nop 0
	v_readlane_b32 s6, v28, s38
	v_readlane_b32 s7, v74, s38
	v_readlane_b32 s8, v82, s11
	v_readlane_b32 s9, v78, s11
	v_fma_f32 v31, -s6, v110, v31
	v_fma_f32 v181, -s7, v16, v181
	v_fma_f32 v180, -s8, v104, v180
	v_fma_f32 v30, -s9, v12, v30
	s_nop 0
	s_nop 0
	v_readlane_b32 s6, v28, s11
	v_readlane_b32 s7, v74, s11
	v_readlane_b32 s8, v14, s38
	v_readlane_b32 s9, v70, s38
	v_fma_f32 v31, -s6, v96, v31
	v_fma_f32 v181, -s7, v10, v181
	v_fma_f32 v180, -s8, v94, v180
	v_fma_f32 v30, -s9, v8, v30
	s_nop 0
	s_nop 0
	v_readlane_b32 s6, v66, s38
	v_readlane_b32 s7, v62, s38
	v_readlane_b32 s8, v14, s11
	v_readlane_b32 s9, v70, s11
	v_fma_f32 v31, -s6, v92, v31
	v_fma_f32 v181, -s7, v4, v181
	v_fma_f32 v180, -s8, v90, v180
	v_fma_f32 v30, -s9, v91, v30
	s_nop 0
	s_nop 0
	v_readlane_b32 s6, v66, s11
	s_nop 1
	v_fma_f32 v31, -s6, v88, v31
	s_nop 0
	s_nop 0
	v_readlane_b32 s6, v62, s11
	s_nop 1
	v_fma_f32 v31, -s6, v89, v31
	s_nop 0
	v_pk_add_f32 v[30:31], v[180:181], v[30:31]
	v_mov_b32_e32 v181, v123
	v_mov_b32_e32 v180, v123
	v_pk_add_f32 v[30:31], v[30:31], v[30:31] op_sel:[0,1] op_sel_hi:[1,0]
	s_nop 0
	s_nop 0
	v_readlane_b32 s6, v142, s27
	v_readlane_b32 s7, v24, s27
	v_readlane_b32 s8, v84, s27
	v_readlane_b32 s9, v82, s43
	v_fma_f32 v119, -s6, v30, v119
	v_fma_f32 v181, -s7, v116, v181
	v_fma_f32 v180, -s8, v26, v180
	v_fma_f32 v118, -s9, v114, v118
	s_nop 0
	s_nop 0
	v_readlane_b32 s6, v78, s43
	v_readlane_b32 s7, v28, s43
	v_readlane_b32 s8, v74, s43
	v_readlane_b32 s9, v82, s27
	v_fma_f32 v119, -s6, v22, v119
	v_fma_f32 v181, -s7, v110, v181
	v_fma_f32 v180, -s8, v16, v180
	v_fma_f32 v118, -s9, v104, v118
	s_nop 0
	s_nop 0
	v_readlane_b32 s6, v78, s27
	v_readlane_b32 s7, v28, s27
	v_readlane_b32 s8, v74, s27
	v_readlane_b32 s9, v14, s43
	v_fma_f32 v119, -s6, v12, v119
	v_fma_f32 v181, -s7, v96, v181
	v_fma_f32 v180, -s8, v10, v180
	v_fma_f32 v118, -s9, v94, v118
	s_nop 0
	s_nop 0
	v_readlane_b32 s6, v70, s43
	v_readlane_b32 s7, v66, s43
	v_readlane_b32 s8, v62, s43
	v_readlane_b32 s9, v14, s27
	v_fma_f32 v119, -s6, v8, v119
	v_fma_f32 v181, -s7, v92, v181
	v_fma_f32 v180, -s8, v4, v180
	v_fma_f32 v118, -s9, v90, v118
	s_nop 0
	s_nop 0
	v_readlane_b32 s6, v70, s27
	s_nop 1
	v_fma_f32 v119, -s6, v91, v119
	s_nop 0
	s_nop 0
	v_readlane_b32 s6, v66, s27
	s_nop 1
	v_fma_f32 v119, -s6, v88, v119
	s_nop 0
	s_nop 0
	v_readlane_b32 s6, v62, s27
	s_nop 1
	v_fma_f32 v119, -s6, v89, v119
	s_nop 0
	v_pk_add_f32 v[118:119], v[180:181], v[118:119]
	v_mov_b32_e32 v181, v123
	v_mov_b32_e32 v180, v123
	v_pk_add_f32 v[118:119], v[118:119], v[118:119] op_sel:[0,1] op_sel_hi:[1,0]
	s_nop 0
	s_nop 0
	v_readlane_b32 s6, v6, s67
	v_readlane_b32 s7, v142, s67
	v_readlane_b32 s8, v24, s67
	v_readlane_b32 s9, v84, s67
	v_fma_f32 v33, -s6, v118, v33
	v_fma_f32 v181, -s7, v30, v181
	v_fma_f32 v180, -s8, v116, v180
	v_fma_f32 v32, -s9, v26, v32
	v_mov_b32_e32 v119, v30
	s_nop 0
	v_readlane_b32 s6, v82, s42
	v_readlane_b32 s7, v78, s42
	v_readlane_b32 s8, v28, s42
	v_readlane_b32 s9, v74, s42
	v_fma_f32 v33, -s6, v114, v33
	v_fma_f32 v181, -s7, v22, v181
	v_fma_f32 v180, -s8, v110, v180
	v_fma_f32 v32, -s9, v16, v32
	s_nop 0
	s_nop 0
	v_readlane_b32 s6, v82, s67
	v_readlane_b32 s7, v78, s67
	v_readlane_b32 s8, v28, s67
	v_readlane_b32 s9, v74, s67
	v_fma_f32 v33, -s6, v104, v33
	v_fma_f32 v181, -s7, v12, v181
	v_fma_f32 v180, -s8, v96, v180
	v_fma_f32 v32, -s9, v10, v32
	s_nop 0
	s_nop 0
	v_readlane_b32 s6, v14, s42
	v_readlane_b32 s7, v70, s42
	v_readlane_b32 s8, v66, s42
	v_readlane_b32 s9, v62, s42
	v_fma_f32 v33, -s6, v94, v33
	v_fma_f32 v181, -s7, v8, v181
	v_fma_f32 v180, -s8, v92, v180
	v_fma_f32 v32, -s9, v4, v32
	s_nop 0
	s_nop 0
	v_readlane_b32 s6, v14, s67
	v_readlane_b32 s7, v70, s67
	v_readlane_b32 s8, v66, s67
	v_readlane_b32 s9, v62, s67
	v_fma_f32 v33, -s6, v90, v33
	v_fma_f32 v181, -s7, v91, v181
	v_fma_f32 v180, -s8, v88, v180
	v_fma_f32 v32, -s9, v89, v32
	s_nop 0
	v_pk_add_f32 v[32:33], v[180:181], v[32:33]
	v_mov_b32_e32 v181, v123
	v_mov_b32_e32 v180, v123
	v_pk_add_f32 v[32:33], v[32:33], v[32:33] op_sel:[0,1] op_sel_hi:[1,0]
	s_nop 0
	s_nop 0
	v_readlane_b32 s6, v84, s46
	v_readlane_b32 s7, v6, s2
	v_readlane_b32 s8, v142, s2
	v_readlane_b32 s9, v24, s2
	v_fma_f32 v129, -s6, v32, v129
	v_fma_f32 v181, -s7, v118, v181
	v_fma_f32 v180, -s8, v30, v180
	v_fma_f32 v128, -s9, v116, v128
	s_nop 0
	s_nop 0
	v_readlane_b32 s6, v84, s2
	v_readlane_b32 s7, v82, s46
	v_readlane_b32 s8, v78, s46
	v_readlane_b32 s9, v28, s46
	v_fma_f32 v129, -s6, v26, v129
	v_fma_f32 v181, -s7, v114, v181
	v_fma_f32 v180, -s8, v22, v180
	v_fma_f32 v128, -s9, v110, v128
	s_nop 0
	s_nop 0
	v_readlane_b32 s6, v74, s46
	v_readlane_b32 s7, v82, s2
	v_readlane_b32 s8, v78, s2
	v_readlane_b32 s9, v28, s2
	v_fma_f32 v129, -s6, v16, v129
	v_fma_f32 v181, -s7, v104, v181
	v_fma_f32 v180, -s8, v12, v180
	v_fma_f32 v128, -s9, v96, v128
	s_nop 0
	s_nop 0
	v_readlane_b32 s6, v74, s2
	v_readlane_b32 s7, v14, s46
	v_readlane_b32 s8, v70, s46
	v_readlane_b32 s9, v66, s46
	v_fma_f32 v129, -s6, v10, v129
	v_fma_f32 v181, -s7, v94, v181
	v_fma_f32 v180, -s8, v8, v180
	v_fma_f32 v128, -s9, v92, v128
	s_nop 0
	s_nop 0
	v_readlane_b32 s6, v62, s46
	v_readlane_b32 s7, v14, s2
	v_readlane_b32 s8, v70, s2
	v_readlane_b32 s9, v66, s2
	v_fma_f32 v129, -s6, v4, v129
	v_fma_f32 v181, -s7, v90, v181
	v_fma_f32 v180, -s8, v91, v180
	v_fma_f32 v128, -s9, v88, v128
	s_nop 0
	s_nop 0
	v_readlane_b32 s6, v62, s2
	s_nop 1
	v_fma_f32 v129, -s6, v89, v129
	s_nop 0
	v_pk_add_f32 v[128:129], v[180:181], v[128:129]
	v_mov_b32_e32 v181, v123
	v_mov_b32_e32 v180, v123
	v_pk_add_f32 v[128:129], v[128:129], v[128:129] op_sel:[0,1] op_sel_hi:[1,0]
	s_nop 0
	s_nop 0
	v_readlane_b32 s6, v24, s37
	v_readlane_b32 s7, v84, s37
	v_readlane_b32 s8, v6, s18
	v_readlane_b32 s9, v142, s18
	v_fma_f32 v65, -s6, v128, v65
	v_fma_f32 v181, -s7, v32, v181
	v_fma_f32 v180, -s8, v118, v180
	v_fma_f32 v64, -s9, v30, v64
	v_mov_b32_e32 v129, v32
	s_nop 0
	v_readlane_b32 s6, v24, s18
	v_readlane_b32 s7, v84, s18
	v_readlane_b32 s8, v82, s37
	v_readlane_b32 s9, v78, s37
	v_fma_f32 v65, -s6, v116, v65
	v_fma_f32 v181, -s7, v26, v181
	v_fma_f32 v180, -s8, v114, v180
	v_fma_f32 v64, -s9, v22, v64
	s_nop 0
	s_nop 0
	v_readlane_b32 s6, v28, s37
	v_readlane_b32 s7, v74, s37
	v_readlane_b32 s8, v82, s18
	v_readlane_b32 s9, v78, s18
	v_fma_f32 v65, -s6, v110, v65
	v_fma_f32 v181, -s7, v16, v181
	v_fma_f32 v180, -s8, v104, v180
	v_fma_f32 v64, -s9, v12, v64
	s_nop 0
	s_nop 0
	v_readlane_b32 s6, v28, s18
	v_readlane_b32 s7, v74, s18
	v_readlane_b32 s8, v14, s37
	v_readlane_b32 s9, v70, s37
	v_fma_f32 v65, -s6, v96, v65
	v_fma_f32 v181, -s7, v10, v181
	v_fma_f32 v180, -s8, v94, v180
	v_fma_f32 v64, -s9, v8, v64
	s_nop 0
	s_nop 0
	v_readlane_b32 s6, v66, s37
	v_readlane_b32 s7, v62, s37
	v_readlane_b32 s8, v14, s18
	v_readlane_b32 s9, v70, s18
	v_fma_f32 v65, -s6, v92, v65
	v_fma_f32 v181, -s7, v4, v181
	v_fma_f32 v180, -s8, v90, v180
	v_fma_f32 v64, -s9, v91, v64
	s_nop 0
	s_nop 0
	v_readlane_b32 s6, v66, s18
	s_nop 1
	v_fma_f32 v65, -s6, v88, v65
	s_nop 0
	s_nop 0
	v_readlane_b32 s6, v62, s18
	s_nop 1
	v_fma_f32 v65, -s6, v89, v65
	s_nop 0
	v_pk_add_f32 v[64:65], v[180:181], v[64:65]
	v_mov_b32_e32 v181, v123
	v_mov_b32_e32 v180, v123
	v_pk_add_f32 v[64:65], v[64:65], v[64:65] op_sel:[0,1] op_sel_hi:[1,0]
	s_nop 0
	s_nop 0
	v_readlane_b32 s6, v142, s40
	v_readlane_b32 s7, v24, s40
	v_readlane_b32 s8, v84, s40
	v_readlane_b32 s9, v6, s19
	v_fma_f32 v131, -s6, v64, v131
	v_fma_f32 v181, -s7, v128, v181
	v_fma_f32 v180, -s8, v32, v180
	v_fma_f32 v130, -s9, v118, v130
	s_nop 0
	s_nop 0
	v_readlane_b32 s6, v142, s19
	v_readlane_b32 s7, v24, s19
	v_readlane_b32 s8, v84, s19
	v_readlane_b32 s9, v82, s40
	v_fma_f32 v131, -s6, v30, v131
	v_fma_f32 v181, -s7, v116, v181
	v_fma_f32 v180, -s8, v26, v180
	v_fma_f32 v130, -s9, v114, v130
	s_nop 0
	s_nop 0
	v_readlane_b32 s6, v78, s40
	v_readlane_b32 s7, v28, s40
	v_readlane_b32 s8, v74, s40
	v_readlane_b32 s9, v82, s19
	v_fma_f32 v131, -s6, v22, v131
	v_fma_f32 v181, -s7, v110, v181
	v_fma_f32 v180, -s8, v16, v180
	v_fma_f32 v130, -s9, v104, v130
	s_nop 0
	s_nop 0
	v_readlane_b32 s6, v78, s19
	v_readlane_b32 s7, v28, s19
	v_readlane_b32 s8, v74, s19
	v_readlane_b32 s9, v14, s40
	v_fma_f32 v131, -s6, v12, v131
	v_fma_f32 v181, -s7, v96, v181
	v_fma_f32 v180, -s8, v10, v180
	v_fma_f32 v130, -s9, v94, v130
	s_nop 0
	s_nop 0
	v_readlane_b32 s6, v70, s40
	v_readlane_b32 s7, v66, s40
	v_readlane_b32 s8, v62, s40
	v_readlane_b32 s9, v14, s19
	v_fma_f32 v131, -s6, v8, v131
	v_fma_f32 v181, -s7, v92, v181
	v_fma_f32 v180, -s8, v4, v180
	v_fma_f32 v130, -s9, v90, v130
	s_nop 0
	s_nop 0
	v_readlane_b32 s6, v70, s19
	s_nop 1
	v_fma_f32 v131, -s6, v91, v131
	s_nop 0
	s_nop 0
	v_readlane_b32 s6, v66, s19
	s_nop 1
	v_fma_f32 v131, -s6, v88, v131
	s_nop 0
	s_nop 0
	v_readlane_b32 s6, v62, s19
	s_nop 1
	v_fma_f32 v131, -s6, v89, v131
	s_nop 0
	v_pk_add_f32 v[130:131], v[180:181], v[130:131]
	v_mov_b32_e32 v181, v123
	v_mov_b32_e32 v180, v123
	v_pk_add_f32 v[130:131], v[130:131], v[130:131] op_sel:[0,1] op_sel_hi:[1,0]
	s_nop 0
	s_nop 0
	v_readlane_b32 s6, v6, s44
	v_readlane_b32 s7, v142, s44
	v_readlane_b32 s8, v24, s44
	v_readlane_b32 s9, v84, s44
	v_fma_f32 v69, -s6, v130, v69
	v_fma_f32 v181, -s7, v64, v181
	v_fma_f32 v180, -s8, v128, v180
	v_fma_f32 v68, -s9, v32, v68
	v_mov_b32_e32 v131, v64
	s_nop 0
	v_readlane_b32 s6, v6, s68
	v_readlane_b32 s7, v142, s68
	v_readlane_b32 s8, v24, s68
	v_readlane_b32 s9, v84, s68
	v_fma_f32 v69, -s6, v118, v69
	v_fma_f32 v181, -s7, v30, v181
	v_fma_f32 v180, -s8, v116, v180
	v_fma_f32 v68, -s9, v26, v68
	s_nop 0
	s_nop 0
	v_readlane_b32 s6, v82, s44
	v_readlane_b32 s7, v78, s44
	v_readlane_b32 s8, v28, s44
	v_readlane_b32 s9, v74, s44
	v_fma_f32 v69, -s6, v114, v69
	v_fma_f32 v181, -s7, v22, v181
	v_fma_f32 v180, -s8, v110, v180
	v_fma_f32 v68, -s9, v16, v68
	s_nop 0
	s_nop 0
	v_readlane_b32 s6, v82, s68
	v_readlane_b32 s7, v78, s68
	v_readlane_b32 s8, v28, s68
	v_readlane_b32 s9, v74, s68
	v_fma_f32 v69, -s6, v104, v69
	v_fma_f32 v181, -s7, v12, v181
	v_fma_f32 v180, -s8, v96, v180
	v_fma_f32 v68, -s9, v10, v68
	s_nop 0
	s_nop 0
	v_readlane_b32 s6, v14, s44
	v_readlane_b32 s7, v70, s44
	v_readlane_b32 s8, v66, s44
	v_readlane_b32 s9, v62, s44
	v_fma_f32 v69, -s6, v94, v69
	v_fma_f32 v181, -s7, v8, v181
	v_fma_f32 v180, -s8, v92, v180
	v_fma_f32 v68, -s9, v4, v68
	s_nop 0
	s_nop 0
	v_readlane_b32 s6, v14, s68
	v_readlane_b32 s7, v70, s68
	v_readlane_b32 s8, v66, s68
	v_readlane_b32 s9, v62, s68
	v_fma_f32 v69, -s6, v90, v69
	v_fma_f32 v181, -s7, v91, v181
	v_fma_f32 v180, -s8, v88, v180
	v_fma_f32 v68, -s9, v89, v68
	s_nop 0
	v_pk_add_f32 v[68:69], v[180:181], v[68:69]
	v_mov_b32_e32 v181, v123
	v_mov_b32_e32 v180, v123
	v_pk_add_f32 v[68:69], v[68:69], v[68:69] op_sel:[0,1] op_sel_hi:[1,0]
	s_nop 0
	s_nop 0
	v_readlane_b32 s6, v140, s3
	v_readlane_b32 s7, v6, s35
	v_readlane_b32 s8, v142, s35
	v_readlane_b32 s9, v24, s35
	v_fma_f32 v133, -s6, v68, v133
	v_fma_f32 v181, -s7, v130, v181
	v_fma_f32 v180, -s8, v64, v180
	v_fma_f32 v132, -s9, v128, v132
	s_nop 0
	s_nop 0
	v_readlane_b32 s6, v84, s35
	v_readlane_b32 s7, v6, s3
	v_readlane_b32 s8, v142, s3
	v_readlane_b32 s9, v24, s3
	v_fma_f32 v133, -s6, v32, v133
	v_fma_f32 v181, -s7, v118, v181
	v_fma_f32 v180, -s8, v30, v180
	v_fma_f32 v132, -s9, v116, v132
	s_nop 0
	s_nop 0
	v_readlane_b32 s6, v84, s3
	v_readlane_b32 s7, v82, s35
	v_readlane_b32 s8, v78, s35
	v_readlane_b32 s9, v28, s35
	v_fma_f32 v133, -s6, v26, v133
	v_fma_f32 v181, -s7, v114, v181
	v_fma_f32 v180, -s8, v22, v180
	v_fma_f32 v132, -s9, v110, v132
	s_nop 0
	s_nop 0
	v_readlane_b32 s6, v74, s35
	v_readlane_b32 s7, v82, s3
	v_readlane_b32 s8, v78, s3
	v_readlane_b32 s9, v28, s3
	v_fma_f32 v133, -s6, v16, v133
	v_fma_f32 v181, -s7, v104, v181
	v_fma_f32 v180, -s8, v12, v180
	v_fma_f32 v132, -s9, v96, v132
	s_nop 0
	s_nop 0
	v_readlane_b32 s6, v74, s3
	v_readlane_b32 s7, v14, s35
	v_readlane_b32 s8, v70, s35
	v_readlane_b32 s9, v66, s35
	v_fma_f32 v133, -s6, v10, v133
	v_fma_f32 v181, -s7, v94, v181
	v_fma_f32 v180, -s8, v8, v180
	v_fma_f32 v132, -s9, v92, v132
	s_nop 0
	s_nop 0
	v_readlane_b32 s6, v62, s35
	v_readlane_b32 s7, v14, s3
	v_readlane_b32 s8, v70, s3
	v_readlane_b32 s9, v66, s3
	v_fma_f32 v133, -s6, v4, v133
	v_fma_f32 v181, -s7, v90, v181
	v_fma_f32 v180, -s8, v91, v180
	v_fma_f32 v132, -s9, v88, v132
	s_nop 0
	s_nop 0
	v_readlane_b32 s6, v62, s3
	s_nop 1
	v_fma_f32 v133, -s6, v89, v133
	s_nop 0
	v_pk_add_f32 v[132:133], v[180:181], v[132:133]
	v_mov_b32_e32 v181, v123
	v_mov_b32_e32 v180, v123
	v_pk_add_f32 v[132:133], v[132:133], v[132:133] op_sel:[0,1] op_sel_hi:[1,0]
	s_nop 0
	s_nop 0
	v_readlane_b32 s6, v144, s16
	v_readlane_b32 s7, v140, s16
	v_readlane_b32 s8, v6, s30
	v_readlane_b32 s9, v142, s30
	v_fma_f32 v73, -s6, v132, v73
	v_fma_f32 v181, -s7, v68, v181
	v_fma_f32 v180, -s8, v130, v180
	v_fma_f32 v72, -s9, v64, v72
	v_mov_b32_e32 v133, v68
	s_nop 0
	v_readlane_b32 s6, v24, s30
	v_readlane_b32 s7, v84, s30
	v_readlane_b32 s8, v6, s16
	v_readlane_b32 s9, v142, s16
	v_fma_f32 v73, -s6, v128, v73
	v_fma_f32 v181, -s7, v32, v181
	v_fma_f32 v180, -s8, v118, v180
	v_fma_f32 v72, -s9, v30, v72
	s_nop 0
	s_nop 0
	v_readlane_b32 s6, v24, s16
	v_readlane_b32 s7, v84, s16
	v_readlane_b32 s8, v82, s30
	v_readlane_b32 s9, v78, s30
	v_fma_f32 v73, -s6, v116, v73
	v_fma_f32 v181, -s7, v26, v181
	v_fma_f32 v180, -s8, v114, v180
	v_fma_f32 v72, -s9, v22, v72
	s_nop 0
	s_nop 0
	v_readlane_b32 s6, v28, s30
	v_readlane_b32 s7, v74, s30
	v_readlane_b32 s8, v82, s16
	v_readlane_b32 s9, v78, s16
	v_fma_f32 v73, -s6, v110, v73
	v_fma_f32 v181, -s7, v16, v181
	v_fma_f32 v180, -s8, v104, v180
	v_fma_f32 v72, -s9, v12, v72
	s_nop 0
	s_nop 0
	v_readlane_b32 s6, v28, s16
	v_readlane_b32 s7, v74, s16
	v_readlane_b32 s8, v14, s30
	v_readlane_b32 s9, v70, s30
	v_fma_f32 v73, -s6, v96, v73
	v_fma_f32 v181, -s7, v10, v181
	v_fma_f32 v180, -s8, v94, v180
	v_fma_f32 v72, -s9, v8, v72
	s_nop 0
	s_nop 0
	v_readlane_b32 s6, v66, s30
	v_readlane_b32 s7, v62, s30
	v_readlane_b32 s8, v14, s16
	v_readlane_b32 s9, v70, s16
	v_fma_f32 v73, -s6, v92, v73
	v_fma_f32 v181, -s7, v4, v181
	v_fma_f32 v180, -s8, v90, v180
	v_fma_f32 v72, -s9, v91, v72
	s_nop 0
	s_nop 0
	v_readlane_b32 s6, v66, s16
	s_nop 1
	v_fma_f32 v73, -s6, v88, v73
	s_nop 0
	s_nop 0
	v_readlane_b32 s6, v62, s16
	s_nop 1
	v_fma_f32 v73, -s6, v89, v73
	s_nop 0
	v_pk_add_f32 v[72:73], v[180:181], v[72:73]
	v_mov_b32_e32 v181, v123
	v_mov_b32_e32 v180, v123
	v_pk_add_f32 v[72:73], v[72:73], v[72:73] op_sel:[0,1] op_sel_hi:[1,0]
	s_nop 0
	s_nop 0
	v_readlane_b32 s6, v146, s17
	v_readlane_b32 s7, v144, s17
	v_readlane_b32 s8, v140, s17
	v_readlane_b32 s9, v6, s36
	v_fma_f32 v135, -s6, v72, v135
	v_fma_f32 v181, -s7, v132, v181
	v_fma_f32 v180, -s8, v68, v180
	v_fma_f32 v134, -s9, v130, v134
	s_nop 0
	s_nop 0
	v_readlane_b32 s6, v142, s36
	v_readlane_b32 s7, v24, s36
	v_readlane_b32 s8, v84, s36
	v_readlane_b32 s9, v6, s17
	v_fma_f32 v135, -s6, v64, v135
	v_fma_f32 v181, -s7, v128, v181
	v_fma_f32 v180, -s8, v32, v180
	v_fma_f32 v134, -s9, v118, v134
	s_nop 0
	s_nop 0
	v_readlane_b32 s6, v142, s17
	v_readlane_b32 s7, v24, s17
	v_readlane_b32 s8, v84, s17
	v_readlane_b32 s9, v82, s36
	v_fma_f32 v135, -s6, v30, v135
	v_fma_f32 v181, -s7, v116, v181
	v_fma_f32 v180, -s8, v26, v180
	v_fma_f32 v134, -s9, v114, v134
	s_nop 0
	s_nop 0
	v_readlane_b32 s6, v78, s36
	v_readlane_b32 s7, v28, s36
	v_readlane_b32 s8, v74, s36
	v_readlane_b32 s9, v82, s17
	v_fma_f32 v135, -s6, v22, v135
	v_fma_f32 v181, -s7, v110, v181
	v_fma_f32 v180, -s8, v16, v180
	v_fma_f32 v134, -s9, v104, v134
	s_nop 0
	s_nop 0
	v_readlane_b32 s6, v78, s17
	v_readlane_b32 s7, v28, s17
	v_readlane_b32 s8, v74, s17
	v_readlane_b32 s9, v14, s36
	v_fma_f32 v135, -s6, v12, v135
	v_fma_f32 v181, -s7, v96, v181
	v_fma_f32 v180, -s8, v10, v180
	v_fma_f32 v134, -s9, v94, v134
	s_nop 0
	s_nop 0
	v_readlane_b32 s6, v70, s36
	v_readlane_b32 s7, v66, s36
	v_readlane_b32 s8, v62, s36
	v_readlane_b32 s9, v14, s17
	v_fma_f32 v135, -s6, v8, v135
	v_fma_f32 v181, -s7, v92, v181
	v_fma_f32 v180, -s8, v4, v180
	v_fma_f32 v134, -s9, v90, v134
	s_nop 0
	s_nop 0
	v_readlane_b32 s6, v70, s17
	s_nop 1
	v_fma_f32 v135, -s6, v91, v135
	s_nop 0
	s_nop 0
	v_readlane_b32 s6, v66, s17
	s_nop 1
	v_fma_f32 v135, -s6, v88, v135
	s_nop 0
	s_nop 0
	v_readlane_b32 s6, v62, s17
	s_nop 1
	v_fma_f32 v135, -s6, v89, v135
	s_nop 0
	v_pk_add_f32 v[134:135], v[180:181], v[134:135]
	v_mov_b32_e32 v181, v123
	v_mov_b32_e32 v180, v123
	v_pk_add_f32 v[134:135], v[134:135], v[134:135] op_sel:[0,1] op_sel_hi:[1,0]
	s_nop 0
	s_nop 0
	v_readlane_b32 s6, v2, s69
	v_readlane_b32 s7, v146, s69
	v_readlane_b32 s8, v144, s69
	v_readlane_b32 s9, v140, s69
	v_fma_f32 v77, -s6, v134, v77
	v_fma_f32 v181, -s7, v72, v181
	v_fma_f32 v180, -s8, v132, v180
	v_fma_f32 v76, -s9, v68, v76
	v_mov_b32_e32 v135, v72
	s_nop 0
	v_readlane_b32 s6, v6, s12
	v_readlane_b32 s7, v142, s12
	v_readlane_b32 s8, v24, s12
	v_readlane_b32 s9, v84, s12
	v_fma_f32 v77, -s6, v130, v77
	v_fma_f32 v181, -s7, v64, v181
	v_fma_f32 v180, -s8, v128, v180
	v_fma_f32 v76, -s9, v32, v76
	s_nop 0
	s_nop 0
	v_readlane_b32 s6, v6, s69
	v_readlane_b32 s7, v142, s69
	v_readlane_b32 s8, v24, s69
	v_readlane_b32 s9, v84, s69
	v_fma_f32 v77, -s6, v118, v77
	v_fma_f32 v181, -s7, v30, v181
	v_fma_f32 v180, -s8, v116, v180
	v_fma_f32 v76, -s9, v26, v76
	s_nop 0
	s_nop 0
	v_readlane_b32 s6, v82, s12
	v_readlane_b32 s7, v78, s12
	v_readlane_b32 s8, v28, s12
	v_readlane_b32 s9, v74, s12
	v_fma_f32 v77, -s6, v114, v77
	v_fma_f32 v181, -s7, v22, v181
	v_fma_f32 v180, -s8, v110, v180
	v_fma_f32 v76, -s9, v16, v76
	s_nop 0
	s_nop 0
	v_readlane_b32 s6, v82, s69
	v_readlane_b32 s7, v78, s69
	v_readlane_b32 s8, v28, s69
	v_readlane_b32 s9, v74, s69
	v_fma_f32 v77, -s6, v104, v77
	v_fma_f32 v181, -s7, v12, v181
	v_fma_f32 v180, -s8, v96, v180
	v_fma_f32 v76, -s9, v10, v76
	s_nop 0
	s_nop 0
	v_readlane_b32 s6, v14, s12
	v_readlane_b32 s7, v70, s12
	v_readlane_b32 s8, v66, s12
	v_readlane_b32 s9, v62, s12
	v_fma_f32 v77, -s6, v94, v77
	v_fma_f32 v181, -s7, v8, v181
	v_fma_f32 v180, -s8, v92, v180
	v_fma_f32 v76, -s9, v4, v76
	s_nop 0
	s_nop 0
	v_readlane_b32 s6, v14, s69
	v_readlane_b32 s7, v70, s69
	v_readlane_b32 s8, v66, s69
	v_readlane_b32 s9, v62, s69
	v_fma_f32 v77, -s6, v90, v77
	v_fma_f32 v181, -s7, v91, v181
	v_fma_f32 v180, -s8, v88, v180
	v_fma_f32 v76, -s9, v89, v76
	s_nop 0
	v_pk_add_f32 v[76:77], v[180:181], v[76:77]
	v_mov_b32_e32 v181, v123
	v_mov_b32_e32 v180, v123
	v_pk_add_f32 v[76:77], v[76:77], v[76:77] op_sel:[0,1] op_sel_hi:[1,0]
	s_nop 0
	s_nop 0
	v_readlane_b32 s6, v140, s15
	v_readlane_b32 s7, v2, s23
	v_readlane_b32 s8, v146, s23
	v_readlane_b32 s9, v144, s23
	v_fma_f32 v137, -s6, v76, v137
	v_fma_f32 v181, -s7, v134, v181
	v_fma_f32 v180, -s8, v72, v180
	v_fma_f32 v136, -s9, v132, v136
	s_nop 0
	s_nop 0
	v_readlane_b32 s6, v140, s23
	v_readlane_b32 s7, v6, s15
	v_readlane_b32 s8, v142, s15
	v_readlane_b32 s9, v24, s15
	v_fma_f32 v137, -s6, v68, v137
	v_fma_f32 v181, -s7, v130, v181
	v_fma_f32 v180, -s8, v64, v180
	v_fma_f32 v136, -s9, v128, v136
	s_nop 0
	s_nop 0
	v_readlane_b32 s6, v84, s15
	v_readlane_b32 s7, v6, s23
	v_readlane_b32 s8, v142, s23
	v_readlane_b32 s9, v24, s23
	v_fma_f32 v137, -s6, v32, v137
	v_fma_f32 v181, -s7, v118, v181
	v_fma_f32 v180, -s8, v30, v180
	v_fma_f32 v136, -s9, v116, v136
	s_nop 0
	s_nop 0
	v_readlane_b32 s6, v84, s23
	v_readlane_b32 s7, v82, s15
	v_readlane_b32 s8, v78, s15
	v_readlane_b32 s9, v28, s15
	v_fma_f32 v137, -s6, v26, v137
	v_fma_f32 v181, -s7, v114, v181
	v_fma_f32 v180, -s8, v22, v180
	v_fma_f32 v136, -s9, v110, v136
	s_nop 0
	s_nop 0
	v_readlane_b32 s6, v74, s15
	v_readlane_b32 s7, v82, s23
	v_readlane_b32 s8, v78, s23
	v_readlane_b32 s9, v28, s23
	v_fma_f32 v137, -s6, v16, v137
	v_fma_f32 v181, -s7, v104, v181
	v_fma_f32 v180, -s8, v12, v180
	v_fma_f32 v136, -s9, v96, v136
	s_nop 0
	s_nop 0
	v_readlane_b32 s6, v74, s23
	v_readlane_b32 s7, v14, s15
	v_readlane_b32 s8, v70, s15
	v_readlane_b32 s9, v66, s15
	v_fma_f32 v137, -s6, v10, v137
	v_fma_f32 v181, -s7, v94, v181
	v_fma_f32 v180, -s8, v8, v180
	v_fma_f32 v136, -s9, v92, v136
	s_nop 0
	s_nop 0
	v_readlane_b32 s6, v62, s15
	v_readlane_b32 s7, v14, s23
	v_readlane_b32 s8, v70, s23
	v_readlane_b32 s9, v66, s23
	v_fma_f32 v137, -s6, v4, v137
	v_fma_f32 v181, -s7, v90, v181
	v_fma_f32 v180, -s8, v91, v180
	v_fma_f32 v136, -s9, v88, v136
	s_nop 0
	s_nop 0
	v_readlane_b32 s6, v62, s23
	s_nop 1
	v_fma_f32 v137, -s6, v89, v137
	s_nop 0
	v_pk_add_f32 v[136:137], v[180:181], v[136:137]
	v_mov_b32_e32 v181, v123
	v_mov_b32_e32 v180, v123
	v_pk_add_f32 v[136:137], v[136:137], v[136:137] op_sel:[0,1] op_sel_hi:[1,0]
	s_nop 0
	s_nop 0
	v_readlane_b32 s6, v144, s26
	v_readlane_b32 s7, v140, s26
	v_readlane_b32 s8, v2, s10
	v_readlane_b32 s9, v146, s10
	v_fma_f32 v81, -s6, v136, v81
	v_fma_f32 v181, -s7, v76, v181
	v_fma_f32 v180, -s8, v134, v180
	v_fma_f32 v80, -s9, v72, v80
	v_mov_b32_e32 v137, v76
	s_nop 0
	v_readlane_b32 s6, v144, s10
	v_readlane_b32 s7, v140, s10
	v_readlane_b32 s8, v6, s26
	v_readlane_b32 s9, v142, s26
	v_fma_f32 v81, -s6, v132, v81
	v_fma_f32 v181, -s7, v68, v181
	v_fma_f32 v180, -s8, v130, v180
	v_fma_f32 v80, -s9, v64, v80
	s_nop 0
	s_nop 0
	v_readlane_b32 s6, v24, s26
	v_readlane_b32 s7, v84, s26
	v_readlane_b32 s8, v6, s10
	v_readlane_b32 s9, v142, s10
	v_fma_f32 v81, -s6, v128, v81
	v_fma_f32 v181, -s7, v32, v181
	v_fma_f32 v180, -s8, v118, v180
	v_fma_f32 v80, -s9, v30, v80
	s_nop 0
	s_nop 0
	v_readlane_b32 s6, v24, s10
	v_readlane_b32 s7, v84, s10
	v_readlane_b32 s8, v82, s26
	v_readlane_b32 s9, v78, s26
	v_fma_f32 v81, -s6, v116, v81
	v_fma_f32 v181, -s7, v26, v181
	v_fma_f32 v180, -s8, v114, v180
	v_fma_f32 v80, -s9, v22, v80
	s_nop 0
	s_nop 0
	v_readlane_b32 s6, v28, s26
	v_readlane_b32 s7, v74, s26
	v_readlane_b32 s8, v82, s10
	v_readlane_b32 s9, v78, s10
	v_fma_f32 v81, -s6, v110, v81
	v_fma_f32 v181, -s7, v16, v181
	v_fma_f32 v180, -s8, v104, v180
	v_fma_f32 v80, -s9, v12, v80
	s_nop 0
	s_nop 0
	v_readlane_b32 s6, v28, s10
	v_readlane_b32 s7, v74, s10
	v_readlane_b32 s8, v14, s26
	v_readlane_b32 s9, v70, s26
	v_fma_f32 v81, -s6, v96, v81
	v_fma_f32 v181, -s7, v10, v181
	v_fma_f32 v180, -s8, v94, v180
	v_fma_f32 v80, -s9, v8, v80
	s_nop 0
	s_nop 0
	v_readlane_b32 s6, v66, s26
	v_readlane_b32 s7, v62, s26
	v_readlane_b32 s8, v14, s10
	v_readlane_b32 s9, v70, s10
	v_fma_f32 v81, -s6, v92, v81
	v_fma_f32 v181, -s7, v4, v181
	v_fma_f32 v180, -s8, v90, v180
	v_fma_f32 v80, -s9, v91, v80
	s_nop 0
	s_nop 0
	v_readlane_b32 s6, v66, s10
	s_nop 1
	v_fma_f32 v81, -s6, v88, v81
	s_nop 0
	s_nop 0
	v_readlane_b32 s6, v62, s10
	s_nop 1
	v_fma_f32 v81, -s6, v89, v81
	s_nop 0
	v_pk_add_f32 v[80:81], v[180:181], v[80:81]
	v_mov_b32_e32 v181, v123
	v_mov_b32_e32 v180, v123
	v_pk_add_f32 v[80:81], v[80:81], v[80:81] op_sel:[0,1] op_sel_hi:[1,0]
	s_nop 0
	s_nop 0
	v_readlane_b32 s6, v146, s13
	v_readlane_b32 s7, v144, s13
	v_readlane_b32 s8, v140, s13
	v_readlane_b32 s9, v2, s31
	v_fma_f32 v139, -s6, v80, v139
	v_fma_f32 v181, -s7, v136, v181
	v_fma_f32 v180, -s8, v76, v180
	v_fma_f32 v138, -s9, v134, v138
	v_mov_b32_e32 v2, v123
	s_nop 0
	v_readlane_b32 s6, v146, s31
	v_readlane_b32 s7, v144, s31
	v_readlane_b32 s8, v140, s31
	v_readlane_b32 s9, v6, s13
	v_fma_f32 v139, -s6, v72, v139
	v_fma_f32 v181, -s7, v132, v181
	v_fma_f32 v180, -s8, v68, v180
	v_fma_f32 v138, -s9, v130, v138
	v_mov_b32_e32 v140, v123
	s_nop 0
	v_readlane_b32 s6, v142, s13
	v_readlane_b32 s7, v24, s13
	v_readlane_b32 s8, v84, s13
	v_readlane_b32 s9, v6, s31
	v_fma_f32 v139, -s6, v64, v139
	v_fma_f32 v181, -s7, v128, v181
	v_fma_f32 v180, -s8, v32, v180
	v_fma_f32 v138, -s9, v118, v138
	v_mov_b32_e32 v144, v123
	s_nop 0
	v_readlane_b32 s6, v142, s31
	v_readlane_b32 s7, v24, s31
	v_readlane_b32 s8, v84, s31
	v_readlane_b32 s9, v82, s13
	v_fma_f32 v139, -s6, v30, v139
	v_fma_f32 v181, -s7, v116, v181
	v_fma_f32 v180, -s8, v26, v180
	v_fma_f32 v138, -s9, v114, v138
	v_mov_b32_e32 v142, v123
	s_nop 0
	v_readlane_b32 s6, v78, s13
	v_readlane_b32 s7, v28, s13
	v_readlane_b32 s8, v74, s13
	v_readlane_b32 s9, v82, s31
	v_fma_f32 v139, -s6, v22, v139
	v_fma_f32 v181, -s7, v110, v181
	v_fma_f32 v180, -s8, v16, v180
	v_fma_f32 v138, -s9, v104, v138
	v_mov_b32_e32 v146, v123
	s_nop 0
	v_readlane_b32 s6, v78, s31
	v_readlane_b32 s7, v28, s31
	v_readlane_b32 s8, v74, s31
	v_readlane_b32 s9, v14, s13
	v_fma_f32 v139, -s6, v12, v139
	v_fma_f32 v181, -s7, v96, v181
	v_fma_f32 v180, -s8, v10, v180
	v_fma_f32 v138, -s9, v94, v138
	v_mov_b32_e32 v84, v123
	s_nop 0
	v_readlane_b32 s6, v70, s13
	v_readlane_b32 s7, v66, s13
	v_readlane_b32 s8, v62, s13
	v_readlane_b32 s9, v14, s31
	v_fma_f32 v139, -s6, v8, v139
	v_fma_f32 v181, -s7, v92, v181
	v_fma_f32 v180, -s8, v4, v180
	v_fma_f32 v138, -s9, v90, v138
	v_mov_b32_e32 v82, v123
	s_nop 0
	v_readlane_b32 s6, v70, s31
	s_nop 1
	v_fma_f32 v139, -s6, v91, v139
	v_mov_b32_e32 v78, v123
	s_nop 0
	v_readlane_b32 s6, v66, s31
	s_nop 1
	v_fma_f32 v139, -s6, v88, v139
	v_mov_b32_e32 v74, v123
	s_nop 0
	v_readlane_b32 s6, v62, s31
	s_nop 1
	v_fma_f32 v139, -s6, v89, v139
	v_mov_b32_e32 v70, v123
	v_pk_add_f32 v[138:139], v[180:181], v[138:139]
	v_mov_b32_e32 v181, v123
	v_mov_b32_e32 v180, v123
	v_pk_add_f32 v[138:139], v[138:139], v[138:139] op_sel:[0,1] op_sel_hi:[1,0]
	v_mov_b32_e32 v66, v123
	v_readlane_b32 s98, v251, 55
	s_nop 3
	s_mul_i32 s98, s98, 9
	s_add_i32 s98, s98, 0x4000
	v_mbcnt_lo_u32_b32 v255, -1, 0
	v_mbcnt_hi_u32_b32 v255, -1, v255
	v_and_b32_e32 v253, 31, v255
	v_lshrrev_b32_e32 v254, 5, v255
	v_cmp_lt_u32_e64 s[96:97], 31, v255
	v_mul_u32_u24_e32 v248, 0x210, v254
	v_lshl_add_u32 v248, v253, 2, v248
	v_add_u32_e32 v248, s98, v248
	v_mul_u32_u24_e32 v249, 0x84, v253
	v_add_u32_e32 v249, s98, v249
	v_lshlrev_b32_e32 v255, 2, v253
	v_add_u32_e32 v255, 0x1080, v255
	v_add_u32_e32 v255, s98, v255
	ds_write_b32 v255, v123
	s_add_i32 s98, s98, 0x1080
	v_mov_b32_e32 v253, s98
	s_nop 1
	v_cndmask_b32_e64 v249, v253, v249, s[96:97]
	v_mov_b32_e32 v244, v134
	v_mov_b32_e32 v245, v138
	s_nop 1
	v_permlane32_swap_b32_e32 v245, v244
	s_nop 1
	v_mfma_f32_32x32x2_f32 v[228:243], v244, v226, 0
	v_mov_b32_e32 v246, v72
	v_mov_b32_e32 v247, v80
	s_nop 1
	v_permlane32_swap_b32_e32 v247, v246
	s_nop 1
	v_mfma_f32_32x32x2_f32 v[228:243], v246, v225, v[228:243]
	v_mov_b32_e32 v244, v132
	v_mov_b32_e32 v245, v136
	s_nop 1
	v_permlane32_swap_b32_e32 v245, v244
	s_nop 1
	v_mfma_f32_32x32x2_f32 v[228:243], v244, v224, v[228:243]
	v_mov_b32_e32 v246, v68
	v_mov_b32_e32 v247, v76
	s_nop 1
	v_permlane32_swap_b32_e32 v247, v246
	s_nop 1
	v_mfma_f32_32x32x2_f32 v[228:243], v246, v223, v[228:243]
	v_mov_b32_e32 v244, v118
	v_mov_b32_e32 v245, v130
	s_nop 1
	v_permlane32_swap_b32_e32 v245, v244
	s_nop 1
	v_mfma_f32_32x32x2_f32 v[228:243], v244, v222, v[228:243]
	v_mov_b32_e32 v246, v30
	v_mov_b32_e32 v247, v64
	s_nop 1
	v_permlane32_swap_b32_e32 v247, v246
	s_nop 1
	v_mfma_f32_32x32x2_f32 v[228:243], v246, v221, v[228:243]
	v_mov_b32_e32 v244, v116
	v_mov_b32_e32 v245, v128
	s_nop 1
	v_permlane32_swap_b32_e32 v245, v244
	s_nop 1
	v_mfma_f32_32x32x2_f32 v[228:243], v244, v220, v[228:243]
	v_mov_b32_e32 v246, v26
	v_mov_b32_e32 v247, v32
	s_nop 1
	v_permlane32_swap_b32_e32 v247, v246
	s_nop 1
	v_mfma_f32_32x32x2_f32 v[228:243], v246, v219, v[228:243]
	v_mov_b32_e32 v244, v104
	v_mov_b32_e32 v245, v114
	s_nop 1
	v_permlane32_swap_b32_e32 v245, v244
	s_nop 1
	v_mfma_f32_32x32x2_f32 v[228:243], v244, v218, v[228:243]
	v_mov_b32_e32 v246, v12
	v_mov_b32_e32 v247, v22
	s_nop 1
	v_permlane32_swap_b32_e32 v247, v246
	s_nop 1
	v_mfma_f32_32x32x2_f32 v[228:243], v246, v217, v[228:243]
	v_mov_b32_e32 v244, v96
	v_mov_b32_e32 v245, v110
	s_nop 1
	v_permlane32_swap_b32_e32 v245, v244
	s_nop 1
	v_mfma_f32_32x32x2_f32 v[228:243], v244, v216, v[228:243]
	v_mov_b32_e32 v246, v10
	v_mov_b32_e32 v247, v16
	s_nop 1
	v_permlane32_swap_b32_e32 v247, v246
	s_nop 1
	v_mfma_f32_32x32x2_f32 v[228:243], v246, v215, v[228:243]
	v_mov_b32_e32 v244, v90
	v_mov_b32_e32 v245, v94
	s_nop 1
	v_permlane32_swap_b32_e32 v245, v244
	s_nop 1
	v_mfma_f32_32x32x2_f32 v[228:243], v244, v214, v[228:243]
	v_mov_b32_e32 v246, v91
	v_mov_b32_e32 v247, v8
	s_nop 1
	v_permlane32_swap_b32_e32 v247, v246
	s_nop 1
	v_mfma_f32_32x32x2_f32 v[228:243], v246, v213, v[228:243]
	v_mov_b32_e32 v244, v88
	v_mov_b32_e32 v245, v92
	s_nop 1
	v_permlane32_swap_b32_e32 v245, v244
	s_nop 1
	v_mfma_f32_32x32x2_f32 v[228:243], v244, v212, v[228:243]
	v_mov_b32_e32 v246, v89
	v_mov_b32_e32 v247, v4
	s_nop 1
	v_permlane32_swap_b32_e32 v247, v246
	s_nop 1
	v_mfma_f32_32x32x2_f32 v[228:243], v246, v211, v[228:243]
	s_nop 15
	s_nop 3
	ds_write_b32 v248, v228 offset:0
	ds_write_b32 v248, v229 offset:132
	ds_write_b32 v248, v230 offset:264
	ds_write_b32 v248, v231 offset:396
	ds_write_b32 v248, v232 offset:1056
	ds_write_b32 v248, v233 offset:1188
	ds_write_b32 v248, v234 offset:1320
	ds_write_b32 v248, v235 offset:1452
	ds_write_b32 v248, v236 offset:2112
	ds_write_b32 v248, v237 offset:2244
	ds_write_b32 v248, v238 offset:2376
	ds_write_b32 v248, v239 offset:2508
	ds_write_b32 v248, v240 offset:3168
	ds_write_b32 v248, v241 offset:3300
	ds_write_b32 v248, v242 offset:3432
	ds_write_b32 v248, v243 offset:3564
	s_waitcnt lgkmcnt(0)
	ds_read_b32 v246, v249 offset:124
	s_mov_b32 s96, 0x9003000
	s_mov_b32 s97, 0
	v_lshl_add_u64 v[244:245], v[98:99], 0, s[96:97]
	global_load_dwordx4 v[212:215], v[244:245], off offset:-4096
	global_load_dwordx4 v[216:219], v[244:245], off offset:-4064
	global_load_dwordx4 v[220:223], v[244:245], off offset:-4032
	global_load_dwordx4 v[224:227], v[244:245], off offset:-4000
	global_load_dwordx4 v[228:231], v[244:245], off
	global_load_dwordx4 v[232:235], v[244:245], off offset:32
	global_load_dwordx4 v[236:239], v[244:245], off offset:64
	global_load_dwordx4 v[240:243], v[244:245], off offset:96
	s_waitcnt lgkmcnt(0)
	v_sub_f32_e32 v153, v153, v246
	ds_read_b32 v247, v249 offset:120
	s_nop 0
	v_mov_b32_e32 v62, v123
	s_nop 0
	v_mov_b32_e32 v28, v123
	s_nop 0
	v_mov_b32_e32 v24, v123
	s_nop 0
	v_mov_b32_e32 v14, v123
	s_nop 0
	v_mov_b32_e32 v6, v123
	s_nop 0
	v_mov_b32_e32 v139, v80
	s_nop 0
	s_nop 0
	s_nop 0
	s_mov_b32 s20, 30
	v_pk_add_f32 v[152:153], v[180:181], v[152:153]
	v_mov_b32_e32 v181, v123
	v_mov_b32_e32 v180, v123
	v_pk_add_f32 v[152:153], v[152:153], v[152:153] op_sel:[0,1] op_sel_hi:[1,0]
	s_nop 0
	s_waitcnt lgkmcnt(0)
	v_sub_f32_e32 v141, v141, v247
	ds_read_b32 v246, v249 offset:116
	s_nop 0
	v_readlane_b32 s6, v209, s54
	s_nop 1
	v_fma_f32 v141, -s6, v152, v141
	s_nop 0
	s_nop 0
	s_nop 0
	s_nop 0
	s_nop 0
	s_nop 0
	s_nop 0
	s_nop 0
	s_nop 0
	s_nop 0
	s_nop 0
	s_nop 0
	s_nop 0
	s_nop 0
	s_mov_b32 s20, 29
	s_nop 0
	s_nop 1
	s_nop 0
	v_pk_add_f32 v[140:141], v[180:181], v[140:141]
	v_mov_b32_e32 v181, v123
	v_mov_b32_e32 v180, v123
	v_pk_add_f32 v[140:141], v[140:141], v[140:141] op_sel:[0,1] op_sel_hi:[1,0]
	s_nop 0
	s_waitcnt lgkmcnt(0)
	v_sub_f32_e32 v159, v159, v246
	ds_read_b32 v247, v249 offset:112
	s_nop 0
	v_readlane_b32 s6, v207, s55
	v_readlane_b32 s7, v209, s55
	s_nop 0
	v_fma_f32 v159, -s6, v140, v159
	v_fma_f32 v181, -s7, v152, v181
	v_mov_b32_e32 v141, v152
	s_nop 0
	s_nop 0
	s_nop 0
	s_nop 0
	s_nop 0
	s_nop 0
	s_nop 0
	s_nop 0
	s_nop 0
	s_nop 0
	s_nop 0
	s_nop 0
	s_nop 0
	s_mov_b32 s20, 28
	s_nop 0
	s_nop 1
	s_nop 0
	s_nop 0
	s_nop 1
	s_nop 0
	v_pk_add_f32 v[158:159], v[180:181], v[158:159]
	v_mov_b32_e32 v181, v123
	v_mov_b32_e32 v180, v123
	v_pk_add_f32 v[158:159], v[158:159], v[158:159] op_sel:[0,1] op_sel_hi:[1,0]
	s_nop 0
	s_waitcnt lgkmcnt(0)
	v_sub_f32_e32 v143, v143, v247
	ds_read_b32 v246, v249 offset:108
	s_nop 0
	v_readlane_b32 s6, v208, s56
	v_readlane_b32 s7, v207, s56
	v_readlane_b32 s8, v209, s56
	v_fma_f32 v143, -s6, v158, v143
	v_fma_f32 v181, -s7, v140, v181
	v_fma_f32 v180, -s8, v152, v180
	s_nop 0
	s_nop 0
	s_nop 0
	s_nop 0
	s_nop 0
	s_nop 0
	s_nop 0
	s_nop 0
	s_nop 0
	s_nop 0
	s_nop 0
	s_nop 0
	s_nop 0
	s_nop 0
	s_mov_b32 s20, 27
	s_nop 0
	s_nop 1
	s_nop 0
	s_nop 0
	s_nop 1
	s_nop 0
	s_nop 0
	s_nop 1
	s_nop 0
	v_pk_add_f32 v[142:143], v[180:181], v[142:143]
	v_mov_b32_e32 v181, v123
	v_mov_b32_e32 v180, v123
	v_pk_add_f32 v[142:143], v[142:143], v[142:143] op_sel:[0,1] op_sel_hi:[1,0]
	s_nop 0
	s_waitcnt lgkmcnt(0)
	v_sub_f32_e32 v167, v167, v246
	ds_read_b32 v247, v249 offset:104
	s_nop 0
	v_readlane_b32 s6, v205, s57
	v_readlane_b32 s7, v208, s57
	v_readlane_b32 s8, v207, s57
	v_readlane_b32 s9, v209, s57
	v_fma_f32 v167, -s6, v142, v167
	v_fma_f32 v181, -s7, v158, v181
	v_fma_f32 v180, -s8, v140, v180
	v_fma_f32 v166, -s9, v152, v166
	v_mov_b32_e32 v143, v158
	s_nop 0
	s_nop 0
	s_nop 0
	s_nop 0
	s_nop 0
	s_nop 0
	s_nop 0
	s_nop 0
	s_nop 0
	s_nop 0
	s_nop 0
	s_nop 0
	s_nop 0
	s_nop 0
	s_nop 0
	s_nop 0
	v_pk_add_f32 v[166:167], v[180:181], v[166:167]
	v_mov_b32_e32 v181, v123
	v_mov_b32_e32 v180, v123
	v_pk_add_f32 v[166:167], v[166:167], v[166:167] op_sel:[0,1] op_sel_hi:[1,0]
	s_nop 0
	s_waitcnt lgkmcnt(0)
	v_sub_f32_e32 v145, v145, v247
	ds_read_b32 v246, v249 offset:100
	s_nop 0
	v_readlane_b32 s6, v209, s53
	v_readlane_b32 s7, v205, s58
	v_readlane_b32 s8, v208, s58
	v_readlane_b32 s9, v207, s58
	v_fma_f32 v145, -s6, v166, v145
	v_fma_f32 v181, -s7, v142, v181
	v_fma_f32 v180, -s8, v158, v180
	v_fma_f32 v144, -s9, v140, v144
	s_nop 0
	s_nop 0
	v_readlane_b32 s6, v209, s58
	s_nop 1
	v_fma_f32 v145, -s6, v152, v145
	s_nop 0
	s_nop 0
	s_nop 0
	s_nop 0
	s_nop 0
	s_nop 0
	s_nop 0
	s_nop 0
	s_nop 0
	s_nop 0
	s_nop 0
	s_nop 0
	s_nop 0
	s_nop 0
	s_nop 0
	s_nop 0
	s_nop 1
	s_nop 0
	v_pk_add_f32 v[144:145], v[180:181], v[144:145]
	v_mov_b32_e32 v181, v123
	v_mov_b32_e32 v180, v123
	v_pk_add_f32 v[144:145], v[144:145], v[144:145] op_sel:[0,1] op_sel_hi:[1,0]
	s_nop 0
	s_waitcnt lgkmcnt(0)
	v_sub_f32_e32 v171, v171, v246
	ds_read_b32 v247, v249 offset:96
	s_nop 0
	v_readlane_b32 s6, v207, s52
	v_readlane_b32 s7, v209, s52
	v_readlane_b32 s8, v205, s59
	v_readlane_b32 s9, v208, s59
	v_fma_f32 v171, -s6, v144, v171
	v_fma_f32 v181, -s7, v166, v181
	v_fma_f32 v180, -s8, v142, v180
	v_fma_f32 v170, -s9, v158, v170
	v_mov_b32_e32 v145, v166
	s_nop 0
	v_readlane_b32 s6, v207, s59
	v_readlane_b32 s7, v209, s59
	s_nop 0
	v_fma_f32 v171, -s6, v140, v171
	v_fma_f32 v181, -s7, v152, v181
	s_nop 0
	s_nop 0
	s_nop 0
	s_nop 0
	s_nop 0
	s_nop 0
	s_nop 0
	s_nop 0
	s_nop 0
	s_nop 0
	s_nop 0
	s_nop 0
	s_nop 0
	s_nop 0
	s_nop 0
	s_nop 0
	s_nop 1
	s_nop 0
	s_nop 0
	s_nop 1
	s_nop 0
	v_pk_add_f32 v[170:171], v[180:181], v[170:171]
	v_mov_b32_e32 v181, v123
	v_mov_b32_e32 v180, v123
	v_pk_add_f32 v[170:171], v[170:171], v[170:171] op_sel:[0,1] op_sel_hi:[1,0]
	s_nop 0
	s_waitcnt lgkmcnt(0)
	v_sub_f32_e32 v147, v147, v247
	ds_read_b32 v246, v249 offset:92
	s_nop 0
	v_readlane_b32 s6, v208, s51
	v_readlane_b32 s7, v207, s51
	v_readlane_b32 s8, v209, s51
	v_readlane_b32 s9, v205, s60
	v_fma_f32 v147, -s6, v170, v147
	v_fma_f32 v181, -s7, v144, v181
	v_fma_f32 v180, -s8, v166, v180
	v_fma_f32 v146, -s9, v142, v146
	s_nop 0
	s_nop 0
	v_readlane_b32 s6, v208, s60
	v_readlane_b32 s7, v207, s60
	v_readlane_b32 s8, v209, s60
	v_fma_f32 v147, -s6, v158, v147
	v_fma_f32 v181, -s7, v140, v181
	v_fma_f32 v180, -s8, v152, v180
	s_nop 0
	s_nop 0
	s_nop 0
	s_nop 0
	s_nop 0
	s_nop 0
	s_nop 0
	s_nop 0
	s_nop 0
	s_nop 0
	s_nop 0
	s_nop 0
	s_nop 0
	s_nop 0
	s_nop 0
	s_nop 0
	s_nop 1
	s_nop 0
	s_nop 0
	s_nop 1
	s_nop 0
	s_nop 0
	s_nop 1
	s_nop 0
	v_pk_add_f32 v[146:147], v[180:181], v[146:147]
	v_mov_b32_e32 v181, v123
	v_mov_b32_e32 v180, v123
	v_pk_add_f32 v[146:147], v[146:147], v[146:147] op_sel:[0,1] op_sel_hi:[1,0]
	s_nop 0
	s_waitcnt lgkmcnt(0)
	v_sub_f32_e32 v175, v175, v246
	ds_read_b32 v247, v249 offset:88
	s_nop 0
	v_readlane_b32 s6, v205, s70
	v_readlane_b32 s7, v208, s70
	v_readlane_b32 s8, v207, s70
	v_readlane_b32 s9, v209, s70
	v_fma_f32 v175, -s6, v146, v175
	v_fma_f32 v181, -s7, v170, v181
	v_fma_f32 v180, -s8, v144, v180
	v_fma_f32 v174, -s9, v166, v174
	v_mov_b32_e32 v147, v170
	s_nop 0
	v_readlane_b32 s6, v205, s61
	v_readlane_b32 s7, v208, s61
	v_readlane_b32 s8, v207, s61
	v_readlane_b32 s9, v209, s61
	v_fma_f32 v175, -s6, v142, v175
	v_fma_f32 v181, -s7, v158, v181
	v_fma_f32 v180, -s8, v140, v180
	v_fma_f32 v174, -s9, v152, v174
	s_nop 0
	s_nop 0
	s_nop 0
	s_nop 0
	s_nop 0
	s_nop 0
	s_nop 0
	s_nop 0
	s_nop 0
	s_nop 0
	s_nop 0
	s_nop 0
	s_nop 0
	s_nop 0
	s_nop 0
	s_nop 0
	s_nop 0
	v_pk_add_f32 v[174:175], v[180:181], v[174:175]
	v_mov_b32_e32 v181, v123
	v_mov_b32_e32 v180, v123
	v_pk_add_f32 v[174:175], v[174:175], v[174:175] op_sel:[0,1] op_sel_hi:[1,0]
	s_nop 0
	s_waitcnt lgkmcnt(0)
	v_sub_f32_e32 v149, v149, v247
	ds_read_b32 v246, v249 offset:84
	s_nop 0
	v_readlane_b32 s6, v206, s62
	v_readlane_b32 s7, v205, s71
	v_readlane_b32 s8, v208, s71
	v_readlane_b32 s9, v207, s71
	v_fma_f32 v149, -s6, v174, v149
	v_fma_f32 v181, -s7, v146, v181
	v_fma_f32 v180, -s8, v170, v180
	v_fma_f32 v148, -s9, v144, v148
	s_nop 0
	s_nop 0
	v_readlane_b32 s6, v209, s71
	v_readlane_b32 s7, v205, s62
	v_readlane_b32 s8, v208, s62
	v_readlane_b32 s9, v207, s62
	v_fma_f32 v149, -s6, v166, v149
	v_fma_f32 v181, -s7, v142, v181
	v_fma_f32 v180, -s8, v158, v180
	v_fma_f32 v148, -s9, v140, v148
	s_nop 0
	s_nop 0
	v_readlane_b32 s6, v209, s62
	s_nop 1
	v_fma_f32 v149, -s6, v152, v149
	s_nop 0
	s_nop 0
	s_nop 0
	s_nop 0
	s_nop 0
	s_nop 0
	s_nop 0
	s_nop 0
	s_nop 0
	s_nop 0
	s_nop 0
	s_nop 0
	s_nop 0
	s_nop 0
	s_nop 0
	s_nop 0
	s_nop 1
	s_nop 0
	v_pk_add_f32 v[148:149], v[180:181], v[148:149]
	v_mov_b32_e32 v181, v123
	v_mov_b32_e32 v180, v123
	v_pk_add_f32 v[148:149], v[148:149], v[148:149] op_sel:[0,1] op_sel_hi:[1,0]
	s_nop 0
	s_waitcnt lgkmcnt(0)
	v_sub_f32_e32 v179, v179, v246
	ds_read_b32 v247, v249 offset:80
	s_nop 0
	v_readlane_b32 s6, v203, s63
	v_readlane_b32 s7, v206, s63
	v_readlane_b32 s8, v205, s72
	v_readlane_b32 s9, v208, s72
	v_fma_f32 v179, -s6, v148, v179
	v_fma_f32 v181, -s7, v174, v181
	v_fma_f32 v180, -s8, v146, v180
	v_fma_f32 v178, -s9, v170, v178
	v_mov_b32_e32 v149, v174
	s_nop 0
	v_readlane_b32 s6, v207, s72
	v_readlane_b32 s7, v209, s72
	v_readlane_b32 s8, v205, s63
	v_readlane_b32 s9, v208, s63
	v_fma_f32 v179, -s6, v144, v179
	v_fma_f32 v181, -s7, v166, v181
	v_fma_f32 v180, -s8, v142, v180
	v_fma_f32 v178, -s9, v158, v178
	s_nop 0
	s_nop 0
	v_readlane_b32 s6, v207, s63
	v_readlane_b32 s7, v209, s63
	s_nop 0
	v_fma_f32 v179, -s6, v140, v179
	v_fma_f32 v181, -s7, v152, v181
	s_nop 0
	s_nop 0
	s_nop 0
	s_nop 0
	s_nop 0
	s_nop 0
	s_nop 0
	s_nop 0
	s_nop 0
	s_nop 0
	s_nop 0
	s_nop 0
	s_nop 0
	s_nop 0
	s_nop 0
	s_nop 0
	s_nop 1
	s_nop 0
	s_nop 0
	s_nop 1
	s_nop 0
	v_pk_add_f32 v[178:179], v[180:181], v[178:179]
	v_mov_b32_e32 v181, v123
	v_mov_b32_e32 v180, v123
	v_pk_add_f32 v[178:179], v[178:179], v[178:179] op_sel:[0,1] op_sel_hi:[1,0]
	s_nop 0
	s_waitcnt lgkmcnt(0)
	v_sub_f32_e32 v151, v151, v247
	ds_read_b32 v246, v249 offset:76
	s_nop 0
	v_readlane_b32 s6, v204, s22
	v_readlane_b32 s7, v203, s22
	v_readlane_b32 s8, v206, s22
	v_readlane_b32 s9, v205, s73
	v_fma_f32 v151, -s6, v178, v151
	v_fma_f32 v181, -s7, v148, v181
	v_fma_f32 v180, -s8, v174, v180
	v_fma_f32 v150, -s9, v146, v150
	s_nop 0
	s_nop 0
	v_readlane_b32 s6, v208, s73
	v_readlane_b32 s7, v207, s73
	v_readlane_b32 s8, v209, s73
	v_readlane_b32 s9, v205, s22
	v_fma_f32 v151, -s6, v170, v151
	v_fma_f32 v181, -s7, v144, v181
	v_fma_f32 v180, -s8, v166, v180
	v_fma_f32 v150, -s9, v142, v150
	s_nop 0
	s_nop 0
	v_readlane_b32 s6, v208, s22
	v_readlane_b32 s7, v207, s22
	v_readlane_b32 s8, v209, s22
	v_fma_f32 v151, -s6, v158, v151
	v_fma_f32 v181, -s7, v140, v181
	v_fma_f32 v180, -s8, v152, v180
	s_nop 0
	s_nop 0
	s_nop 0
	s_nop 0
	s_nop 0
	s_nop 0
	s_nop 0
	s_nop 0
	s_nop 0
	s_nop 0
	s_nop 0
	s_nop 0
	s_nop 0
	s_nop 0
	s_nop 0
	s_nop 0
	s_nop 1
	s_nop 0
	s_nop 0
	s_nop 1
	s_nop 0
	s_nop 0
	s_nop 1
	s_nop 0
	v_pk_add_f32 v[150:151], v[180:181], v[150:151]
	v_mov_b32_e32 v181, v123
	v_mov_b32_e32 v180, v123
	v_pk_add_f32 v[150:151], v[150:151], v[150:151] op_sel:[0,1] op_sel_hi:[1,0]
	s_nop 0
	s_waitcnt lgkmcnt(0)
	v_sub_f32_e32 v177, v177, v246
	ds_read_b32 v247, v249 offset:72
	s_nop 0
	v_readlane_b32 s6, v201, s64
	v_readlane_b32 s7, v204, s64
	v_readlane_b32 s8, v203, s64
	v_readlane_b32 s9, v206, s64
	v_fma_f32 v177, -s6, v150, v177
	v_fma_f32 v181, -s7, v178, v181
	v_fma_f32 v180, -s8, v148, v180
	v_fma_f32 v176, -s9, v174, v176
	v_mov_b32_e32 v151, v178
	s_nop 0
	v_readlane_b32 s6, v205, s50
	v_readlane_b32 s7, v208, s50
	v_readlane_b32 s8, v207, s50
	v_readlane_b32 s9, v209, s50
	v_fma_f32 v177, -s6, v146, v177
	v_fma_f32 v181, -s7, v170, v181
	v_fma_f32 v180, -s8, v144, v180
	v_fma_f32 v176, -s9, v166, v176
	s_nop 0
	s_nop 0
	v_readlane_b32 s6, v205, s64
	v_readlane_b32 s7, v208, s64
	v_readlane_b32 s8, v207, s64
	v_readlane_b32 s9, v209, s64
	v_fma_f32 v177, -s6, v142, v177
	v_fma_f32 v181, -s7, v158, v181
	v_fma_f32 v180, -s8, v140, v180
	v_fma_f32 v176, -s9, v152, v176
	s_nop 0
	s_nop 0
	s_nop 0
	s_nop 0
	s_nop 0
	s_nop 0
	s_nop 0
	s_nop 0
	s_nop 0
	s_nop 0
	s_nop 0
	s_nop 0
	s_nop 0
	s_nop 0
	s_nop 0
	s_nop 0
	s_nop 0
	v_pk_add_f32 v[176:177], v[180:181], v[176:177]
	v_mov_b32_e32 v181, v123
	v_mov_b32_e32 v180, v123
	v_pk_add_f32 v[176:177], v[176:177], v[176:177] op_sel:[0,1] op_sel_hi:[1,0]
	s_nop 0
	s_waitcnt lgkmcnt(0)
	v_sub_f32_e32 v157, v157, v247
	ds_read_b32 v246, v249 offset:68
	s_nop 0
	v_readlane_b32 s6, v206, s49
	v_readlane_b32 s7, v201, s65
	v_readlane_b32 s8, v204, s65
	v_readlane_b32 s9, v203, s65
	v_fma_f32 v157, -s6, v176, v157
	v_fma_f32 v181, -s7, v150, v181
	v_fma_f32 v180, -s8, v178, v180
	v_fma_f32 v156, -s9, v148, v156
	s_nop 0
	s_nop 0
	v_readlane_b32 s6, v206, s65
	v_readlane_b32 s7, v205, s49
	v_readlane_b32 s8, v208, s49
	v_readlane_b32 s9, v207, s49
	v_fma_f32 v157, -s6, v174, v157
	v_fma_f32 v181, -s7, v146, v181
	v_fma_f32 v180, -s8, v170, v180
	v_fma_f32 v156, -s9, v144, v156
	s_nop 0
	s_nop 0
	v_readlane_b32 s6, v209, s49
	v_readlane_b32 s7, v205, s65
	v_readlane_b32 s8, v208, s65
	v_readlane_b32 s9, v207, s65
	v_fma_f32 v157, -s6, v166, v157
	v_fma_f32 v181, -s7, v142, v181
	v_fma_f32 v180, -s8, v158, v180
	v_fma_f32 v156, -s9, v140, v156
	s_nop 0
	s_nop 0
	v_readlane_b32 s6, v209, s65
	s_nop 1
	v_fma_f32 v157, -s6, v152, v157
	s_nop 0
	s_nop 0
	s_nop 0
	s_nop 0
	s_nop 0
	s_nop 0
	s_nop 0
	s_nop 0
	s_nop 0
	s_nop 0
	s_nop 0
	s_nop 0
	s_nop 0
	s_nop 0
	s_nop 0
	s_nop 0
	s_nop 1
	s_nop 0
	v_pk_add_f32 v[156:157], v[180:181], v[156:157]
	v_mov_b32_e32 v181, v123
	v_mov_b32_e32 v180, v123
	v_pk_add_f32 v[156:157], v[156:157], v[156:157] op_sel:[0,1] op_sel_hi:[1,0]
	s_nop 0
	s_waitcnt lgkmcnt(0)
	v_sub_f32_e32 v173, v173, v246
	ds_read_b32 v247, v249 offset:64
	s_nop 0
	v_readlane_b32 s6, v203, s48
	v_readlane_b32 s7, v206, s48
	v_readlane_b32 s8, v201, s21
	v_readlane_b32 s9, v204, s21
	v_fma_f32 v173, -s6, v156, v173
	v_fma_f32 v181, -s7, v176, v181
	v_fma_f32 v180, -s8, v150, v180
	v_fma_f32 v172, -s9, v178, v172
	v_mov_b32_e32 v157, v176
	s_nop 0
	v_readlane_b32 s6, v203, s21
	v_readlane_b32 s7, v206, s21
	v_readlane_b32 s8, v205, s48
	v_readlane_b32 s9, v208, s48
	v_fma_f32 v173, -s6, v148, v173
	v_fma_f32 v181, -s7, v174, v181
	v_fma_f32 v180, -s8, v146, v180
	v_fma_f32 v172, -s9, v170, v172
	s_nop 0
	s_nop 0
	v_readlane_b32 s6, v207, s48
	v_readlane_b32 s7, v209, s48
	v_readlane_b32 s8, v205, s21
	v_readlane_b32 s9, v208, s21
	v_fma_f32 v173, -s6, v144, v173
	v_fma_f32 v181, -s7, v166, v181
	v_fma_f32 v180, -s8, v142, v180
	v_fma_f32 v172, -s9, v158, v172
	s_nop 0
	s_nop 0
	v_readlane_b32 s6, v207, s21
	v_readlane_b32 s7, v209, s21
	s_nop 0
	v_fma_f32 v173, -s6, v140, v173
	v_fma_f32 v181, -s7, v152, v181
	s_nop 0
	s_nop 0
	s_nop 0
	s_nop 0
	s_nop 0
	s_nop 0
	s_nop 0
	s_nop 0
	s_nop 0
	s_nop 0
	s_nop 0
	s_nop 0
	s_nop 0
	s_nop 0
	s_nop 0
	s_nop 0
	s_nop 1
	s_nop 0
	s_nop 0
	s_nop 1
	s_nop 0
	v_pk_add_f32 v[172:173], v[180:181], v[172:173]
	v_mov_b32_e32 v181, v123
	v_mov_b32_e32 v180, v123
	v_pk_add_f32 v[172:173], v[172:173], v[172:173] op_sel:[0,1] op_sel_hi:[1,0]
	s_nop 0
	s_waitcnt lgkmcnt(0)
	v_sub_f32_e32 v165, v165, v247
	ds_read_b32 v246, v249 offset:60
	s_nop 0
	v_readlane_b32 s6, v204, s47
	v_readlane_b32 s7, v203, s47
	v_readlane_b32 s8, v206, s47
	v_readlane_b32 s9, v201, s34
	v_fma_f32 v165, -s6, v172, v165
	v_fma_f32 v181, -s7, v156, v181
	v_fma_f32 v180, -s8, v176, v180
	v_fma_f32 v164, -s9, v150, v164
	s_nop 0
	s_nop 0
	v_readlane_b32 s6, v204, s34
	v_readlane_b32 s7, v203, s34
	v_readlane_b32 s8, v206, s34
	v_readlane_b32 s9, v205, s47
	v_fma_f32 v165, -s6, v178, v165
	v_fma_f32 v181, -s7, v148, v181
	v_fma_f32 v180, -s8, v174, v180
	v_fma_f32 v164, -s9, v146, v164
	s_nop 0
	s_nop 0
	v_readlane_b32 s6, v208, s47
	v_readlane_b32 s7, v207, s47
	v_readlane_b32 s8, v209, s47
	v_readlane_b32 s9, v205, s34
	v_fma_f32 v165, -s6, v170, v165
	v_fma_f32 v181, -s7, v144, v181
	v_fma_f32 v180, -s8, v166, v180
	v_fma_f32 v164, -s9, v142, v164
	s_nop 0
	s_nop 0
	v_readlane_b32 s6, v208, s34
	v_readlane_b32 s7, v207, s34
	v_readlane_b32 s8, v209, s34
	v_fma_f32 v165, -s6, v158, v165
	v_fma_f32 v181, -s7, v140, v181
	v_fma_f32 v180, -s8, v152, v180
	s_nop 0
	s_nop 0
	s_nop 0
	s_nop 0
	s_nop 0
	s_nop 0
	s_nop 0
	s_nop 0
	s_nop 0
	s_nop 0
	s_nop 0
	s_nop 0
	s_nop 0
	s_nop 0
	s_nop 0
	s_nop 0
	s_nop 1
	s_nop 0
	s_nop 0
	s_nop 1
	s_nop 0
	s_nop 0
	s_nop 1
	s_nop 0
	v_pk_add_f32 v[164:165], v[180:181], v[164:165]
	v_mov_b32_e32 v181, v123
	v_mov_b32_e32 v180, v123
	v_pk_add_f32 v[164:165], v[164:165], v[164:165] op_sel:[0,1] op_sel_hi:[1,0]
	s_nop 0
	s_waitcnt lgkmcnt(0)
	v_sub_f32_e32 v169, v169, v246
	ds_read_b32 v247, v249 offset:56
	s_nop 0
	v_readlane_b32 s6, v201, s45
	v_readlane_b32 s7, v204, s45
	v_readlane_b32 s8, v203, s45
	v_readlane_b32 s9, v206, s45
	v_fma_f32 v169, -s6, v164, v169
	v_fma_f32 v181, -s7, v172, v181
	v_fma_f32 v180, -s8, v156, v180
	v_fma_f32 v168, -s9, v176, v168
	v_mov_b32_e32 v165, v172
	s_nop 0
	v_readlane_b32 s6, v201, s66
	v_readlane_b32 s7, v204, s66
	v_readlane_b32 s8, v203, s66
	v_readlane_b32 s9, v206, s66
	v_fma_f32 v169, -s6, v150, v169
	v_fma_f32 v181, -s7, v178, v181
	v_fma_f32 v180, -s8, v148, v180
	v_fma_f32 v168, -s9, v174, v168
	s_nop 0
	s_nop 0
	v_readlane_b32 s6, v205, s45
	v_readlane_b32 s7, v208, s45
	v_readlane_b32 s8, v207, s45
	v_readlane_b32 s9, v209, s45
	v_fma_f32 v169, -s6, v146, v169
	v_fma_f32 v181, -s7, v170, v181
	v_fma_f32 v180, -s8, v144, v180
	v_fma_f32 v168, -s9, v166, v168
	s_nop 0
	s_nop 0
	v_readlane_b32 s6, v205, s66
	v_readlane_b32 s7, v208, s66
	v_readlane_b32 s8, v207, s66
	v_readlane_b32 s9, v209, s66
	v_fma_f32 v169, -s6, v142, v169
	v_fma_f32 v181, -s7, v158, v181
	v_fma_f32 v180, -s8, v140, v180
	v_fma_f32 v168, -s9, v152, v168
	s_nop 0
	s_nop 0
	s_nop 0
	s_nop 0
	s_nop 0
	s_nop 0
	s_nop 0
	s_nop 0
	s_nop 0
	s_nop 0
	s_nop 0
	s_nop 0
	s_nop 0
	s_nop 0
	s_nop 0
	s_nop 0
	s_nop 0
	v_pk_add_f32 v[168:169], v[180:181], v[168:169]
	s_nop 0
	v_pk_add_f32 v[180:181], v[168:169], v[168:169] op_sel:[0,1] op_sel_hi:[1,0]
	v_mov_b32_e32 v169, v123
	v_mov_b32_e32 v168, v123
	s_waitcnt lgkmcnt(0)
	v_sub_f32_e32 v163, v163, v247
	ds_read_b32 v246, v249 offset:52
	s_nop 0
	v_readlane_b32 s6, v202, s14
	v_readlane_b32 s7, v201, s39
	v_readlane_b32 s8, v204, s39
	v_readlane_b32 s9, v203, s39
	v_fma_f32 v163, -s6, v180, v163
	v_fma_f32 v169, -s7, v164, v169
	v_fma_f32 v168, -s8, v172, v168
	v_fma_f32 v162, -s9, v156, v162
	s_nop 0
	s_nop 0
	v_readlane_b32 s6, v206, s39
	v_readlane_b32 s7, v201, s14
	v_readlane_b32 s8, v204, s14
	v_readlane_b32 s9, v203, s14
	v_fma_f32 v163, -s6, v176, v163
	v_fma_f32 v169, -s7, v150, v169
	v_fma_f32 v168, -s8, v178, v168
	v_fma_f32 v162, -s9, v148, v162
	s_nop 0
	s_nop 0
	v_readlane_b32 s6, v206, s14
	v_readlane_b32 s7, v205, s39
	v_readlane_b32 s8, v208, s39
	v_readlane_b32 s9, v207, s39
	v_fma_f32 v163, -s6, v174, v163
	v_fma_f32 v169, -s7, v146, v169
	v_fma_f32 v168, -s8, v170, v168
	v_fma_f32 v162, -s9, v144, v162
	s_nop 0
	s_nop 0
	v_readlane_b32 s6, v209, s39
	v_readlane_b32 s7, v205, s14
	v_readlane_b32 s8, v208, s14
	v_readlane_b32 s9, v207, s14
	v_fma_f32 v163, -s6, v166, v163
	v_fma_f32 v169, -s7, v142, v169
	v_fma_f32 v168, -s8, v158, v168
	v_fma_f32 v162, -s9, v140, v162
	s_nop 0
	s_nop 0
	v_readlane_b32 s6, v209, s14
	s_nop 1
	v_fma_f32 v163, -s6, v152, v163
	s_nop 0
	s_nop 0
	s_nop 0
	s_nop 0
	s_nop 0
	s_nop 0
	s_nop 0
	s_nop 0
	s_nop 0
	s_nop 0
	s_nop 0
	s_nop 0
	s_nop 0
	s_nop 0
	s_nop 0
	s_nop 0
	s_nop 1
	s_nop 0
	v_pk_add_f32 v[162:163], v[168:169], v[162:163]
	v_mov_b32_e32 v169, v123
	v_mov_b32_e32 v168, v123
	v_pk_add_f32 v[162:163], v[162:163], v[162:163] op_sel:[0,1] op_sel_hi:[1,0]
	s_nop 0
	s_waitcnt lgkmcnt(0)
	v_sub_f32_e32 v161, v161, v246
	ds_read_b32 v247, v249 offset:48
	s_nop 0
	v_readlane_b32 s6, v199, s11
	v_readlane_b32 s7, v202, s11
	v_readlane_b32 s8, v201, s38
	v_readlane_b32 s9, v204, s38
	v_fma_f32 v161, -s6, v162, v161
	v_fma_f32 v169, -s7, v180, v169
	v_fma_f32 v168, -s8, v164, v168
	v_fma_f32 v160, -s9, v172, v160
	v_mov_b32_e32 v163, v180
	s_nop 0
	v_readlane_b32 s6, v203, s38
	v_readlane_b32 s7, v206, s38
	v_readlane_b32 s8, v201, s11
	v_readlane_b32 s9, v204, s11
	v_fma_f32 v161, -s6, v156, v161
	v_fma_f32 v169, -s7, v176, v169
	v_fma_f32 v168, -s8, v150, v168
	v_fma_f32 v160, -s9, v178, v160
	s_nop 0
	s_nop 0
	v_readlane_b32 s6, v203, s11
	v_readlane_b32 s7, v206, s11
	v_readlane_b32 s8, v205, s38
	v_readlane_b32 s9, v208, s38
	v_fma_f32 v161, -s6, v148, v161
	v_fma_f32 v169, -s7, v174, v169
	v_fma_f32 v168, -s8, v146, v168
	v_fma_f32 v160, -s9, v170, v160
	s_nop 0
	s_nop 0
	v_readlane_b32 s6, v207, s38
	v_readlane_b32 s7, v209, s38
	v_readlane_b32 s8, v205, s11
	v_readlane_b32 s9, v208, s11
	v_fma_f32 v161, -s6, v144, v161
	v_fma_f32 v169, -s7, v166, v169
	v_fma_f32 v168, -s8, v142, v168
	v_fma_f32 v160, -s9, v158, v160
	s_nop 0
	s_nop 0
	v_readlane_b32 s6, v207, s11
	v_readlane_b32 s7, v209, s11
	s_nop 0
	v_fma_f32 v161, -s6, v140, v161
	v_fma_f32 v169, -s7, v152, v169
	s_nop 0
	s_nop 0
	s_nop 0
	s_nop 0
	s_nop 0
	s_nop 0
	s_nop 0
	s_nop 0
	s_nop 0
	s_nop 0
	s_nop 0
	s_nop 0
	s_nop 0
	s_nop 0
	s_nop 0
	s_nop 0
	s_nop 1
	s_nop 0
	s_nop 0
	s_nop 1
	s_nop 0
	v_pk_add_f32 v[160:161], v[168:169], v[160:161]
	s_nop 0
	v_pk_add_f32 v[184:185], v[160:161], v[160:161] op_sel:[0,1] op_sel_hi:[1,0]
	v_mov_b32_e32 v161, v123
	v_mov_b32_e32 v160, v123
	s_waitcnt lgkmcnt(0)
	v_sub_f32_e32 v155, v155, v247
	ds_read_b32 v246, v249 offset:44
	s_nop 0
	v_readlane_b32 s6, v200, s27
	v_readlane_b32 s7, v199, s27
	v_readlane_b32 s8, v202, s27
	v_readlane_b32 s9, v201, s43
	v_fma_f32 v155, -s6, v184, v155
	v_fma_f32 v161, -s7, v162, v161
	v_fma_f32 v160, -s8, v180, v160
	v_fma_f32 v154, -s9, v164, v154
	s_nop 0
	s_nop 0
	v_readlane_b32 s6, v204, s43
	v_readlane_b32 s7, v203, s43
	v_readlane_b32 s8, v206, s43
	v_readlane_b32 s9, v201, s27
	v_fma_f32 v155, -s6, v172, v155
	v_fma_f32 v161, -s7, v156, v161
	v_fma_f32 v160, -s8, v176, v160
	v_fma_f32 v154, -s9, v150, v154
	s_nop 0
	s_nop 0
	v_readlane_b32 s6, v204, s27
	v_readlane_b32 s7, v203, s27
	v_readlane_b32 s8, v206, s27
	v_readlane_b32 s9, v205, s43
	v_fma_f32 v155, -s6, v178, v155
	v_fma_f32 v161, -s7, v148, v161
	v_fma_f32 v160, -s8, v174, v160
	v_fma_f32 v154, -s9, v146, v154
	s_nop 0
	s_nop 0
	v_readlane_b32 s6, v208, s43
	v_readlane_b32 s7, v207, s43
	v_readlane_b32 s8, v209, s43
	v_readlane_b32 s9, v205, s27
	v_fma_f32 v155, -s6, v170, v155
	v_fma_f32 v161, -s7, v144, v161
	v_fma_f32 v160, -s8, v166, v160
	v_fma_f32 v154, -s9, v142, v154
	s_nop 0
	s_nop 0
	v_readlane_b32 s6, v208, s27
	v_readlane_b32 s7, v207, s27
	v_readlane_b32 s8, v209, s27
	v_fma_f32 v155, -s6, v158, v155
	v_fma_f32 v161, -s7, v140, v161
	v_fma_f32 v160, -s8, v152, v160
	s_nop 0
	s_nop 0
	s_nop 0
	s_nop 0
	s_nop 0
	s_nop 0
	s_nop 0
	s_nop 0
	s_nop 0
	s_nop 0
	s_nop 0
	s_nop 0
	s_nop 0
	s_nop 0
	s_nop 0
	s_nop 0
	s_nop 1
	s_nop 0
	s_nop 0
	s_nop 1
	s_nop 0
	s_nop 0
	s_nop 1
	s_nop 0
	v_pk_add_f32 v[154:155], v[160:161], v[154:155]
	v_mov_b32_e32 v161, v123
	v_mov_b32_e32 v160, v123
	v_pk_add_f32 v[154:155], v[154:155], v[154:155] op_sel:[0,1] op_sel_hi:[1,0]
	s_nop 0
	s_waitcnt lgkmcnt(0)
	v_sub_f32_e32 v85, v85, v246
	ds_read_b32 v247, v249 offset:40
	s_nop 0
	v_readlane_b32 s6, v197, s67
	v_readlane_b32 s7, v200, s67
	v_readlane_b32 s8, v199, s67
	v_readlane_b32 s9, v202, s67
	v_fma_f32 v85, -s6, v154, v85
	v_fma_f32 v161, -s7, v184, v161
	v_fma_f32 v160, -s8, v162, v160
	v_fma_f32 v84, -s9, v180, v84
	v_mov_b32_e32 v155, v184
	s_nop 0
	v_readlane_b32 s6, v201, s42
	v_readlane_b32 s7, v204, s42
	v_readlane_b32 s8, v203, s42
	v_readlane_b32 s9, v206, s42
	v_fma_f32 v85, -s6, v164, v85
	v_fma_f32 v161, -s7, v172, v161
	v_fma_f32 v160, -s8, v156, v160
	v_fma_f32 v84, -s9, v176, v84
	s_nop 0
	s_nop 0
	v_readlane_b32 s6, v201, s67
	v_readlane_b32 s7, v204, s67
	v_readlane_b32 s8, v203, s67
	v_readlane_b32 s9, v206, s67
	v_fma_f32 v85, -s6, v150, v85
	v_fma_f32 v161, -s7, v178, v161
	v_fma_f32 v160, -s8, v148, v160
	v_fma_f32 v84, -s9, v174, v84
	s_nop 0
	s_nop 0
	v_readlane_b32 s6, v205, s42
	v_readlane_b32 s7, v208, s42
	v_readlane_b32 s8, v207, s42
	v_readlane_b32 s9, v209, s42
	v_fma_f32 v85, -s6, v146, v85
	v_fma_f32 v161, -s7, v170, v161
	v_fma_f32 v160, -s8, v144, v160
	v_fma_f32 v84, -s9, v166, v84
	s_nop 0
	s_nop 0
	v_readlane_b32 s6, v205, s67
	v_readlane_b32 s7, v208, s67
	v_readlane_b32 s8, v207, s67
	v_readlane_b32 s9, v209, s67
	v_fma_f32 v85, -s6, v142, v85
	v_fma_f32 v161, -s7, v158, v161
	v_fma_f32 v160, -s8, v140, v160
	v_fma_f32 v84, -s9, v152, v84
	s_nop 0
	s_nop 0
	s_nop 0
	s_nop 0
	s_nop 0
	s_nop 0
	s_nop 0
	s_nop 0
	s_nop 0
	s_nop 0
	s_nop 0
	s_nop 0
	s_nop 0
	s_nop 0
	s_nop 0
	s_nop 0
	s_nop 0
	v_pk_add_f32 v[84:85], v[160:161], v[84:85]
	v_mov_b32_e32 v161, v123
	v_mov_b32_e32 v160, v123
	v_pk_add_f32 v[84:85], v[84:85], v[84:85] op_sel:[0,1] op_sel_hi:[1,0]
	s_nop 0
	s_waitcnt lgkmcnt(0)
	v_sub_f32_e32 v83, v83, v247
	ds_read_b32 v246, v249 offset:36
	s_nop 0
	v_readlane_b32 s6, v202, s46
	v_readlane_b32 s7, v197, s2
	v_readlane_b32 s8, v200, s2
	v_readlane_b32 s9, v199, s2
	v_fma_f32 v83, -s6, v84, v83
	v_fma_f32 v161, -s7, v154, v161
	v_fma_f32 v160, -s8, v184, v160
	v_fma_f32 v82, -s9, v162, v82
	s_nop 0
	s_nop 0
	v_readlane_b32 s6, v202, s2
	v_readlane_b32 s7, v201, s46
	v_readlane_b32 s8, v204, s46
	v_readlane_b32 s9, v203, s46
	v_fma_f32 v83, -s6, v180, v83
	v_fma_f32 v161, -s7, v164, v161
	v_fma_f32 v160, -s8, v172, v160
	v_fma_f32 v82, -s9, v156, v82
	s_nop 0
	s_nop 0
	v_readlane_b32 s6, v206, s46
	v_readlane_b32 s7, v201, s2
	v_readlane_b32 s8, v204, s2
	v_readlane_b32 s9, v203, s2
	v_fma_f32 v83, -s6, v176, v83
	v_fma_f32 v161, -s7, v150, v161
	v_fma_f32 v160, -s8, v178, v160
	v_fma_f32 v82, -s9, v148, v82
	s_nop 0
	s_nop 0
	v_readlane_b32 s6, v206, s2
	v_readlane_b32 s7, v205, s46
	v_readlane_b32 s8, v208, s46
	v_readlane_b32 s9, v207, s46
	v_fma_f32 v83, -s6, v174, v83
	v_fma_f32 v161, -s7, v146, v161
	v_fma_f32 v160, -s8, v170, v160
	v_fma_f32 v82, -s9, v144, v82
	s_nop 0
	s_nop 0
	v_readlane_b32 s6, v209, s46
	v_readlane_b32 s7, v205, s2
	v_readlane_b32 s8, v208, s2
	v_readlane_b32 s9, v207, s2
	v_fma_f32 v83, -s6, v166, v83
	v_fma_f32 v161, -s7, v142, v161
	v_fma_f32 v160, -s8, v158, v160
	v_fma_f32 v82, -s9, v140, v82
	s_nop 0
	s_nop 0
	v_readlane_b32 s6, v209, s2
	s_nop 1
	v_fma_f32 v83, -s6, v152, v83
	s_nop 0
	s_nop 0
	s_nop 0
	s_nop 0
	s_nop 0
	s_nop 0
	s_nop 0
	s_nop 0
	s_nop 0
	s_nop 0
	s_nop 0
	s_nop 0
	s_nop 0
	s_nop 0
	s_nop 0
	s_nop 0
	s_nop 1
	s_nop 0
	v_pk_add_f32 v[82:83], v[160:161], v[82:83]
	s_nop 0
	v_pk_add_f32 v[160:161], v[82:83], v[82:83] op_sel:[0,1] op_sel_hi:[1,0]
	v_mov_b32_e32 v83, v123
	v_mov_b32_e32 v82, v123
	s_waitcnt lgkmcnt(0)
	v_sub_f32_e32 v79, v79, v246
	ds_read_b32 v247, v249 offset:32
	s_nop 0
	v_readlane_b32 s6, v199, s37
	v_readlane_b32 s7, v202, s37
	v_readlane_b32 s8, v197, s18
	v_readlane_b32 s9, v200, s18
	v_fma_f32 v79, -s6, v160, v79
	v_fma_f32 v83, -s7, v84, v83
	v_fma_f32 v82, -s8, v154, v82
	v_fma_f32 v78, -s9, v184, v78
	v_mov_b32_e32 v161, v84
	s_nop 0
	v_readlane_b32 s6, v199, s18
	v_readlane_b32 s7, v202, s18
	v_readlane_b32 s8, v201, s37
	v_readlane_b32 s9, v204, s37
	v_fma_f32 v79, -s6, v162, v79
	v_fma_f32 v83, -s7, v180, v83
	v_fma_f32 v82, -s8, v164, v82
	v_fma_f32 v78, -s9, v172, v78
	s_nop 0
	s_nop 0
	v_readlane_b32 s6, v203, s37
	v_readlane_b32 s7, v206, s37
	v_readlane_b32 s8, v201, s18
	v_readlane_b32 s9, v204, s18
	v_fma_f32 v79, -s6, v156, v79
	v_fma_f32 v83, -s7, v176, v83
	v_fma_f32 v82, -s8, v150, v82
	v_fma_f32 v78, -s9, v178, v78
	s_nop 0
	s_nop 0
	v_readlane_b32 s6, v203, s18
	v_readlane_b32 s7, v206, s18
	v_readlane_b32 s8, v205, s37
	v_readlane_b32 s9, v208, s37
	v_fma_f32 v79, -s6, v148, v79
	v_fma_f32 v83, -s7, v174, v83
	v_fma_f32 v82, -s8, v146, v82
	v_fma_f32 v78, -s9, v170, v78
	s_nop 0
	s_nop 0
	v_readlane_b32 s6, v207, s37
	v_readlane_b32 s7, v209, s37
	v_readlane_b32 s8, v205, s18
	v_readlane_b32 s9, v208, s18
	v_fma_f32 v79, -s6, v144, v79
	v_fma_f32 v83, -s7, v166, v83
	v_fma_f32 v82, -s8, v142, v82
	v_fma_f32 v78, -s9, v158, v78
	s_nop 0
	s_nop 0
	v_readlane_b32 s6, v207, s18
	v_readlane_b32 s7, v209, s18
	s_nop 0
	v_fma_f32 v79, -s6, v140, v79
	v_fma_f32 v83, -s7, v152, v83
	s_nop 0
	s_nop 0
	s_nop 0
	s_nop 0
	s_nop 0
	s_nop 0
	s_nop 0
	s_nop 0
	s_nop 0
	s_nop 0
	s_nop 0
	s_nop 0
	s_nop 0
	s_nop 0
	s_nop 0
	s_nop 0
	s_nop 1
	s_nop 0
	s_nop 0
	s_nop 1
	s_nop 0
	v_pk_add_f32 v[78:79], v[82:83], v[78:79]
	v_mov_b32_e32 v83, v123
	v_mov_b32_e32 v82, v123
	v_pk_add_f32 v[78:79], v[78:79], v[78:79] op_sel:[0,1] op_sel_hi:[1,0]
	s_nop 0
	s_waitcnt lgkmcnt(0)
	v_sub_f32_e32 v75, v75, v247
	ds_read_b32 v246, v249 offset:28
	s_nop 0
	v_readlane_b32 s6, v200, s40
	v_readlane_b32 s7, v199, s40
	v_readlane_b32 s8, v202, s40
	v_readlane_b32 s9, v197, s19
	v_fma_f32 v75, -s6, v78, v75
	v_fma_f32 v83, -s7, v160, v83
	v_fma_f32 v82, -s8, v84, v82
	v_fma_f32 v74, -s9, v154, v74
	s_nop 0
	s_nop 0
	v_readlane_b32 s6, v200, s19
	v_readlane_b32 s7, v199, s19
	v_readlane_b32 s8, v202, s19
	v_readlane_b32 s9, v201, s40
	v_fma_f32 v75, -s6, v184, v75
	v_fma_f32 v83, -s7, v162, v83
	v_fma_f32 v82, -s8, v180, v82
	v_fma_f32 v74, -s9, v164, v74
	s_nop 0
	s_nop 0
	v_readlane_b32 s6, v204, s40
	v_readlane_b32 s7, v203, s40
	v_readlane_b32 s8, v206, s40
	v_readlane_b32 s9, v201, s19
	v_fma_f32 v75, -s6, v172, v75
	v_fma_f32 v83, -s7, v156, v83
	v_fma_f32 v82, -s8, v176, v82
	v_fma_f32 v74, -s9, v150, v74
	s_nop 0
	s_nop 0
	v_readlane_b32 s6, v204, s19
	v_readlane_b32 s7, v203, s19
	v_readlane_b32 s8, v206, s19
	v_readlane_b32 s9, v205, s40
	v_fma_f32 v75, -s6, v178, v75
	v_fma_f32 v83, -s7, v148, v83
	v_fma_f32 v82, -s8, v174, v82
	v_fma_f32 v74, -s9, v146, v74
	s_nop 0
	s_nop 0
	v_readlane_b32 s6, v208, s40
	v_readlane_b32 s7, v207, s40
	v_readlane_b32 s8, v209, s40
	v_readlane_b32 s9, v205, s19
	v_fma_f32 v75, -s6, v170, v75
	v_fma_f32 v83, -s7, v144, v83
	v_fma_f32 v82, -s8, v166, v82
	v_fma_f32 v74, -s9, v142, v74
	s_nop 0
	s_nop 0
	v_readlane_b32 s6, v208, s19
	v_readlane_b32 s7, v207, s19
	v_readlane_b32 s8, v209, s19
	v_fma_f32 v75, -s6, v158, v75
	v_fma_f32 v83, -s7, v140, v83
	v_fma_f32 v82, -s8, v152, v82
	s_nop 0
	s_nop 0
	s_nop 0
	s_nop 0
	s_nop 0
	s_nop 0
	s_nop 0
	s_nop 0
	s_nop 0
	s_nop 0
	s_nop 0
	s_nop 0
	s_nop 0
	s_nop 0
	s_nop 0
	s_nop 0
	s_nop 1
	s_nop 0
	s_nop 0
	s_nop 1
	s_nop 0
	s_nop 0
	s_nop 1
	s_nop 0
	v_pk_add_f32 v[74:75], v[82:83], v[74:75]
	s_nop 0
	v_pk_add_f32 v[168:169], v[74:75], v[74:75] op_sel:[0,1] op_sel_hi:[1,0]
	v_mov_b32_e32 v75, v123
	v_mov_b32_e32 v74, v123
	s_waitcnt lgkmcnt(0)
	v_sub_f32_e32 v71, v71, v246
	ds_read_b32 v247, v249 offset:24
	s_nop 0
	v_readlane_b32 s6, v197, s44
	v_readlane_b32 s7, v200, s44
	v_readlane_b32 s8, v199, s44
	v_readlane_b32 s9, v202, s44
	v_fma_f32 v71, -s6, v168, v71
	v_fma_f32 v75, -s7, v78, v75
	v_fma_f32 v74, -s8, v160, v74
	v_fma_f32 v70, -s9, v84, v70
	v_mov_b32_e32 v169, v78
	s_nop 0
	v_readlane_b32 s6, v197, s68
	v_readlane_b32 s7, v200, s68
	v_readlane_b32 s8, v199, s68
	v_readlane_b32 s9, v202, s68
	v_fma_f32 v71, -s6, v154, v71
	v_fma_f32 v75, -s7, v184, v75
	v_fma_f32 v74, -s8, v162, v74
	v_fma_f32 v70, -s9, v180, v70
	s_nop 0
	s_nop 0
	v_readlane_b32 s6, v201, s44
	v_readlane_b32 s7, v204, s44
	v_readlane_b32 s8, v203, s44
	v_readlane_b32 s9, v206, s44
	v_fma_f32 v71, -s6, v164, v71
	v_fma_f32 v75, -s7, v172, v75
	v_fma_f32 v74, -s8, v156, v74
	v_fma_f32 v70, -s9, v176, v70
	s_nop 0
	s_nop 0
	v_readlane_b32 s6, v201, s68
	v_readlane_b32 s7, v204, s68
	v_readlane_b32 s8, v203, s68
	v_readlane_b32 s9, v206, s68
	v_fma_f32 v71, -s6, v150, v71
	v_fma_f32 v75, -s7, v178, v75
	v_fma_f32 v74, -s8, v148, v74
	v_fma_f32 v70, -s9, v174, v70
	s_nop 0
	s_nop 0
	v_readlane_b32 s6, v205, s44
	v_readlane_b32 s7, v208, s44
	v_readlane_b32 s8, v207, s44
	v_readlane_b32 s9, v209, s44
	v_fma_f32 v71, -s6, v146, v71
	v_fma_f32 v75, -s7, v170, v75
	v_fma_f32 v74, -s8, v144, v74
	v_fma_f32 v70, -s9, v166, v70
	s_nop 0
	s_nop 0
	v_readlane_b32 s6, v205, s68
	v_readlane_b32 s7, v208, s68
	v_readlane_b32 s8, v207, s68
	v_readlane_b32 s9, v209, s68
	v_fma_f32 v71, -s6, v142, v71
	v_fma_f32 v75, -s7, v158, v75
	v_fma_f32 v74, -s8, v140, v74
	v_fma_f32 v70, -s9, v152, v70
	s_nop 0
	s_nop 0
	s_nop 0
	s_nop 0
	s_nop 0
	s_nop 0
	s_nop 0
	s_nop 0
	s_nop 0
	s_nop 0
	s_nop 0
	s_nop 0
	s_nop 0
	s_nop 0
	s_nop 0
	s_nop 0
	s_nop 0
	v_pk_add_f32 v[70:71], v[74:75], v[70:71]
	v_mov_b32_e32 v75, v123
	v_mov_b32_e32 v74, v123
	v_pk_add_f32 v[70:71], v[70:71], v[70:71] op_sel:[0,1] op_sel_hi:[1,0]
	s_nop 0
	s_waitcnt lgkmcnt(0)
	v_sub_f32_e32 v67, v67, v247
	ds_read_b32 v246, v249 offset:20
	s_nop 0
	v_readlane_b32 s6, v198, s3
	v_readlane_b32 s7, v197, s35
	v_readlane_b32 s8, v200, s35
	v_readlane_b32 s9, v199, s35
	v_fma_f32 v67, -s6, v70, v67
	v_fma_f32 v75, -s7, v168, v75
	v_fma_f32 v74, -s8, v78, v74
	v_fma_f32 v66, -s9, v160, v66
	s_nop 0
	s_nop 0
	v_readlane_b32 s6, v202, s35
	v_readlane_b32 s7, v197, s3
	v_readlane_b32 s8, v200, s3
	v_readlane_b32 s9, v199, s3
	v_fma_f32 v67, -s6, v84, v67
	v_fma_f32 v75, -s7, v154, v75
	v_fma_f32 v74, -s8, v184, v74
	v_fma_f32 v66, -s9, v162, v66
	s_nop 0
	s_nop 0
	v_readlane_b32 s6, v202, s3
	v_readlane_b32 s7, v201, s35
	v_readlane_b32 s8, v204, s35
	v_readlane_b32 s9, v203, s35
	v_fma_f32 v67, -s6, v180, v67
	v_fma_f32 v75, -s7, v164, v75
	v_fma_f32 v74, -s8, v172, v74
	v_fma_f32 v66, -s9, v156, v66
	s_nop 0
	s_nop 0
	v_readlane_b32 s6, v206, s35
	v_readlane_b32 s7, v201, s3
	v_readlane_b32 s8, v204, s3
	v_readlane_b32 s9, v203, s3
	v_fma_f32 v67, -s6, v176, v67
	v_fma_f32 v75, -s7, v150, v75
	v_fma_f32 v74, -s8, v178, v74
	v_fma_f32 v66, -s9, v148, v66
	s_nop 0
	s_nop 0
	v_readlane_b32 s6, v206, s3
	v_readlane_b32 s7, v205, s35
	v_readlane_b32 s8, v208, s35
	v_readlane_b32 s9, v207, s35
	v_fma_f32 v67, -s6, v174, v67
	v_fma_f32 v75, -s7, v146, v75
	v_fma_f32 v74, -s8, v170, v74
	v_fma_f32 v66, -s9, v144, v66
	s_nop 0
	s_nop 0
	v_readlane_b32 s6, v209, s35
	v_readlane_b32 s7, v205, s3
	v_readlane_b32 s8, v208, s3
	v_readlane_b32 s9, v207, s3
	v_fma_f32 v67, -s6, v166, v67
	v_fma_f32 v75, -s7, v142, v75
	v_fma_f32 v74, -s8, v158, v74
	v_fma_f32 v66, -s9, v140, v66
	s_nop 0
	s_nop 0
	v_readlane_b32 s6, v209, s3
	s_nop 1
	v_fma_f32 v67, -s6, v152, v67
	s_nop 0
	s_nop 0
	s_nop 0
	s_nop 0
	s_nop 0
	s_nop 0
	s_nop 0
	s_nop 0
	s_nop 0
	s_nop 0
	s_nop 0
	s_nop 0
	s_nop 0
	s_nop 0
	s_nop 0
	s_nop 0
	s_nop 1
	s_nop 0
	v_pk_add_f32 v[66:67], v[74:75], v[66:67]
	s_nop 0
	v_pk_add_f32 v[182:183], v[66:67], v[66:67] op_sel:[0,1] op_sel_hi:[1,0]
	v_mov_b32_e32 v67, v123
	v_mov_b32_e32 v66, v123
	s_waitcnt lgkmcnt(0)
	v_sub_f32_e32 v63, v63, v246
	ds_read_b32 v247, v249 offset:16
	s_nop 0
	v_readlane_b32 s6, v195, s16
	v_readlane_b32 s7, v198, s16
	v_readlane_b32 s8, v197, s30
	v_readlane_b32 s9, v200, s30
	v_fma_f32 v63, -s6, v182, v63
	v_fma_f32 v67, -s7, v70, v67
	v_fma_f32 v66, -s8, v168, v66
	v_fma_f32 v62, -s9, v78, v62
	v_mov_b32_e32 v183, v70
	s_nop 0
	v_readlane_b32 s6, v199, s30
	v_readlane_b32 s7, v202, s30
	v_readlane_b32 s8, v197, s16
	v_readlane_b32 s9, v200, s16
	v_fma_f32 v63, -s6, v160, v63
	v_fma_f32 v67, -s7, v84, v67
	v_fma_f32 v66, -s8, v154, v66
	v_fma_f32 v62, -s9, v184, v62
	s_nop 0
	s_nop 0
	v_readlane_b32 s6, v199, s16
	v_readlane_b32 s7, v202, s16
	v_readlane_b32 s8, v201, s30
	v_readlane_b32 s9, v204, s30
	v_fma_f32 v63, -s6, v162, v63
	v_fma_f32 v67, -s7, v180, v67
	v_fma_f32 v66, -s8, v164, v66
	v_fma_f32 v62, -s9, v172, v62
	s_nop 0
	s_nop 0
	v_readlane_b32 s6, v203, s30
	v_readlane_b32 s7, v206, s30
	v_readlane_b32 s8, v201, s16
	v_readlane_b32 s9, v204, s16
	v_fma_f32 v63, -s6, v156, v63
	v_fma_f32 v67, -s7, v176, v67
	v_fma_f32 v66, -s8, v150, v66
	v_fma_f32 v62, -s9, v178, v62
	s_nop 0
	s_nop 0
	v_readlane_b32 s6, v203, s16
	v_readlane_b32 s7, v206, s16
	v_readlane_b32 s8, v205, s30
	v_readlane_b32 s9, v208, s30
	v_fma_f32 v63, -s6, v148, v63
	v_fma_f32 v67, -s7, v174, v67
	v_fma_f32 v66, -s8, v146, v66
	v_fma_f32 v62, -s9, v170, v62
	s_nop 0
	s_nop 0
	v_readlane_b32 s6, v207, s30
	v_readlane_b32 s7, v209, s30
	v_readlane_b32 s8, v205, s16
	v_readlane_b32 s9, v208, s16
	v_fma_f32 v63, -s6, v144, v63
	v_fma_f32 v67, -s7, v166, v67
	v_fma_f32 v66, -s8, v142, v66
	v_fma_f32 v62, -s9, v158, v62
	s_nop 0
	s_nop 0
	v_readlane_b32 s6, v207, s16
	v_readlane_b32 s7, v209, s16
	s_nop 0
	v_fma_f32 v63, -s6, v140, v63
	v_fma_f32 v67, -s7, v152, v67
	s_nop 0
	s_nop 0
	s_nop 0
	s_nop 0
	s_nop 0
	s_nop 0
	s_nop 0
	s_nop 0
	s_nop 0
	s_nop 0
	s_nop 0
	s_nop 0
	s_nop 0
	s_nop 0
	s_nop 0
	s_nop 0
	s_nop 1
	s_nop 0
	s_nop 0
	s_nop 1
	s_nop 0
	v_pk_add_f32 v[62:63], v[66:67], v[62:63]
	v_mov_b32_e32 v67, v123
	v_mov_b32_e32 v66, v123
	v_pk_add_f32 v[62:63], v[62:63], v[62:63] op_sel:[0,1] op_sel_hi:[1,0]
	s_nop 0
	s_waitcnt lgkmcnt(0)
	v_sub_f32_e32 v29, v29, v247
	ds_read_b32 v246, v249 offset:12
	s_nop 0
	v_readlane_b32 s6, v196, s17
	v_readlane_b32 s7, v195, s17
	v_readlane_b32 s8, v198, s17
	v_readlane_b32 s9, v197, s36
	v_fma_f32 v29, -s6, v62, v29
	v_fma_f32 v67, -s7, v182, v67
	v_fma_f32 v66, -s8, v70, v66
	v_fma_f32 v28, -s9, v168, v28
	s_nop 0
	s_nop 0
	v_readlane_b32 s6, v200, s36
	v_readlane_b32 s7, v199, s36
	v_readlane_b32 s8, v202, s36
	v_readlane_b32 s9, v197, s17
	v_fma_f32 v29, -s6, v78, v29
	v_fma_f32 v67, -s7, v160, v67
	v_fma_f32 v66, -s8, v84, v66
	v_fma_f32 v28, -s9, v154, v28
	s_nop 0
	s_nop 0
	v_readlane_b32 s6, v200, s17
	v_readlane_b32 s7, v199, s17
	v_readlane_b32 s8, v202, s17
	v_readlane_b32 s9, v201, s36
	v_fma_f32 v29, -s6, v184, v29
	v_fma_f32 v67, -s7, v162, v67
	v_fma_f32 v66, -s8, v180, v66
	v_fma_f32 v28, -s9, v164, v28
	s_nop 0
	s_nop 0
	v_readlane_b32 s6, v204, s36
	v_readlane_b32 s7, v203, s36
	v_readlane_b32 s8, v206, s36
	v_readlane_b32 s9, v201, s17
	v_fma_f32 v29, -s6, v172, v29
	v_fma_f32 v67, -s7, v156, v67
	v_fma_f32 v66, -s8, v176, v66
	v_fma_f32 v28, -s9, v150, v28
	s_nop 0
	s_nop 0
	v_readlane_b32 s6, v204, s17
	v_readlane_b32 s7, v203, s17
	v_readlane_b32 s8, v206, s17
	v_readlane_b32 s9, v205, s36
	v_fma_f32 v29, -s6, v178, v29
	v_fma_f32 v67, -s7, v148, v67
	v_fma_f32 v66, -s8, v174, v66
	v_fma_f32 v28, -s9, v146, v28
	s_nop 0
	s_nop 0
	v_readlane_b32 s6, v208, s36
	v_readlane_b32 s7, v207, s36
	v_readlane_b32 s8, v209, s36
	v_readlane_b32 s9, v205, s17
	v_fma_f32 v29, -s6, v170, v29
	v_fma_f32 v67, -s7, v144, v67
	v_fma_f32 v66, -s8, v166, v66
	v_fma_f32 v28, -s9, v142, v28
	s_nop 0
	s_nop 0
	v_readlane_b32 s6, v208, s17
	v_readlane_b32 s7, v207, s17
	v_readlane_b32 s8, v209, s17
	v_fma_f32 v29, -s6, v158, v29
	v_fma_f32 v67, -s7, v140, v67
	v_fma_f32 v66, -s8, v152, v66
	s_nop 0
	s_nop 0
	s_nop 0
	s_nop 0
	s_nop 0
	s_nop 0
	s_nop 0
	s_nop 0
	s_nop 0
	s_nop 0
	s_nop 0
	s_nop 0
	s_nop 0
	s_nop 0
	s_nop 0
	s_nop 0
	s_nop 1
	s_nop 0
	s_nop 0
	s_nop 1
	s_nop 0
	s_nop 0
	s_nop 1
	s_nop 0
	v_pk_add_f32 v[28:29], v[66:67], v[28:29]
	s_nop 0
	v_pk_add_f32 v[186:187], v[28:29], v[28:29] op_sel:[0,1] op_sel_hi:[1,0]
	v_mov_b32_e32 v29, v123
	v_mov_b32_e32 v28, v123
	s_waitcnt lgkmcnt(0)
	v_sub_f32_e32 v25, v25, v246
	ds_read_b32 v247, v249 offset:8
	s_nop 0
	v_readlane_b32 s6, v194, s69
	v_readlane_b32 s7, v196, s69
	v_readlane_b32 s8, v195, s69
	v_readlane_b32 s9, v198, s69
	v_fma_f32 v25, -s6, v186, v25
	v_fma_f32 v29, -s7, v62, v29
	v_fma_f32 v28, -s8, v182, v28
	v_fma_f32 v24, -s9, v70, v24
	v_mov_b32_e32 v187, v62
	s_nop 0
	v_readlane_b32 s6, v197, s12
	v_readlane_b32 s7, v200, s12
	v_readlane_b32 s8, v199, s12
	v_readlane_b32 s9, v202, s12
	v_fma_f32 v25, -s6, v168, v25
	v_fma_f32 v29, -s7, v78, v29
	v_fma_f32 v28, -s8, v160, v28
	v_fma_f32 v24, -s9, v84, v24
	s_nop 0
	s_nop 0
	v_readlane_b32 s6, v197, s69
	v_readlane_b32 s7, v200, s69
	v_readlane_b32 s8, v199, s69
	v_readlane_b32 s9, v202, s69
	v_fma_f32 v25, -s6, v154, v25
	v_fma_f32 v29, -s7, v184, v29
	v_fma_f32 v28, -s8, v162, v28
	v_fma_f32 v24, -s9, v180, v24
	s_nop 0
	s_nop 0
	v_readlane_b32 s6, v201, s12
	v_readlane_b32 s7, v204, s12
	v_readlane_b32 s8, v203, s12
	v_readlane_b32 s9, v206, s12
	v_fma_f32 v25, -s6, v164, v25
	v_fma_f32 v29, -s7, v172, v29
	v_fma_f32 v28, -s8, v156, v28
	v_fma_f32 v24, -s9, v176, v24
	s_nop 0
	s_nop 0
	v_readlane_b32 s6, v201, s69
	v_readlane_b32 s7, v204, s69
	v_readlane_b32 s8, v203, s69
	v_readlane_b32 s9, v206, s69
	v_fma_f32 v25, -s6, v150, v25
	v_fma_f32 v29, -s7, v178, v29
	v_fma_f32 v28, -s8, v148, v28
	v_fma_f32 v24, -s9, v174, v24
	s_nop 0
	s_nop 0
	v_readlane_b32 s6, v205, s12
	v_readlane_b32 s7, v208, s12
	v_readlane_b32 s8, v207, s12
	v_readlane_b32 s9, v209, s12
	v_fma_f32 v25, -s6, v146, v25
	v_fma_f32 v29, -s7, v170, v29
	v_fma_f32 v28, -s8, v144, v28
	v_fma_f32 v24, -s9, v166, v24
	s_nop 0
	s_nop 0
	v_readlane_b32 s6, v205, s69
	v_readlane_b32 s7, v208, s69
	v_readlane_b32 s8, v207, s69
	v_readlane_b32 s9, v209, s69
	v_fma_f32 v25, -s6, v142, v25
	v_fma_f32 v29, -s7, v158, v29
	v_fma_f32 v28, -s8, v140, v28
	v_fma_f32 v24, -s9, v152, v24
	s_nop 0
	s_nop 0
	s_nop 0
	s_nop 0
	s_nop 0
	s_nop 0
	s_nop 0
	s_nop 0
	s_nop 0
	s_nop 0
	s_nop 0
	s_nop 0
	s_nop 0
	s_nop 0
	s_nop 0
	s_nop 0
	s_nop 0
	v_pk_add_f32 v[24:25], v[28:29], v[24:25]
	v_mov_b32_e32 v29, v123
	v_mov_b32_e32 v28, v123
	v_pk_add_f32 v[24:25], v[24:25], v[24:25] op_sel:[0,1] op_sel_hi:[1,0]
	s_nop 0
	s_waitcnt lgkmcnt(0)
	v_sub_f32_e32 v15, v15, v247
	ds_read_b32 v246, v249 offset:4
	s_nop 0
	v_readlane_b32 s6, v198, s15
	v_readlane_b32 s7, v194, s23
	v_readlane_b32 s8, v196, s23
	v_readlane_b32 s9, v195, s23
	v_fma_f32 v15, -s6, v24, v15
	v_fma_f32 v29, -s7, v186, v29
	v_fma_f32 v28, -s8, v62, v28
	v_fma_f32 v14, -s9, v182, v14
	s_nop 0
	s_nop 0
	v_readlane_b32 s6, v198, s23
	v_readlane_b32 s7, v197, s15
	v_readlane_b32 s8, v200, s15
	v_readlane_b32 s9, v199, s15
	v_fma_f32 v15, -s6, v70, v15
	v_fma_f32 v29, -s7, v168, v29
	v_fma_f32 v28, -s8, v78, v28
	v_fma_f32 v14, -s9, v160, v14
	s_nop 0
	s_nop 0
	v_readlane_b32 s6, v202, s15
	v_readlane_b32 s7, v197, s23
	v_readlane_b32 s8, v200, s23
	v_readlane_b32 s9, v199, s23
	v_fma_f32 v15, -s6, v84, v15
	v_fma_f32 v29, -s7, v154, v29
	v_fma_f32 v28, -s8, v184, v28
	v_fma_f32 v14, -s9, v162, v14
	s_nop 0
	s_nop 0
	v_readlane_b32 s6, v202, s23
	v_readlane_b32 s7, v201, s15
	v_readlane_b32 s8, v204, s15
	v_readlane_b32 s9, v203, s15
	v_fma_f32 v15, -s6, v180, v15
	v_fma_f32 v29, -s7, v164, v29
	v_fma_f32 v28, -s8, v172, v28
	v_fma_f32 v14, -s9, v156, v14
	s_nop 0
	s_nop 0
	v_readlane_b32 s6, v206, s15
	v_readlane_b32 s7, v201, s23
	v_readlane_b32 s8, v204, s23
	v_readlane_b32 s9, v203, s23
	v_fma_f32 v15, -s6, v176, v15
	v_fma_f32 v29, -s7, v150, v29
	v_fma_f32 v28, -s8, v178, v28
	v_fma_f32 v14, -s9, v148, v14
	s_nop 0
	s_nop 0
	v_readlane_b32 s6, v206, s23
	v_readlane_b32 s7, v205, s15
	v_readlane_b32 s8, v208, s15
	v_readlane_b32 s9, v207, s15
	v_fma_f32 v15, -s6, v174, v15
	v_fma_f32 v29, -s7, v146, v29
	v_fma_f32 v28, -s8, v170, v28
	v_fma_f32 v14, -s9, v144, v14
	s_nop 0
	s_nop 0
	v_readlane_b32 s6, v209, s15
	v_readlane_b32 s7, v205, s23
	v_readlane_b32 s8, v208, s23
	v_readlane_b32 s9, v207, s23
	v_fma_f32 v15, -s6, v166, v15
	v_fma_f32 v29, -s7, v142, v29
	v_fma_f32 v28, -s8, v158, v28
	v_fma_f32 v14, -s9, v140, v14
	s_nop 0
	s_nop 0
	v_readlane_b32 s6, v209, s23
	s_nop 1
	v_fma_f32 v15, -s6, v152, v15
	s_nop 0
	s_nop 0
	s_nop 0
	s_nop 0
	s_nop 0
	s_nop 0
	s_nop 0
	s_nop 0
	s_nop 0
	s_nop 0
	s_nop 0
	s_nop 0
	s_nop 0
	s_nop 0
	s_nop 0
	s_nop 0
	s_nop 1
	s_nop 0
	v_pk_add_f32 v[14:15], v[28:29], v[14:15]
	s_nop 0
	v_pk_add_f32 v[188:189], v[14:15], v[14:15] op_sel:[0,1] op_sel_hi:[1,0]
	v_mov_b32_e32 v15, v123
	v_mov_b32_e32 v14, v123
	s_waitcnt lgkmcnt(0)
	v_sub_f32_e32 v7, v7, v246
	ds_read_b32 v247, v249 offset:0
	s_nop 0
	v_readlane_b32 s6, v195, s26
	v_readlane_b32 s7, v198, s26
	v_readlane_b32 s8, v194, s10
	v_readlane_b32 s9, v196, s10
	v_fma_f32 v7, -s6, v188, v7
	v_fma_f32 v15, -s7, v24, v15
	v_fma_f32 v14, -s8, v186, v14
	v_fma_f32 v6, -s9, v62, v6
	v_mov_b32_e32 v189, v24
	s_nop 0
	v_readlane_b32 s6, v195, s10
	v_readlane_b32 s7, v198, s10
	v_readlane_b32 s8, v197, s26
	v_readlane_b32 s9, v200, s26
	v_fma_f32 v7, -s6, v182, v7
	v_fma_f32 v15, -s7, v70, v15
	v_fma_f32 v14, -s8, v168, v14
	v_fma_f32 v6, -s9, v78, v6
	s_nop 0
	s_nop 0
	v_readlane_b32 s6, v199, s26
	v_readlane_b32 s7, v202, s26
	v_readlane_b32 s8, v197, s10
	v_readlane_b32 s9, v200, s10
	v_fma_f32 v7, -s6, v160, v7
	v_fma_f32 v15, -s7, v84, v15
	v_fma_f32 v14, -s8, v154, v14
	v_fma_f32 v6, -s9, v184, v6
	s_nop 0
	s_nop 0
	v_readlane_b32 s6, v199, s10
	v_readlane_b32 s7, v202, s10
	v_readlane_b32 s8, v201, s26
	v_readlane_b32 s9, v204, s26
	v_fma_f32 v7, -s6, v162, v7
	v_fma_f32 v15, -s7, v180, v15
	v_fma_f32 v14, -s8, v164, v14
	v_fma_f32 v6, -s9, v172, v6
	s_nop 0
	s_nop 0
	v_readlane_b32 s6, v203, s26
	v_readlane_b32 s7, v206, s26
	v_readlane_b32 s8, v201, s10
	v_readlane_b32 s9, v204, s10
	v_fma_f32 v7, -s6, v156, v7
	v_fma_f32 v15, -s7, v176, v15
	v_fma_f32 v14, -s8, v150, v14
	v_fma_f32 v6, -s9, v178, v6
	s_nop 0
	s_nop 0
	v_readlane_b32 s6, v203, s10
	v_readlane_b32 s7, v206, s10
	v_readlane_b32 s8, v205, s26
	v_readlane_b32 s9, v208, s26
	v_fma_f32 v7, -s6, v148, v7
	v_fma_f32 v15, -s7, v174, v15
	v_fma_f32 v14, -s8, v146, v14
	v_fma_f32 v6, -s9, v170, v6
	s_nop 0
	s_nop 0
	v_readlane_b32 s6, v207, s26
	v_readlane_b32 s7, v209, s26
	v_readlane_b32 s8, v205, s10
	v_readlane_b32 s9, v208, s10
	v_fma_f32 v7, -s6, v144, v7
	v_fma_f32 v15, -s7, v166, v15
	v_fma_f32 v14, -s8, v142, v14
	v_fma_f32 v6, -s9, v158, v6
	s_nop 0
	s_nop 0
	v_readlane_b32 s6, v207, s10
	v_readlane_b32 s7, v209, s10
	s_nop 0
	v_fma_f32 v7, -s6, v140, v7
	v_fma_f32 v15, -s7, v152, v15
	s_nop 0
	s_nop 0
	s_nop 0
	s_nop 0
	s_nop 0
	s_nop 0
	s_nop 0
	s_nop 0
	s_nop 0
	s_nop 0
	s_nop 0
	s_nop 0
	s_nop 0
	s_nop 0
	s_nop 0
	s_nop 0
	s_nop 1
	s_nop 0
	s_nop 0
	s_nop 1
	s_nop 0
	v_pk_add_f32 v[6:7], v[14:15], v[6:7]
	v_mov_b32_e32 v15, v123
	v_mov_b32_e32 v14, v123
	v_pk_add_f32 v[6:7], v[6:7], v[6:7] op_sel:[0,1] op_sel_hi:[1,0]
	s_nop 0
	s_waitcnt lgkmcnt(0)
	v_sub_f32_e32 v3, v3, v247
	s_nop 0
	v_readlane_b32 s6, v196, s13
	v_readlane_b32 s7, v195, s13
	v_readlane_b32 s8, v198, s13
	v_readlane_b32 s9, v194, s31
	v_fma_f32 v3, -s6, v6, v3
	v_fma_f32 v15, -s7, v188, v15
	v_fma_f32 v14, -s8, v24, v14
	v_fma_f32 v2, -s9, v186, v2
	s_nop 0
	s_nop 0
	v_readlane_b32 s6, v196, s31
	v_readlane_b32 s7, v195, s31
	v_readlane_b32 s8, v198, s31
	v_readlane_b32 s9, v197, s13
	v_fma_f32 v3, -s6, v62, v3
	v_fma_f32 v15, -s7, v182, v15
	v_fma_f32 v14, -s8, v70, v14
	v_fma_f32 v2, -s9, v168, v2
	s_nop 0
	s_nop 0
	v_readlane_b32 s6, v200, s13
	v_readlane_b32 s7, v199, s13
	v_readlane_b32 s8, v202, s13
	v_readlane_b32 s9, v197, s31
	v_fma_f32 v3, -s6, v78, v3
	v_fma_f32 v15, -s7, v160, v15
	v_fma_f32 v14, -s8, v84, v14
	v_fma_f32 v2, -s9, v154, v2
	s_nop 0
	s_nop 0
	v_readlane_b32 s6, v200, s31
	v_readlane_b32 s7, v199, s31
	v_readlane_b32 s8, v202, s31
	v_readlane_b32 s9, v201, s13
	v_fma_f32 v3, -s6, v184, v3
	v_fma_f32 v15, -s7, v162, v15
	v_fma_f32 v14, -s8, v180, v14
	v_fma_f32 v2, -s9, v164, v2
	s_nop 0
	s_nop 0
	v_readlane_b32 s6, v204, s13
	v_readlane_b32 s7, v203, s13
	v_readlane_b32 s8, v206, s13
	v_readlane_b32 s9, v201, s31
	v_fma_f32 v3, -s6, v172, v3
	v_fma_f32 v15, -s7, v156, v15
	v_fma_f32 v14, -s8, v176, v14
	v_fma_f32 v2, -s9, v150, v2
	s_nop 0
	s_nop 0
	v_readlane_b32 s6, v204, s31
	v_readlane_b32 s7, v203, s31
	v_readlane_b32 s8, v206, s31
	v_readlane_b32 s9, v205, s13
	v_fma_f32 v3, -s6, v178, v3
	v_fma_f32 v15, -s7, v148, v15
	v_fma_f32 v14, -s8, v174, v14
	v_fma_f32 v2, -s9, v146, v2
	s_nop 0
	s_nop 0
	v_readlane_b32 s6, v208, s13
	v_readlane_b32 s7, v207, s13
	v_readlane_b32 s8, v209, s13
	v_readlane_b32 s9, v205, s31
	v_fma_f32 v3, -s6, v170, v3
	v_fma_f32 v15, -s7, v144, v15
	v_fma_f32 v14, -s8, v166, v14
	v_fma_f32 v2, -s9, v142, v2
	s_nop 0
	s_nop 0
	v_readlane_b32 s6, v208, s31
	v_readlane_b32 s7, v207, s31
	v_readlane_b32 s8, v209, s31
	v_fma_f32 v3, -s6, v158, v3
	v_fma_f32 v15, -s7, v140, v15
	v_fma_f32 v14, -s8, v152, v14
	s_nop 0
	s_nop 0
	s_nop 0
	s_nop 0
	s_nop 0
	s_nop 0
	s_nop 0
	s_nop 0
	s_nop 0
	s_nop 0
	s_nop 0
	s_nop 0
	s_nop 0
	s_nop 0
	s_nop 0
	s_nop 0
	s_nop 1
	s_nop 0
	s_nop 0
	s_nop 1
	s_nop 0
	s_nop 0
	s_nop 1
	s_nop 0
	v_pk_add_f32 v[2:3], v[14:15], v[2:3]
	s_nop 0
	v_pk_add_f32 v[152:153], v[2:3], v[2:3] op_sel:[0,1] op_sel_hi:[1,0]
	v_readlane_b32 s6, v193, 0
	v_readlane_b32 s7, v193, 1
	v_mov_b32_e32 v153, v6
	s_nop 0
	v_pk_mul_f32 v[2:3], v[152:153], s[6:7]
	v_readlane_b32 s6, v193, 8
	v_readlane_b32 s7, v193, 9
	v_cvt_pk_bf16_f32 v62, v2, v3
	s_nop 0
	v_pk_mul_f32 v[4:5], v[168:169], s[6:7]
	v_readlane_b32 s6, v193, 2
	v_readlane_b32 s7, v193, 3
	v_cvt_pk_bf16_f32 v66, v4, v5
	s_nop 1
	v_permlane32_swap_b32_e32 v62, v66
	v_pk_mul_f32 v[6:7], v[188:189], s[6:7]
	v_readlane_b32 s6, v193, 10
	v_readlane_b32 s7, v193, 11
	v_cvt_pk_bf16_f32 v63, v6, v7
	s_nop 0
	v_pk_mul_f32 v[8:9], v[160:161], s[6:7]
	v_readlane_b32 s6, v193, 4
	v_readlane_b32 s7, v193, 5
	v_cvt_pk_bf16_f32 v67, v8, v9
	s_nop 1
	v_permlane32_swap_b32_e32 v63, v67
	v_pk_mul_f32 v[10:11], v[186:187], s[6:7]
	v_readlane_b32 s6, v193, 12
	v_readlane_b32 s7, v193, 13
	v_cvt_pk_bf16_f32 v64, v10, v11
	s_nop 0
	v_pk_mul_f32 v[12:13], v[154:155], s[6:7]
	v_readlane_b32 s6, v193, 6
	v_readlane_b32 s7, v193, 7
	v_cvt_pk_bf16_f32 v68, v12, v13
	s_nop 1
	v_permlane32_swap_b32_e32 v64, v68
	v_pk_mul_f32 v[14:15], v[182:183], s[6:7]
	v_readlane_b32 s6, v193, 14
	v_readlane_b32 s7, v193, 15
	v_cvt_pk_bf16_f32 v65, v14, v15
	s_nop 0
	v_pk_mul_f32 v[16:17], v[162:163], s[6:7]
	v_readlane_b32 s6, v193, 16
	v_readlane_b32 s7, v193, 17
	v_cvt_pk_bf16_f32 v69, v16, v17
	s_nop 1
	v_permlane32_swap_b32_e32 v65, v69
	v_pk_mul_f32 v[2:3], v[164:165], s[6:7]
	v_readlane_b32 s6, v193, 24
	v_readlane_b32 s7, v193, 25
	v_cvt_pk_bf16_f32 v70, v2, v3
	s_nop 0
	v_pk_mul_f32 v[4:5], v[146:147], s[6:7]
	v_readlane_b32 s6, v193, 18
	v_readlane_b32 s7, v193, 19
	v_cvt_pk_bf16_f32 v74, v4, v5
	s_nop 1
	v_permlane32_swap_b32_e32 v70, v74
	v_pk_mul_f32 v[6:7], v[156:157], s[6:7]
	v_readlane_b32 s6, v193, 26
	v_readlane_b32 s7, v193, 27
	v_cvt_pk_bf16_f32 v71, v6, v7
	s_nop 0
	v_pk_mul_f32 v[8:9], v[144:145], s[6:7]
	v_readlane_b32 s6, v193, 20
	v_readlane_b32 s7, v193, 21
	v_cvt_pk_bf16_f32 v75, v8, v9
	s_nop 1
	v_permlane32_swap_b32_e32 v71, v75
	v_pk_mul_f32 v[10:11], v[150:151], s[6:7]
	v_readlane_b32 s6, v193, 28
	v_readlane_b32 s7, v193, 29
	v_cvt_pk_bf16_f32 v72, v10, v11
	s_nop 0
	v_pk_mul_f32 v[12:13], v[142:143], s[6:7]
	v_readlane_b32 s6, v193, 22
	v_readlane_b32 s7, v193, 23
	v_cvt_pk_bf16_f32 v76, v12, v13
	s_nop 1
	v_permlane32_swap_b32_e32 v72, v76
	v_pk_mul_f32 v[14:15], v[148:149], s[6:7]
	v_readlane_b32 s6, v193, 30
	v_readlane_b32 s7, v193, 31
	v_cvt_pk_bf16_f32 v73, v14, v15
	s_nop 0
	v_pk_mul_f32 v[16:17], v[140:141], s[6:7]
	v_readlane_b32 s6, v193, 32
	v_readlane_b32 s7, v193, 33
	v_cvt_pk_bf16_f32 v77, v16, v17
	s_nop 1
	v_permlane32_swap_b32_e32 v73, v77
	v_pk_mul_f32 v[2:3], v[138:139], s[6:7]
	v_readlane_b32 s6, v193, 40
	v_readlane_b32 s7, v193, 41
	v_cvt_pk_bf16_f32 v2, v2, v3
	s_nop 0
	v_pk_mul_f32 v[4:5], v[130:131], s[6:7]
	v_readlane_b32 s6, v193, 34
	v_readlane_b32 s7, v193, 35
	v_cvt_pk_bf16_f32 v78, v4, v5
	s_nop 1
	v_permlane32_swap_b32_e32 v2, v78
	v_pk_mul_f32 v[6:7], v[136:137], s[6:7]
	v_readlane_b32 s6, v193, 42
	v_readlane_b32 s7, v193, 43
	v_cvt_pk_bf16_f32 v3, v6, v7
	s_nop 0
	v_pk_mul_f32 v[8:9], v[128:129], s[6:7]
	v_readlane_b32 s6, v193, 36
	v_readlane_b32 s7, v193, 37
	v_cvt_pk_bf16_f32 v79, v8, v9
	s_nop 1
	v_permlane32_swap_b32_e32 v3, v79
	v_pk_mul_f32 v[10:11], v[134:135], s[6:7]
	v_readlane_b32 s6, v193, 44
	v_readlane_b32 s7, v193, 45
	v_cvt_pk_bf16_f32 v6, v10, v11
	s_nop 0
	v_pk_mul_f32 v[12:13], v[118:119], s[6:7]
	v_readlane_b32 s6, v193, 38
	v_readlane_b32 s7, v193, 39
	v_cvt_pk_bf16_f32 v80, v12, v13
	s_nop 1
	v_permlane32_swap_b32_e32 v6, v80
	v_pk_mul_f32 v[14:15], v[132:133], s[6:7]
	v_readlane_b32 s6, v193, 46
	v_readlane_b32 s7, v193, 47
	v_cvt_pk_bf16_f32 v7, v14, v15
	s_nop 0
	v_pk_mul_f32 v[16:17], v[116:117], s[6:7]
	v_readlane_b32 s6, v193, 48
	v_readlane_b32 s7, v193, 49
	v_cvt_pk_bf16_f32 v81, v16, v17
	s_nop 1
	v_permlane32_swap_b32_e32 v7, v81
	v_pk_mul_f32 v[2:3], v[114:115], s[6:7]
	v_readlane_b32 s6, v193, 56
	v_readlane_b32 s7, v193, 57
	v_cvt_pk_bf16_f32 v2, v2, v3
	s_nop 0
	v_pk_mul_f32 v[4:5], v[94:95], s[6:7]
	v_readlane_b32 s6, v193, 50
	v_readlane_b32 s7, v193, 51
	v_cvt_pk_bf16_f32 v82, v4, v5
	s_nop 1
	v_permlane32_swap_b32_e32 v2, v82
	v_pk_mul_f32 v[6:7], v[110:111], s[6:7]
	v_readlane_b32 s6, v193, 58
	v_readlane_b32 s7, v193, 59
	v_cvt_pk_bf16_f32 v3, v6, v7
	s_nop 0
	v_pk_mul_f32 v[8:9], v[92:93], s[6:7]
	v_readlane_b32 s6, v193, 52
	v_readlane_b32 s7, v193, 53
	v_cvt_pk_bf16_f32 v83, v8, v9
	s_nop 1
	v_permlane32_swap_b32_e32 v3, v83
	v_pk_mul_f32 v[10:11], v[104:105], s[6:7]
	v_readlane_b32 s6, v193, 60
	v_readlane_b32 s7, v193, 61
	v_cvt_pk_bf16_f32 v6, v10, v11
	s_nop 0
	v_pk_mul_f32 v[12:13], v[90:91], s[6:7]
	v_readlane_b32 s6, v193, 54
	v_readlane_b32 s7, v193, 55
	v_cvt_pk_bf16_f32 v84, v12, v13
	s_nop 1
	v_permlane32_swap_b32_e32 v6, v84
	v_pk_mul_f32 v[14:15], v[96:97], s[6:7]
	v_readlane_b32 s6, v193, 62
	v_readlane_b32 s7, v193, 63
	v_cvt_pk_bf16_f32 v7, v14, v15
	s_nop 0
	v_pk_mul_f32 v[16:17], v[88:89], s[6:7]
	s_mov_b32 s7, 0x26400000
	v_cvt_pk_bf16_f32 v85, v16, v17
	s_nop 1
	v_permlane32_swap_b32_e32 v7, v85
	s_waitcnt vmcnt(5)
	v_mfma_f32_32x32x16_bf16 v[2:17], v[62:65], v[18:21], 0
	s_mov_b32 s6, 0x9002000
	v_mfma_f32_32x32x16_bf16 v[18:33], v[66:69], v[18:21], 0
	v_mfma_f32_32x32x16_bf16 v[18:33], v[74:77], v[58:61], v[18:33]
	v_mfma_f32_32x32x16_bf16 v[18:33], v[78:81], v[54:57], v[18:33]
	v_mfma_f32_32x32x16_bf16 v[2:17], v[70:73], v[58:61], v[2:17]
	s_waitcnt vmcnt(4)
	v_mfma_f32_32x32x16_bf16 v[18:33], v[82:85], v[50:53], v[18:33]
	v_add_co_u32_e32 v50, vcc, s7, v126
	s_nop 8
	v_cvt_pk_bf16_f32 v2, v2, v3
	v_cvt_pk_bf16_f32 v3, v4, v5
	v_cvt_pk_bf16_f32 v4, v6, v7
	v_cvt_pk_bf16_f32 v5, v8, v9
	v_addc_co_u32_e32 v51, vcc, 0, v127, vcc
	global_store_dwordx4 v[50:51], v[2:5], off
	v_add_co_u32_e32 v6, vcc, s7, v120
	s_nop 0
	v_cvt_pk_bf16_f32 v2, v10, v11
	v_cvt_pk_bf16_f32 v3, v12, v13
	v_cvt_pk_bf16_f32 v4, v14, v15
	v_cvt_pk_bf16_f32 v5, v16, v17
	global_store_dwordx4 v[50:51], v[2:5], off offset:16
	v_addc_co_u32_e32 v7, vcc, 0, v121, vcc
	s_nop 0
	v_cvt_pk_bf16_f32 v2, v18, v19
	v_cvt_pk_bf16_f32 v3, v20, v21
	v_cvt_pk_bf16_f32 v4, v22, v23
	v_cvt_pk_bf16_f32 v5, v24, v25
	global_store_dwordx4 v[6:7], v[2:5], off
	s_nop 1
	v_cvt_pk_bf16_f32 v2, v26, v27
	v_cvt_pk_bf16_f32 v3, v28, v29
	v_cvt_pk_bf16_f32 v4, v30, v31
	v_cvt_pk_bf16_f32 v5, v32, v33
	global_store_dwordx4 v[6:7], v[2:5], off offset:16
	s_waitcnt vmcnt(7)
	v_mfma_f32_32x32x16_bf16 v[18:33], v[62:65], v[46:49], 0
	v_mfma_f32_32x32x16_bf16 v[2:17], v[66:69], v[46:49], 0
	s_waitcnt vmcnt(6)
	v_mfma_f32_32x32x16_bf16 v[2:17], v[74:77], v[42:45], v[2:17]
	s_waitcnt vmcnt(5)
	v_mfma_f32_32x32x16_bf16 v[2:17], v[78:81], v[38:41], v[2:17]
	s_waitcnt vmcnt(4)
	v_mfma_f32_32x32x16_bf16 v[2:17], v[82:85], v[34:37], v[2:17]
	v_mfma_f32_32x32x16_bf16 v[18:33], v[70:73], v[42:45], v[18:33]
	s_nop 10
	v_cvt_pk_bf16_f32 v2, v2, v3
	v_cvt_pk_bf16_f32 v3, v4, v5
	v_cvt_pk_bf16_f32 v4, v6, v7
	v_add_co_u32_e32 v6, vcc, s7, v112
	v_cvt_pk_bf16_f32 v5, v8, v9
	s_nop 0
	v_addc_co_u32_e32 v7, vcc, 0, v113, vcc
	v_cvt_pk_bf16_f32 v18, v18, v19
	v_cvt_pk_bf16_f32 v19, v20, v21
	v_cvt_pk_bf16_f32 v20, v22, v23
	v_cvt_pk_bf16_f32 v21, v24, v25
	v_add_co_u32_e32 v38, vcc, s6, v98
	global_store_dwordx4 v[50:51], v[18:21], off offset:2048
	s_nop 0
	v_addc_co_u32_e32 v39, vcc, 0, v99, vcc
	v_cvt_pk_bf16_f32 v18, v26, v27
	v_cvt_pk_bf16_f32 v19, v28, v29
	v_cvt_pk_bf16_f32 v20, v30, v31
	v_cvt_pk_bf16_f32 v21, v32, v33
	s_mov_b32 s6, 0x9003000
	global_store_dwordx4 v[50:51], v[18:21], off offset:2064
	global_store_dwordx4 v[6:7], v[2:5], off
	v_add_co_u32_e32 v40, vcc, s6, v98
	s_nop 0
	v_cvt_pk_bf16_f32 v2, v10, v11
	v_cvt_pk_bf16_f32 v3, v12, v13
	v_cvt_pk_bf16_f32 v4, v14, v15
	v_cvt_pk_bf16_f32 v5, v16, v17
	global_store_dwordx4 v[6:7], v[2:5], off offset:16
	v_addc_co_u32_e32 v41, vcc, 0, v99, vcc
	s_nop 0
	s_nop 0
	s_nop 0
	v_mfma_f32_32x32x16_bf16 v[18:33], v[62:65], v[212:215], 0
	v_mfma_f32_32x32x16_bf16 v[2:17], v[66:69], v[212:215], 0
	s_nop 0
	v_mfma_f32_32x32x16_bf16 v[18:33], v[70:73], v[216:219], v[18:33]
	v_mfma_f32_32x32x16_bf16 v[2:17], v[74:77], v[216:219], v[2:17]
	s_nop 0
	s_nop 9
	v_cvt_pk_bf16_f32 v18, v18, v19
	v_cvt_pk_bf16_f32 v19, v20, v21
	v_cvt_pk_bf16_f32 v20, v22, v23
	v_add_co_u32_e32 v22, vcc, s7, v108
	v_cvt_pk_bf16_f32 v21, v24, v25
	s_nop 0
	v_mfma_f32_32x32x16_bf16 v[2:17], v[78:81], v[220:223], v[2:17]
	s_nop 0
	v_addc_co_u32_e32 v23, vcc, 0, v109, vcc
	global_store_dwordx4 v[22:23], v[18:21], off
	s_nop 1
	v_cvt_pk_bf16_f32 v18, v26, v27
	s_nop 0
	v_mfma_f32_32x32x16_bf16 v[2:17], v[82:85], v[224:227], v[2:17]
	v_cvt_pk_bf16_f32 v19, v28, v29
	v_cvt_pk_bf16_f32 v20, v30, v31
	v_cvt_pk_bf16_f32 v21, v32, v33
	global_store_dwordx4 v[22:23], v[18:21], off offset:16
	s_nop 7
	v_cvt_pk_bf16_f32 v2, v2, v3
	v_cvt_pk_bf16_f32 v3, v4, v5
	v_cvt_pk_bf16_f32 v4, v6, v7
	v_add_co_u32_e32 v6, vcc, s7, v106
	v_cvt_pk_bf16_f32 v5, v8, v9
	s_nop 0
	v_addc_co_u32_e32 v7, vcc, 0, v107, vcc
	global_store_dwordx4 v[6:7], v[2:5], off
	s_nop 1
	v_cvt_pk_bf16_f32 v2, v10, v11
	v_cvt_pk_bf16_f32 v3, v12, v13
	v_cvt_pk_bf16_f32 v4, v14, v15
	v_cvt_pk_bf16_f32 v5, v16, v17
	global_store_dwordx4 v[6:7], v[2:5], off offset:16
	s_nop 0
	s_nop 0
	s_nop 0
	s_nop 0
	v_mfma_f32_32x32x16_bf16 v[18:33], v[62:65], v[228:231], 0
	v_mfma_f32_32x32x16_bf16 v[2:17], v[66:69], v[228:231], 0
	s_nop 0
	v_mfma_f32_32x32x16_bf16 v[18:33], v[70:73], v[232:235], v[18:33]
	v_mfma_f32_32x32x16_bf16 v[2:17], v[74:77], v[232:235], v[2:17]
	s_nop 0
	s_nop 9
	v_cvt_pk_bf16_f32 v18, v18, v19
	v_cvt_pk_bf16_f32 v19, v20, v21
	v_cvt_pk_bf16_f32 v20, v22, v23
	v_add_co_u32_e32 v22, vcc, s7, v102
	v_cvt_pk_bf16_f32 v21, v24, v25
	s_nop 0
	v_mfma_f32_32x32x16_bf16 v[2:17], v[78:81], v[236:239], v[2:17]
	s_nop 0
	v_addc_co_u32_e32 v23, vcc, 0, v103, vcc
	global_store_dwordx4 v[22:23], v[18:21], off
	s_nop 1
	v_cvt_pk_bf16_f32 v18, v26, v27
	s_nop 0
	v_mfma_f32_32x32x16_bf16 v[2:17], v[82:85], v[240:243], v[2:17]
	v_cvt_pk_bf16_f32 v19, v28, v29
	v_cvt_pk_bf16_f32 v20, v30, v31
	v_cvt_pk_bf16_f32 v21, v32, v33
	global_store_dwordx4 v[22:23], v[18:21], off offset:16
	s_nop 7
	v_cvt_pk_bf16_f32 v2, v2, v3
	v_cvt_pk_bf16_f32 v3, v4, v5
	v_cvt_pk_bf16_f32 v4, v6, v7
	v_add_co_u32_e32 v6, vcc, s7, v100
	v_cvt_pk_bf16_f32 v5, v8, v9
	s_nop 0
	v_addc_co_u32_e32 v7, vcc, 0, v101, vcc
	global_store_dwordx4 v[6:7], v[2:5], off
	s_nop 1
	v_cvt_pk_bf16_f32 v2, v10, v11
	v_cvt_pk_bf16_f32 v3, v12, v13
	v_cvt_pk_bf16_f32 v4, v14, v15
	v_cvt_pk_bf16_f32 v5, v16, v17
	global_store_dwordx4 v[6:7], v[2:5], off offset:16
	v_readlane_b32 s6, v210, 0
	v_readlane_b32 s7, v210, 1
	s_lshl_b64 s[4:5], s[4:5], 20
	v_readlane_b32 s8, v250, 17
	v_pk_mul_f32 v[2:3], v[152:153], s[6:7]
	v_readlane_b32 s6, v210, 8
	v_readlane_b32 s7, v210, 9
	v_cvt_pk_bf16_f32 v34, v2, v3
	s_nop 0
	v_pk_mul_f32 v[4:5], v[168:169], s[6:7]
	v_readlane_b32 s6, v210, 2
	v_readlane_b32 s7, v210, 3
	v_cvt_pk_bf16_f32 v38, v4, v5
	s_nop 1
	v_permlane32_swap_b32_e32 v34, v38
	v_pk_mul_f32 v[6:7], v[188:189], s[6:7]
	v_readlane_b32 s6, v210, 10
	v_readlane_b32 s7, v210, 11
	v_cvt_pk_bf16_f32 v35, v6, v7
	s_nop 0
	v_pk_mul_f32 v[8:9], v[160:161], s[6:7]
	v_readlane_b32 s6, v210, 4
	v_readlane_b32 s7, v210, 5
	v_cvt_pk_bf16_f32 v39, v8, v9
	s_nop 1
	v_permlane32_swap_b32_e32 v35, v39
	v_pk_mul_f32 v[10:11], v[186:187], s[6:7]
	v_readlane_b32 s6, v210, 12
	v_readlane_b32 s7, v210, 13
	v_cvt_pk_bf16_f32 v36, v10, v11
	s_nop 0
	v_pk_mul_f32 v[12:13], v[154:155], s[6:7]
	v_readlane_b32 s6, v210, 6
	v_readlane_b32 s7, v210, 7
	v_cvt_pk_bf16_f32 v40, v12, v13
	s_nop 1
	v_permlane32_swap_b32_e32 v36, v40
	v_pk_mul_f32 v[14:15], v[182:183], s[6:7]
	v_readlane_b32 s6, v210, 14
	v_readlane_b32 s7, v210, 15
	v_cvt_pk_bf16_f32 v37, v14, v15
	s_nop 0
	v_pk_mul_f32 v[16:17], v[162:163], s[6:7]
	v_readlane_b32 s6, v210, 16
	v_readlane_b32 s7, v210, 17
	v_cvt_pk_bf16_f32 v41, v16, v17
	s_nop 1
	v_permlane32_swap_b32_e32 v37, v41
	v_pk_mul_f32 v[2:3], v[164:165], s[6:7]
	v_readlane_b32 s6, v210, 24
	v_readlane_b32 s7, v210, 25
	v_cvt_pk_bf16_f32 v42, v2, v3
	s_nop 0
	v_pk_mul_f32 v[4:5], v[146:147], s[6:7]
	v_readlane_b32 s6, v210, 18
	v_readlane_b32 s7, v210, 19
	v_cvt_pk_bf16_f32 v46, v4, v5
	s_nop 1
	v_permlane32_swap_b32_e32 v42, v46
	v_pk_mul_f32 v[6:7], v[156:157], s[6:7]
	v_readlane_b32 s6, v210, 26
	v_readlane_b32 s7, v210, 27
	v_cvt_pk_bf16_f32 v43, v6, v7
	s_nop 0
	v_pk_mul_f32 v[8:9], v[144:145], s[6:7]
	v_readlane_b32 s6, v210, 20
	v_readlane_b32 s7, v210, 21
	v_cvt_pk_bf16_f32 v47, v8, v9
	s_nop 1
	v_permlane32_swap_b32_e32 v43, v47
	v_pk_mul_f32 v[10:11], v[150:151], s[6:7]
	v_readlane_b32 s6, v210, 28
	v_readlane_b32 s7, v210, 29
	v_cvt_pk_bf16_f32 v44, v10, v11
	s_nop 0
	v_pk_mul_f32 v[12:13], v[142:143], s[6:7]
	v_readlane_b32 s6, v210, 22
	v_readlane_b32 s7, v210, 23
	v_cvt_pk_bf16_f32 v48, v12, v13
	s_nop 1
	v_permlane32_swap_b32_e32 v44, v48
	v_pk_mul_f32 v[14:15], v[148:149], s[6:7]
	v_readlane_b32 s6, v210, 30
	v_readlane_b32 s7, v210, 31
	v_cvt_pk_bf16_f32 v45, v14, v15
	s_nop 0
	v_pk_mul_f32 v[16:17], v[140:141], s[6:7]
	v_readlane_b32 s6, v210, 32
	v_readlane_b32 s7, v210, 33
	v_cvt_pk_bf16_f32 v49, v16, v17
	s_nop 1
	v_permlane32_swap_b32_e32 v45, v49
	v_pk_mul_f32 v[2:3], v[138:139], s[6:7]
	v_readlane_b32 s6, v210, 40
	v_readlane_b32 s7, v210, 41
	v_cvt_pk_bf16_f32 v2, v2, v3
	s_nop 0
	v_pk_mul_f32 v[4:5], v[130:131], s[6:7]
	v_readlane_b32 s6, v210, 34
	v_readlane_b32 s7, v210, 35
	v_cvt_pk_bf16_f32 v50, v4, v5
	s_nop 1
	v_permlane32_swap_b32_e32 v2, v50
	v_pk_mul_f32 v[6:7], v[136:137], s[6:7]
	v_readlane_b32 s6, v210, 42
	v_readlane_b32 s7, v210, 43
	v_cvt_pk_bf16_f32 v3, v6, v7
	s_nop 0
	v_pk_mul_f32 v[8:9], v[128:129], s[6:7]
	v_readlane_b32 s6, v210, 36
	v_readlane_b32 s7, v210, 37
	v_cvt_pk_bf16_f32 v51, v8, v9
	s_nop 1
	v_permlane32_swap_b32_e32 v3, v51
	v_pk_mul_f32 v[10:11], v[134:135], s[6:7]
	v_readlane_b32 s6, v210, 44
	v_readlane_b32 s7, v210, 45
	v_cvt_pk_bf16_f32 v6, v10, v11
	s_nop 0
	v_pk_mul_f32 v[12:13], v[118:119], s[6:7]
	v_readlane_b32 s6, v210, 38
	v_readlane_b32 s7, v210, 39
	v_cvt_pk_bf16_f32 v52, v12, v13
	s_nop 1
	v_permlane32_swap_b32_e32 v6, v52
	v_pk_mul_f32 v[14:15], v[132:133], s[6:7]
	v_readlane_b32 s6, v210, 46
	v_readlane_b32 s7, v210, 47
	v_cvt_pk_bf16_f32 v7, v14, v15
	s_nop 0
	v_pk_mul_f32 v[16:17], v[116:117], s[6:7]
	v_readlane_b32 s6, v210, 48
	v_readlane_b32 s7, v210, 49
	v_cvt_pk_bf16_f32 v53, v16, v17
	s_nop 1
	v_permlane32_swap_b32_e32 v7, v53
	v_pk_mul_f32 v[2:3], v[114:115], s[6:7]
	v_readlane_b32 s6, v210, 56
	v_readlane_b32 s7, v210, 57
	v_cvt_pk_bf16_f32 v2, v2, v3
	s_nop 0
	v_pk_mul_f32 v[4:5], v[94:95], s[6:7]
	v_readlane_b32 s6, v210, 50
	v_readlane_b32 s7, v210, 51
	v_cvt_pk_bf16_f32 v54, v4, v5
	s_nop 1
	v_permlane32_swap_b32_e32 v2, v54
	v_pk_mul_f32 v[6:7], v[110:111], s[6:7]
	v_readlane_b32 s6, v210, 58
	v_readlane_b32 s7, v210, 59
	v_cvt_pk_bf16_f32 v3, v6, v7
	v_lshlrev_b32_e32 v2, 8, v192
	v_pk_mul_f32 v[8:9], v[92:93], s[6:7]
	v_readlane_b32 s6, v210, 52
	v_readlane_b32 s7, v210, 53
	v_cvt_pk_bf16_f32 v55, v8, v9
	s_nop 1
	v_permlane32_swap_b32_e32 v3, v55
	v_pk_mul_f32 v[10:11], v[104:105], s[6:7]
	v_readlane_b32 s6, v210, 60
	v_readlane_b32 s7, v210, 61
	v_mov_b32_e32 v3, v123
	v_lshl_add_u64 v[2:3], v[2:3], 0, v[124:125]
	v_pk_mul_f32 v[12:13], v[90:91], s[6:7]
	v_readlane_b32 s6, v210, 54
	v_readlane_b32 s7, v210, 55
	v_lshl_add_u64 v[64:65], s[0:1], 0, v[2:3]
	v_cvt_pk_bf16_f32 v6, v10, v11
	v_pk_mul_f32 v[14:15], v[96:97], s[6:7]
	v_readlane_b32 s6, v210, 62
	v_readlane_b32 s7, v210, 63
	v_cvt_pk_bf16_f32 v7, v14, v15
	v_cvt_pk_bf16_f32 v56, v12, v13
	v_pk_mul_f32 v[16:17], v[88:89], s[6:7]
	v_readlane_b32 s6, v250, 3
	s_add_u32 s4, s6, s4
	v_readlane_b32 s6, v250, 4
	s_addc_u32 s5, s6, s5
	v_readlane_b32 s6, v250, 13
	s_lshl_b32 s6, s6, 14
	s_add_u32 s4, s4, s6
	s_addc_u32 s5, s5, 0
	v_lshl_add_u64 v[62:63], s[4:5], 0, v[86:87]
	v_lshl_add_u64 v[66:67], v[62:63], 0, v[122:123]
	v_mov_b32_e32 v142, 0x1000
	v_mov_b32_e32 v143, 0
	v_lshl_add_u64 v[130:131], v[66:67], 0, v[142:143]
	v_lshl_add_u64 v[134:135], v[130:131], 0, v[142:143]
	v_lshl_add_u64 v[138:139], v[134:135], 0, v[142:143]
	global_load_dwordx4 v[202:205], v[66:67], off
	global_load_dwordx4 v[208:211], v[66:67], off offset:32
	global_load_dwordx4 v[212:215], v[66:67], off offset:64
	global_load_dwordx4 v[216:219], v[66:67], off offset:96
	global_load_dwordx4 v[220:223], v[130:131], off
	global_load_dwordx4 v[234:237], v[130:131], off offset:32
	global_load_dwordx4 v[238:241], v[130:131], off offset:64
	global_load_dwordx4 v[242:245], v[130:131], off offset:96
	s_nop 0
	s_nop 0
	v_cvt_pk_bf16_f32 v57, v16, v17
	v_permlane32_swap_b32_e32 v6, v56
	s_nop 0
	v_permlane32_swap_b32_e32 v7, v57
	s_nop 0
	s_waitcnt vmcnt(7)
	v_mfma_f32_32x32x16_bf16 v[18:33], v[202:205], v[34:37], 0
	s_mov_b32 s0, 0x2e400000
	v_readlane_b32 s7, v250, 15
	v_mfma_f32_32x32x16_bf16 v[2:17], v[202:205], v[38:41], 0
	s_nop 0
	s_waitcnt vmcnt(6)
	v_mfma_f32_32x32x16_bf16 v[18:33], v[208:211], v[42:45], v[18:33]
	v_mfma_f32_32x32x16_bf16 v[2:17], v[208:211], v[46:49], v[2:17]
	s_nop 0
	s_nop 9
	v_cvt_pk_bf16_f32 v18, v18, v19
	v_cvt_pk_bf16_f32 v19, v20, v21
	s_nop 0
	s_waitcnt vmcnt(5)
	v_mfma_f32_32x32x16_bf16 v[2:17], v[212:215], v[50:53], v[2:17]
	s_nop 0
	s_nop 0
	s_waitcnt vmcnt(4)
	v_mfma_f32_32x32x16_bf16 v[2:17], v[216:219], v[54:57], v[2:17]
	v_add_co_u32_e32 v58, vcc, s0, v64
	s_mov_b32 s0, 0x2e402000
	s_nop 0
	v_addc_co_u32_e32 v59, vcc, 0, v65, vcc
	v_add_co_u32_e32 v60, vcc, s0, v64
	s_nop 6
	v_cvt_pk_bf16_f32 v2, v2, v3
	v_cvt_pk_bf16_f32 v3, v4, v5
	v_addc_co_u32_e32 v61, vcc, 0, v65, vcc
	global_store_dwordx2 v[60:61], v[2:3], off
	v_cvt_pk_bf16_f32 v2, v22, v23
	v_cvt_pk_bf16_f32 v3, v24, v25
	global_store_dwordx2 v[58:59], v[2:3], off offset:16
	v_cvt_pk_bf16_f32 v2, v6, v7
	v_cvt_pk_bf16_f32 v3, v8, v9
	global_store_dwordx2 v[60:61], v[2:3], off offset:16
	v_cvt_pk_bf16_f32 v2, v26, v27
	v_cvt_pk_bf16_f32 v3, v28, v29
	global_store_dwordx2 v[58:59], v[2:3], off offset:32
	v_cvt_pk_bf16_f32 v2, v10, v11
	v_cvt_pk_bf16_f32 v3, v12, v13
	global_store_dwordx2 v[60:61], v[2:3], off offset:32
	v_cvt_pk_bf16_f32 v2, v30, v31
	v_cvt_pk_bf16_f32 v3, v32, v33
	global_store_dwordx2 v[58:59], v[2:3], off offset:48
	v_cvt_pk_bf16_f32 v2, v14, v15
	v_cvt_pk_bf16_f32 v3, v16, v17
	global_store_dwordx2 v[60:61], v[2:3], off offset:48
	v_or_b32_e32 v2, 0x1000, v122
	v_mov_b32_e32 v3, v123
	global_store_dwordx2 v[58:59], v[18:19], off
	v_lshl_add_u64 v[68:69], v[62:63], 0, v[2:3]
	global_load_dwordx4 v[202:205], v[134:135], off
	global_load_dwordx4 v[208:211], v[134:135], off offset:32
	global_load_dwordx4 v[212:215], v[134:135], off offset:64
	global_load_dwordx4 v[216:219], v[134:135], off offset:96
	s_nop 0
	s_nop 0
	s_nop 0
	s_waitcnt vmcnt(15)
	v_mfma_f32_32x32x16_bf16 v[18:33], v[220:223], v[34:37], 0
	v_readlane_b32 s0, v250, 9
	v_readlane_b32 s1, v250, 10
	s_add_i32 s33, s33, s0
	v_readlane_b32 s0, v250, 5
	v_readlane_b32 s1, v250, 6
	s_add_u32 s24, s24, s0
	s_addc_u32 s25, s25, s1
	v_mfma_f32_32x32x16_bf16 v[2:17], v[220:223], v[38:41], 0
	v_readlane_b32 s0, v250, 7
	v_readlane_b32 s1, v250, 8
	s_add_u32 s28, s28, s0
	s_addc_u32 s29, s29, s1
	v_readlane_b32 s0, v250, 11
	v_readlane_b32 s1, v250, 12
	s_add_u32 s7, s7, s0
	s_nop 0
	s_waitcnt vmcnt(14)
	v_mfma_f32_32x32x16_bf16 v[18:33], v[234:237], v[42:45], v[18:33]
	s_addc_u32 s8, s8, s1
	s_cmpk_lt_i32 s33, 0x2000
	v_mfma_f32_32x32x16_bf16 v[2:17], v[234:237], v[46:49], v[2:17]
	s_nop 0
	s_nop 7
	v_cvt_pk_bf16_f32 v18, v18, v19
	v_cvt_pk_bf16_f32 v19, v20, v21
	s_nop 0
	s_waitcnt vmcnt(13)
	v_mfma_f32_32x32x16_bf16 v[2:17], v[238:241], v[50:53], v[2:17]
	s_nop 0
	s_nop 0
	global_store_dwordx2 v[58:59], v[18:19], off offset:64
	s_nop 0
	s_waitcnt vmcnt(13)
	v_mfma_f32_32x32x16_bf16 v[2:17], v[242:245], v[54:57], v[2:17]
	s_nop 11
	v_cvt_pk_bf16_f32 v2, v2, v3
	v_cvt_pk_bf16_f32 v3, v4, v5
	global_store_dwordx2 v[60:61], v[2:3], off offset:64
	v_cvt_pk_bf16_f32 v2, v22, v23
	v_cvt_pk_bf16_f32 v3, v24, v25
	global_store_dwordx2 v[58:59], v[2:3], off offset:80
	v_cvt_pk_bf16_f32 v2, v6, v7
	v_cvt_pk_bf16_f32 v3, v8, v9
	global_store_dwordx2 v[60:61], v[2:3], off offset:80
	v_cvt_pk_bf16_f32 v2, v26, v27
	v_cvt_pk_bf16_f32 v3, v28, v29
	global_store_dwordx2 v[58:59], v[2:3], off offset:96
	v_cvt_pk_bf16_f32 v2, v10, v11
	v_cvt_pk_bf16_f32 v3, v12, v13
	global_store_dwordx2 v[60:61], v[2:3], off offset:96
	v_cvt_pk_bf16_f32 v2, v30, v31
	v_cvt_pk_bf16_f32 v3, v32, v33
	global_store_dwordx2 v[58:59], v[2:3], off offset:112
	v_cvt_pk_bf16_f32 v2, v14, v15
	v_cvt_pk_bf16_f32 v3, v16, v17
	global_store_dwordx2 v[60:61], v[2:3], off offset:112
	v_or_b32_e32 v2, 0x2000, v122
	v_mov_b32_e32 v3, v123
	v_lshl_add_u64 v[68:69], v[62:63], 0, v[2:3]
	global_load_dwordx4 v[220:223], v[138:139], off
	global_load_dwordx4 v[234:237], v[138:139], off offset:32
	global_load_dwordx4 v[238:241], v[138:139], off offset:64
	global_load_dwordx4 v[242:245], v[138:139], off offset:96
	s_nop 0
	s_nop 0
	s_nop 0
	s_waitcnt vmcnt(15)
	v_mfma_f32_32x32x16_bf16 v[18:33], v[202:205], v[34:37], 0
	v_or_b32_e32 v122, 0x3000, v122
	v_lshl_add_u64 v[62:63], v[62:63], 0, v[122:123]
	v_mfma_f32_32x32x16_bf16 v[2:17], v[202:205], v[38:41], 0
	s_nop 0
	s_waitcnt vmcnt(14)
	v_mfma_f32_32x32x16_bf16 v[18:33], v[208:211], v[42:45], v[18:33]
	v_mfma_f32_32x32x16_bf16 v[2:17], v[208:211], v[46:49], v[2:17]
	s_nop 0
	s_nop 9
	v_cvt_pk_bf16_f32 v18, v18, v19
	v_cvt_pk_bf16_f32 v19, v20, v21
	s_nop 0
	s_waitcnt vmcnt(13)
	v_mfma_f32_32x32x16_bf16 v[2:17], v[212:215], v[50:53], v[2:17]
	s_nop 0
	s_nop 0
	global_store_dwordx2 v[58:59], v[18:19], off offset:128
	s_nop 0
	s_waitcnt vmcnt(13)
	v_mfma_f32_32x32x16_bf16 v[2:17], v[216:219], v[54:57], v[2:17]
	s_nop 11
	v_cvt_pk_bf16_f32 v2, v2, v3
	v_cvt_pk_bf16_f32 v3, v4, v5
	global_store_dwordx2 v[60:61], v[2:3], off offset:128
	v_cvt_pk_bf16_f32 v2, v22, v23
	v_cvt_pk_bf16_f32 v3, v24, v25
	global_store_dwordx2 v[58:59], v[2:3], off offset:144
	v_cvt_pk_bf16_f32 v2, v6, v7
	v_cvt_pk_bf16_f32 v3, v8, v9
	global_store_dwordx2 v[60:61], v[2:3], off offset:144
	v_cvt_pk_bf16_f32 v2, v26, v27
	v_cvt_pk_bf16_f32 v3, v28, v29
	global_store_dwordx2 v[58:59], v[2:3], off offset:160
	v_cvt_pk_bf16_f32 v2, v10, v11
	v_cvt_pk_bf16_f32 v3, v12, v13
	global_store_dwordx2 v[60:61], v[2:3], off offset:160
	v_cvt_pk_bf16_f32 v2, v30, v31
	v_cvt_pk_bf16_f32 v3, v32, v33
	global_store_dwordx2 v[58:59], v[2:3], off offset:176
	v_cvt_pk_bf16_f32 v2, v14, v15
	v_cvt_pk_bf16_f32 v3, v16, v17
	global_store_dwordx2 v[60:61], v[2:3], off offset:176
	s_nop 0
	s_nop 0
	s_waitcnt vmcnt(11)
	v_mfma_f32_32x32x16_bf16 v[18:33], v[220:223], v[34:37], 0
	s_nop 0
	v_mfma_f32_32x32x16_bf16 v[2:17], v[220:223], v[38:41], 0
	s_nop 0
	s_waitcnt vmcnt(10)
	v_mfma_f32_32x32x16_bf16 v[18:33], v[234:237], v[42:45], v[18:33]
	s_nop 11
	v_cvt_pk_bf16_f32 v18, v18, v19
	v_mfma_f32_32x32x16_bf16 v[2:17], v[234:237], v[46:49], v[2:17]
	s_nop 0
	v_cvt_pk_bf16_f32 v19, v20, v21
	s_nop 0
	s_waitcnt vmcnt(9)
	v_mfma_f32_32x32x16_bf16 v[2:17], v[238:241], v[50:53], v[2:17]
	s_nop 0
	s_nop 0
	global_store_dwordx2 v[58:59], v[18:19], off offset:192
	s_nop 0
	s_waitcnt vmcnt(9)
	v_mfma_f32_32x32x16_bf16 v[2:17], v[242:245], v[54:57], v[2:17]
	s_nop 11
	v_cvt_pk_bf16_f32 v2, v2, v3
	v_cvt_pk_bf16_f32 v3, v4, v5
	global_store_dwordx2 v[60:61], v[2:3], off offset:192
	v_cvt_pk_bf16_f32 v2, v22, v23
	v_cvt_pk_bf16_f32 v3, v24, v25
	global_store_dwordx2 v[58:59], v[2:3], off offset:208
	v_cvt_pk_bf16_f32 v2, v6, v7
	v_cvt_pk_bf16_f32 v3, v8, v9
	global_store_dwordx2 v[60:61], v[2:3], off offset:208
	v_cvt_pk_bf16_f32 v2, v26, v27
	v_cvt_pk_bf16_f32 v3, v28, v29
	global_store_dwordx2 v[58:59], v[2:3], off offset:224
	v_cvt_pk_bf16_f32 v2, v10, v11
	v_cvt_pk_bf16_f32 v3, v12, v13
	global_store_dwordx2 v[60:61], v[2:3], off offset:224
	v_cvt_pk_bf16_f32 v2, v30, v31
	v_cvt_pk_bf16_f32 v3, v32, v33
	global_store_dwordx2 v[58:59], v[2:3], off offset:240
	v_cvt_pk_bf16_f32 v2, v14, v15
	v_cvt_pk_bf16_f32 v3, v16, v17
	global_store_dwordx2 v[60:61], v[2:3], off offset:240
	s_waitcnt lgkmcnt(0)
	s_cbranch_scc0 .LBB0_782
